# attention A item starts wait vmcnt(8) instead of 0 (do not wait for the previous item's store acks); all flat ops converted to global for in-order counting
# speedup vs baseline: 1.0399x; 1.0041x over previous
.LBB0_21:
	s_lshl_b32 s20, s18, 1
	s_lshl_b32 s21, s17, 1
	v_add_u32_e32 v48, s20, v6
	v_add_u32_e32 v50, s21, v19
	v_add_u32_e32 v52, s20, v26
	v_add_u32_e32 v54, s21, v21
	v_add_u32_e32 v56, s20, v28
	v_add_u32_e32 v58, s21, v23
	v_add_u32_e32 v60, s20, v30
	v_add_u32_e32 v62, s21, v27
	v_add_u32_e32 v64, s20, v32
	v_add_u32_e32 v66, s21, v29
	v_add_u32_e32 v68, s20, v34
	v_add_u32_e32 v70, s21, v31
	v_add_u32_e32 v72, s20, v36
	v_add_u32_e32 v74, s21, v33
	v_add_u32_e32 v76, s20, v38
	v_add_u32_e32 v78, s21, v35
	v_ashrrev_i32_e32 v49, 31, v48
	v_ashrrev_i32_e32 v51, 31, v50
	v_ashrrev_i32_e32 v53, 31, v52
	v_ashrrev_i32_e32 v55, 31, v54
	v_ashrrev_i32_e32 v57, 31, v56
	v_ashrrev_i32_e32 v59, 31, v58
	v_ashrrev_i32_e32 v61, 31, v60
	v_ashrrev_i32_e32 v63, 31, v62
	v_ashrrev_i32_e32 v65, 31, v64
	v_ashrrev_i32_e32 v67, 31, v66
	v_ashrrev_i32_e32 v69, 31, v68
	v_ashrrev_i32_e32 v71, 31, v70
	v_ashrrev_i32_e32 v73, 31, v72
	v_ashrrev_i32_e32 v75, 31, v74
	v_ashrrev_i32_e32 v77, 31, v76
	v_ashrrev_i32_e32 v79, 31, v78
	v_lshlrev_b64 v[48:49], 12, v[48:49]
	v_lshlrev_b64 v[50:51], 12, v[50:51]
	v_lshlrev_b64 v[52:53], 12, v[52:53]
	v_lshlrev_b64 v[54:55], 12, v[54:55]
	v_lshlrev_b64 v[56:57], 12, v[56:57]
	v_lshlrev_b64 v[58:59], 12, v[58:59]
	v_lshlrev_b64 v[60:61], 12, v[60:61]
	v_lshlrev_b64 v[62:63], 12, v[62:63]
	v_lshlrev_b64 v[64:65], 12, v[64:65]
	v_lshlrev_b64 v[66:67], 12, v[66:67]
	v_lshlrev_b64 v[68:69], 12, v[68:69]
	v_lshlrev_b64 v[70:71], 12, v[70:71]
	v_lshlrev_b64 v[72:73], 12, v[72:73]
	v_lshlrev_b64 v[74:75], 12, v[74:75]
	v_lshlrev_b64 v[76:77], 12, v[76:77]
	v_lshlrev_b64 v[78:79], 12, v[78:79]
	v_lshl_add_u64 v[48:49], v[24:25], 0, v[48:49]
	v_lshl_add_u64 v[50:51], v[24:25], 0, v[50:51]
	v_lshl_add_u64 v[52:53], v[24:25], 0, v[52:53]
	v_lshl_add_u64 v[54:55], v[24:25], 0, v[54:55]
	v_lshl_add_u64 v[56:57], v[24:25], 0, v[56:57]
	v_lshl_add_u64 v[58:59], v[24:25], 0, v[58:59]
	v_lshl_add_u64 v[60:61], v[24:25], 0, v[60:61]
	v_lshl_add_u64 v[62:63], v[24:25], 0, v[62:63]
	v_lshl_add_u64 v[64:65], v[24:25], 0, v[64:65]
	v_lshl_add_u64 v[66:67], v[24:25], 0, v[66:67]
	v_lshl_add_u64 v[68:69], v[24:25], 0, v[68:69]
	v_lshl_add_u64 v[70:71], v[24:25], 0, v[70:71]
	v_lshl_add_u64 v[72:73], v[24:25], 0, v[72:73]
	v_lshl_add_u64 v[74:75], v[24:25], 0, v[74:75]
	v_lshl_add_u64 v[76:77], v[24:25], 0, v[76:77]
	v_lshl_add_u64 v[78:79], v[24:25], 0, v[78:79]
	global_load_dword v37, v[48:49], off
	global_load_dword v40, v[50:51], off
	global_load_dword v80, v[52:53], off
	global_load_dword v81, v[54:55], off
	global_load_dword v82, v[56:57], off
	global_load_dword v83, v[58:59], off
	global_load_dword v84, v[60:61], off
	global_load_dword v85, v[62:63], off
	global_load_dword v86, v[64:65], off
	global_load_dword v87, v[66:67], off
	global_load_dword v88, v[68:69], off
	global_load_dword v89, v[70:71], off
	global_load_dword v90, v[72:73], off
	global_load_dword v91, v[74:75], off
	global_load_dword v92, v[76:77], off
	global_load_dword v93, v[78:79], off
	s_add_i32 s18, s18, 16
	s_add_i32 s17, s17, 16
	s_add_i32 s19, s19, -16
	v_add_u32_e32 v48, s20, v0
	v_add_u32_e32 v50, s21, v1
	v_add_u32_e32 v52, s20, v8
	v_add_u32_e32 v54, s21, v3
	v_add_u32_e32 v56, s20, v10
	v_add_u32_e32 v58, s21, v5
	v_add_u32_e32 v60, s20, v12
	v_add_u32_e32 v62, s21, v9
	v_add_u32_e32 v64, s20, v14
	v_add_u32_e32 v66, s21, v11
	v_add_u32_e32 v68, s20, v16
	v_add_u32_e32 v70, s21, v13
	v_add_u32_e32 v72, s20, v18
	v_add_u32_e32 v74, s21, v15
	v_add_u32_e32 v76, s20, v22
	v_add_u32_e32 v78, s21, v17
	s_cmp_lg_u32 s19, 0
	v_mad_u64_u32 v[48:49], s[20:21], v48, s14, v[2:3]
	v_mad_u64_u32 v[50:51], s[20:21], v50, s14, v[2:3]
	v_mad_u64_u32 v[52:53], s[20:21], v52, s14, v[2:3]
	v_mad_u64_u32 v[54:55], s[20:21], v54, s14, v[2:3]
	v_mad_u64_u32 v[56:57], s[20:21], v56, s14, v[2:3]
	v_mad_u64_u32 v[58:59], s[20:21], v58, s14, v[2:3]
	v_mad_u64_u32 v[60:61], s[20:21], v60, s14, v[2:3]
	v_mad_u64_u32 v[62:63], s[20:21], v62, s14, v[2:3]
	v_mad_u64_u32 v[64:65], s[20:21], v64, s14, v[2:3]
	v_mad_u64_u32 v[66:67], s[20:21], v66, s14, v[2:3]
	v_mad_u64_u32 v[68:69], s[20:21], v68, s14, v[2:3]
	v_mad_u64_u32 v[70:71], s[20:21], v70, s14, v[2:3]
	v_mad_u64_u32 v[72:73], s[20:21], v72, s14, v[2:3]
	v_mad_u64_u32 v[74:75], s[20:21], v74, s14, v[2:3]
	v_mad_u64_u32 v[76:77], s[20:21], v76, s14, v[2:3]
	v_mad_u64_u32 v[78:79], s[20:21], v78, s14, v[2:3]
	s_waitcnt vmcnt(0)
	ds_write_b32 v48, v37
	s_waitcnt vmcnt(14)
	ds_write_b32 v50, v40
	s_waitcnt vmcnt(13)
	ds_write_b32 v52, v80
	s_waitcnt vmcnt(12)
	ds_write_b32 v54, v81
	s_waitcnt vmcnt(11)
	ds_write_b32 v56, v82
	s_waitcnt vmcnt(10)
	ds_write_b32 v58, v83
	s_waitcnt vmcnt(9)
	ds_write_b32 v60, v84
	s_waitcnt vmcnt(8)
	ds_write_b32 v62, v85
	s_waitcnt vmcnt(7)
	ds_write_b32 v64, v86
	s_waitcnt vmcnt(6)
	ds_write_b32 v66, v87
	s_waitcnt vmcnt(5)
	ds_write_b32 v68, v88
	s_waitcnt vmcnt(4)
	ds_write_b32 v70, v89
	s_waitcnt vmcnt(3)
	ds_write_b32 v72, v90
	s_waitcnt vmcnt(2)
	ds_write_b32 v74, v91
	s_waitcnt vmcnt(1)
	ds_write_b32 v76, v92
	s_waitcnt vmcnt(0)
	ds_write_b32 v78, v93
	s_cbranch_scc1 .LBB0_21
	s_waitcnt lgkmcnt(0)
	ds_read_b32 v19, v42
	ds_read_b32 v21, v42 offset:132
	ds_read_b32 v23, v42 offset:264
	ds_read_b32 v25, v42 offset:396
	ds_read_b32 v26, v42 offset:528
	ds_read_b32 v27, v42 offset:660
	ds_read_b32 v30, v42 offset:792
	ds_read_b32 v31, v42 offset:924
	s_lshl_b64 s[18:19], s[0:1], 22
	s_add_u32 s0, s12, s18
	s_addc_u32 s17, s13, s19
	s_lshl_b32 s7, s7, 1
	s_add_u32 s18, s0, s7
	s_waitcnt lgkmcnt(2)
	v_cvt_pk_bf16_f32 v26, v26, v27
	s_waitcnt lgkmcnt(0)
	v_cvt_pk_bf16_f32 v27, v30, v31
	v_add_u32_e32 v30, s6, v41
	s_addc_u32 s19, s17, 0
	v_lshlrev_b32_e32 v6, 1, v4
	v_ashrrev_i32_e32 v31, 31, v30
	v_lshl_add_u64 v[28:29], s[18:19], 0, v[6:7]
	v_lshlrev_b64 v[30:31], 12, v[30:31]
	v_cvt_pk_bf16_f32 v24, v19, v21
	v_cvt_pk_bf16_f32 v25, v23, v25
	v_lshl_add_u64 v[30:31], v[28:29], 0, v[30:31]
	global_store_dwordx4 v[30:31], v[24:27], off
	ds_read_b32 v6, v42 offset:32
	ds_read_b32 v19, v42 offset:164
	ds_read_b32 v21, v42 offset:296
	ds_read_b32 v23, v42 offset:428
	ds_read_b32 v26, v42 offset:560
	ds_read_b32 v27, v42 offset:692
	ds_read_b32 v30, v42 offset:824
	ds_read_b32 v31, v42 offset:956
	s_waitcnt lgkmcnt(0)
	v_cvt_pk_bf16_f32 v24, v6, v19
	v_cvt_pk_bf16_f32 v25, v21, v23
	v_cvt_pk_bf16_f32 v26, v26, v27
	v_cvt_pk_bf16_f32 v27, v30, v31
	v_add_u32_e32 v30, s6, v43
	v_ashrrev_i32_e32 v31, 31, v30
	v_lshlrev_b64 v[30:31], 12, v[30:31]
	v_lshl_add_u64 v[30:31], v[28:29], 0, v[30:31]
	global_store_dwordx4 v[30:31], v[24:27], off
	ds_read_b32 v6, v42 offset:64
	ds_read_b32 v19, v42 offset:196
	ds_read_b32 v21, v42 offset:328
	ds_read_b32 v23, v42 offset:460
	ds_read_b32 v26, v42 offset:592
	ds_read_b32 v27, v42 offset:724
	ds_read_b32 v30, v42 offset:856
	ds_read_b32 v31, v42 offset:988
	s_waitcnt lgkmcnt(0)
	v_cvt_pk_bf16_f32 v24, v6, v19
	v_cvt_pk_bf16_f32 v25, v21, v23
	v_cvt_pk_bf16_f32 v26, v26, v27
	v_cvt_pk_bf16_f32 v27, v30, v31
	v_add_u32_e32 v30, s6, v44
	v_ashrrev_i32_e32 v31, 31, v30
	v_lshlrev_b64 v[30:31], 12, v[30:31]
	v_lshl_add_u64 v[30:31], v[28:29], 0, v[30:31]
	global_store_dwordx4 v[30:31], v[24:27], off
	ds_read_b32 v6, v42 offset:96
	ds_read_b32 v19, v42 offset:228
	ds_read_b32 v21, v42 offset:360
	ds_read_b32 v23, v42 offset:492
	ds_read_b32 v26, v42 offset:624
	ds_read_b32 v27, v42 offset:756
	ds_read_b32 v30, v42 offset:888
	ds_read_b32 v31, v42 offset:1020
	s_waitcnt lgkmcnt(0)
	v_cvt_pk_bf16_f32 v24, v6, v19
	v_cvt_pk_bf16_f32 v25, v21, v23
	v_cvt_pk_bf16_f32 v26, v26, v27
	v_cvt_pk_bf16_f32 v27, v30, v31
	v_add_u32_e32 v30, s6, v45
	v_ashrrev_i32_e32 v31, 31, v30
	v_lshlrev_b64 v[30:31], 12, v[30:31]
	v_lshl_add_u64 v[28:29], v[28:29], 0, v[30:31]
	global_store_dwordx4 v[28:29], v[24:27], off
	s_waitcnt lgkmcnt(0)
	s_mov_b64 s[6:7], 0

.LBB0_25:
	s_lshl_b32 s21, s19, 1
	s_lshl_b32 s22, s18, 1
	v_add_u32_e32 v48, s21, v6
	v_add_u32_e32 v50, s22, v19
	v_add_u32_e32 v52, s21, v26
	v_add_u32_e32 v54, s22, v21
	v_add_u32_e32 v56, s21, v28
	v_add_u32_e32 v58, s22, v23
	v_add_u32_e32 v60, s21, v30
	v_add_u32_e32 v62, s22, v27
	v_add_u32_e32 v64, s21, v32
	v_add_u32_e32 v66, s22, v29
	v_add_u32_e32 v68, s21, v34
	v_add_u32_e32 v70, s22, v31
	v_add_u32_e32 v72, s21, v36
	v_add_u32_e32 v74, s22, v33
	v_add_u32_e32 v76, s21, v38
	v_add_u32_e32 v78, s22, v35
	v_ashrrev_i32_e32 v49, 31, v48
	v_ashrrev_i32_e32 v51, 31, v50
	v_ashrrev_i32_e32 v53, 31, v52
	v_ashrrev_i32_e32 v55, 31, v54
	v_ashrrev_i32_e32 v57, 31, v56
	v_ashrrev_i32_e32 v59, 31, v58
	v_ashrrev_i32_e32 v61, 31, v60
	v_ashrrev_i32_e32 v63, 31, v62
	v_ashrrev_i32_e32 v65, 31, v64
	v_ashrrev_i32_e32 v67, 31, v66
	v_ashrrev_i32_e32 v69, 31, v68
	v_ashrrev_i32_e32 v71, 31, v70
	v_ashrrev_i32_e32 v73, 31, v72
	v_ashrrev_i32_e32 v75, 31, v74
	v_ashrrev_i32_e32 v77, 31, v76
	v_ashrrev_i32_e32 v79, 31, v78
	v_lshlrev_b64 v[48:49], 13, v[48:49]
	v_lshlrev_b64 v[50:51], 13, v[50:51]
	v_lshlrev_b64 v[52:53], 13, v[52:53]
	v_lshlrev_b64 v[54:55], 13, v[54:55]
	v_lshlrev_b64 v[56:57], 13, v[56:57]
	v_lshlrev_b64 v[58:59], 13, v[58:59]
	v_lshlrev_b64 v[60:61], 13, v[60:61]
	v_lshlrev_b64 v[62:63], 13, v[62:63]
	v_lshlrev_b64 v[64:65], 13, v[64:65]
	v_lshlrev_b64 v[66:67], 13, v[66:67]
	v_lshlrev_b64 v[68:69], 13, v[68:69]
	v_lshlrev_b64 v[70:71], 13, v[70:71]
	v_lshlrev_b64 v[72:73], 13, v[72:73]
	v_lshlrev_b64 v[74:75], 13, v[74:75]
	v_lshlrev_b64 v[76:77], 13, v[76:77]
	v_lshlrev_b64 v[78:79], 13, v[78:79]
	v_lshl_add_u64 v[48:49], v[24:25], 0, v[48:49]
	v_lshl_add_u64 v[50:51], v[24:25], 0, v[50:51]
	v_lshl_add_u64 v[52:53], v[24:25], 0, v[52:53]
	v_lshl_add_u64 v[54:55], v[24:25], 0, v[54:55]
	v_lshl_add_u64 v[56:57], v[24:25], 0, v[56:57]
	v_lshl_add_u64 v[58:59], v[24:25], 0, v[58:59]
	v_lshl_add_u64 v[60:61], v[24:25], 0, v[60:61]
	v_lshl_add_u64 v[62:63], v[24:25], 0, v[62:63]
	v_lshl_add_u64 v[64:65], v[24:25], 0, v[64:65]
	v_lshl_add_u64 v[66:67], v[24:25], 0, v[66:67]
	v_lshl_add_u64 v[68:69], v[24:25], 0, v[68:69]
	v_lshl_add_u64 v[70:71], v[24:25], 0, v[70:71]
	v_lshl_add_u64 v[72:73], v[24:25], 0, v[72:73]
	v_lshl_add_u64 v[74:75], v[24:25], 0, v[74:75]
	v_lshl_add_u64 v[76:77], v[24:25], 0, v[76:77]
	v_lshl_add_u64 v[78:79], v[24:25], 0, v[78:79]
	global_load_dword v37, v[48:49], off
	global_load_dword v40, v[50:51], off
	global_load_dword v80, v[52:53], off
	global_load_dword v81, v[54:55], off
	global_load_dword v82, v[56:57], off
	global_load_dword v83, v[58:59], off
	global_load_dword v84, v[60:61], off
	global_load_dword v85, v[62:63], off
	global_load_dword v86, v[64:65], off
	global_load_dword v87, v[66:67], off
	global_load_dword v88, v[68:69], off
	global_load_dword v89, v[70:71], off
	global_load_dword v90, v[72:73], off
	global_load_dword v91, v[74:75], off
	global_load_dword v92, v[76:77], off
	global_load_dword v93, v[78:79], off
	s_add_i32 s19, s19, 16
	s_add_i32 s18, s18, 16
	s_add_i32 s20, s20, -16
	v_add_u32_e32 v48, s21, v0
	v_add_u32_e32 v50, s22, v1
	v_add_u32_e32 v52, s21, v8
	v_add_u32_e32 v54, s22, v3
	v_add_u32_e32 v56, s21, v10
	v_add_u32_e32 v58, s22, v5
	v_add_u32_e32 v60, s21, v12
	v_add_u32_e32 v62, s22, v9
	v_add_u32_e32 v64, s21, v14
	v_add_u32_e32 v66, s22, v11
	v_add_u32_e32 v68, s21, v16
	v_add_u32_e32 v70, s22, v13
	v_add_u32_e32 v72, s21, v18
	v_add_u32_e32 v74, s22, v15
	v_add_u32_e32 v76, s21, v22
	v_add_u32_e32 v78, s22, v17
	s_cmp_lg_u32 s20, 0
	v_mad_u64_u32 v[48:49], s[22:23], v48, s14, v[2:3]
	v_mad_u64_u32 v[50:51], s[22:23], v50, s14, v[2:3]
	v_mad_u64_u32 v[52:53], s[22:23], v52, s14, v[2:3]
	v_mad_u64_u32 v[54:55], s[22:23], v54, s14, v[2:3]
	v_mad_u64_u32 v[56:57], s[22:23], v56, s14, v[2:3]
	v_mad_u64_u32 v[58:59], s[22:23], v58, s14, v[2:3]
	v_mad_u64_u32 v[60:61], s[22:23], v60, s14, v[2:3]
	v_mad_u64_u32 v[62:63], s[22:23], v62, s14, v[2:3]
	v_mad_u64_u32 v[64:65], s[22:23], v64, s14, v[2:3]
	v_mad_u64_u32 v[66:67], s[22:23], v66, s14, v[2:3]
	v_mad_u64_u32 v[68:69], s[22:23], v68, s14, v[2:3]
	v_mad_u64_u32 v[70:71], s[22:23], v70, s14, v[2:3]
	v_mad_u64_u32 v[72:73], s[22:23], v72, s14, v[2:3]
	v_mad_u64_u32 v[74:75], s[22:23], v74, s14, v[2:3]
	v_mad_u64_u32 v[76:77], s[22:23], v76, s14, v[2:3]
	v_mad_u64_u32 v[78:79], s[22:23], v78, s14, v[2:3]
	s_waitcnt vmcnt(0)
	ds_write_b32 v48, v37
	ds_write_b32 v50, v40
	ds_write_b32 v52, v80
	ds_write_b32 v54, v81
	ds_write_b32 v56, v82
	ds_write_b32 v58, v83
	ds_write_b32 v60, v84
	ds_write_b32 v62, v85
	ds_write_b32 v64, v86
	ds_write_b32 v66, v87
	ds_write_b32 v68, v88
	ds_write_b32 v70, v89
	ds_write_b32 v72, v90
	ds_write_b32 v74, v91
	ds_write_b32 v76, v92
	ds_write_b32 v78, v93
	s_cbranch_scc1 .LBB0_25
	s_waitcnt lgkmcnt(0)
	ds_read_b32 v19, v42
	ds_read_b32 v21, v42 offset:132
	ds_read_b32 v23, v42 offset:264
	ds_read_b32 v25, v42 offset:396
	ds_read_b32 v26, v42 offset:528
	ds_read_b32 v27, v42 offset:660
	ds_read_b32 v30, v42 offset:792
	ds_read_b32 v31, v42 offset:924
	s_lshl_b64 s[6:7], s[6:7], 1
	s_add_u32 s6, s10, s6
	s_addc_u32 s7, s11, s7
	s_lshl_b32 s17, s17, 1
	s_add_u32 s6, s6, s17
	s_waitcnt lgkmcnt(0)
	v_cvt_pk_bf16_f32 v26, v26, v27
	v_cvt_pk_bf16_f32 v27, v30, v31
	v_add_u32_e32 v30, s0, v41
	s_addc_u32 s7, s7, 0
	v_lshlrev_b32_e32 v6, 1, v4
	v_ashrrev_i32_e32 v31, 31, v30
	v_lshl_add_u64 v[28:29], s[6:7], 0, v[6:7]
	v_lshlrev_b64 v[30:31], 12, v[30:31]
	v_cvt_pk_bf16_f32 v24, v19, v21
	v_cvt_pk_bf16_f32 v25, v23, v25
	v_lshl_add_u64 v[30:31], v[28:29], 0, v[30:31]
	global_store_dwordx4 v[30:31], v[24:27], off
	ds_read_b32 v6, v42 offset:32
	ds_read_b32 v19, v42 offset:164
	ds_read_b32 v21, v42 offset:296
	ds_read_b32 v23, v42 offset:428
	ds_read_b32 v26, v42 offset:560
	ds_read_b32 v27, v42 offset:692
	ds_read_b32 v30, v42 offset:824
	ds_read_b32 v31, v42 offset:956
	s_waitcnt lgkmcnt(0)
	v_cvt_pk_bf16_f32 v24, v6, v19
	v_cvt_pk_bf16_f32 v25, v21, v23
	v_cvt_pk_bf16_f32 v26, v26, v27
	v_cvt_pk_bf16_f32 v27, v30, v31
	v_add_u32_e32 v30, s0, v43
	v_ashrrev_i32_e32 v31, 31, v30
	v_lshlrev_b64 v[30:31], 12, v[30:31]
	v_lshl_add_u64 v[30:31], v[28:29], 0, v[30:31]
	global_store_dwordx4 v[30:31], v[24:27], off
	ds_read_b32 v6, v42 offset:64
	ds_read_b32 v19, v42 offset:196
	ds_read_b32 v21, v42 offset:328
	ds_read_b32 v23, v42 offset:460
	ds_read_b32 v26, v42 offset:592
	ds_read_b32 v27, v42 offset:724
	ds_read_b32 v30, v42 offset:856
	ds_read_b32 v31, v42 offset:988
	s_waitcnt lgkmcnt(0)
	v_cvt_pk_bf16_f32 v24, v6, v19
	v_cvt_pk_bf16_f32 v25, v21, v23
	v_cvt_pk_bf16_f32 v26, v26, v27
	v_cvt_pk_bf16_f32 v27, v30, v31
	v_add_u32_e32 v30, s0, v44
	v_ashrrev_i32_e32 v31, 31, v30
	v_lshlrev_b64 v[30:31], 12, v[30:31]
	v_lshl_add_u64 v[30:31], v[28:29], 0, v[30:31]
	global_store_dwordx4 v[30:31], v[24:27], off
	ds_read_b32 v6, v42 offset:96
	ds_read_b32 v19, v42 offset:228
	ds_read_b32 v21, v42 offset:360
	ds_read_b32 v23, v42 offset:492
	ds_read_b32 v26, v42 offset:624
	ds_read_b32 v27, v42 offset:756
	ds_read_b32 v30, v42 offset:888
	ds_read_b32 v31, v42 offset:1020
	s_waitcnt lgkmcnt(0)
	v_cvt_pk_bf16_f32 v24, v6, v19
	v_cvt_pk_bf16_f32 v25, v21, v23
	v_cvt_pk_bf16_f32 v26, v26, v27
	v_cvt_pk_bf16_f32 v27, v30, v31
	v_add_u32_e32 v30, s0, v45
	v_ashrrev_i32_e32 v31, 31, v30
	v_lshlrev_b64 v[30:31], 12, v[30:31]
	v_lshl_add_u64 v[28:29], v[28:29], 0, v[30:31]
	global_store_dwordx4 v[28:29], v[24:27], off
	s_waitcnt lgkmcnt(0)

.LBB0_33:
	s_lshl_b32 s20, s18, 1
	s_lshl_b32 s21, s17, 1
	v_add_u32_e32 v48, s20, v6
	v_add_u32_e32 v50, s21, v19
	v_add_u32_e32 v52, s20, v28
	v_add_u32_e32 v54, s21, v21
	v_add_u32_e32 v56, s20, v30
	v_add_u32_e32 v58, s21, v23
	v_add_u32_e32 v60, s20, v32
	v_add_u32_e32 v62, s21, v29
	v_add_u32_e32 v64, s20, v34
	v_add_u32_e32 v66, s21, v31
	v_add_u32_e32 v68, s20, v36
	v_add_u32_e32 v70, s21, v33
	v_add_u32_e32 v72, s20, v38
	v_add_u32_e32 v74, s21, v35
	v_add_u32_e32 v76, s20, v40
	v_add_u32_e32 v78, s21, v37
	v_mad_i64_i32 v[48:49], s[22:23], v48, s15, v[24:25]
	v_mad_i64_i32 v[50:51], s[22:23], v50, s15, v[24:25]
	v_mad_i64_i32 v[52:53], s[22:23], v52, s15, v[24:25]
	v_mad_i64_i32 v[54:55], s[22:23], v54, s15, v[24:25]
	v_mad_i64_i32 v[56:57], s[22:23], v56, s15, v[24:25]
	v_mad_i64_i32 v[58:59], s[22:23], v58, s15, v[24:25]
	v_mad_i64_i32 v[60:61], s[22:23], v60, s15, v[24:25]
	v_mad_i64_i32 v[62:63], s[22:23], v62, s15, v[24:25]
	v_mad_i64_i32 v[64:65], s[22:23], v64, s15, v[24:25]
	v_mad_i64_i32 v[66:67], s[22:23], v66, s15, v[24:25]
	v_mad_i64_i32 v[68:69], s[22:23], v68, s15, v[24:25]
	v_mad_i64_i32 v[70:71], s[22:23], v70, s15, v[24:25]
	v_mad_i64_i32 v[72:73], s[22:23], v72, s15, v[24:25]
	v_mad_i64_i32 v[74:75], s[22:23], v74, s15, v[24:25]
	v_mad_i64_i32 v[76:77], s[22:23], v76, s15, v[24:25]
	v_mad_i64_i32 v[78:79], s[22:23], v78, s15, v[24:25]
	global_load_dword v48, v[48:49], off
	s_nop 0
	global_load_dword v49, v[50:51], off
	s_nop 0
	global_load_dword v50, v[52:53], off
	global_load_dword v51, v[54:55], off
	s_nop 0
	global_load_dword v52, v[56:57], off
	global_load_dword v53, v[58:59], off
	global_load_dword v54, v[60:61], off
	global_load_dword v55, v[62:63], off
	s_nop 0
	global_load_dword v56, v[64:65], off
	global_load_dword v57, v[66:67], off
	global_load_dword v58, v[68:69], off
	global_load_dword v59, v[70:71], off
	global_load_dword v60, v[72:73], off
	global_load_dword v61, v[74:75], off
	global_load_dword v62, v[76:77], off
	global_load_dword v63, v[78:79], off
	s_add_i32 s18, s18, 16
	s_add_i32 s17, s17, 16
	s_add_i32 s19, s19, -16
	v_add_u32_e32 v64, s20, v0
	v_add_u32_e32 v66, s21, v1
	v_add_u32_e32 v68, s20, v8
	v_add_u32_e32 v70, s21, v3
	v_add_u32_e32 v72, s20, v10
	v_add_u32_e32 v74, s21, v5
	v_add_u32_e32 v76, s20, v12
	v_add_u32_e32 v78, s21, v9
	v_add_u32_e32 v80, s20, v14
	v_add_u32_e32 v82, s21, v11
	v_add_u32_e32 v84, s20, v16
	v_add_u32_e32 v86, s21, v13
	v_add_u32_e32 v88, s20, v18
	v_add_u32_e32 v90, s21, v15
	v_add_u32_e32 v92, s20, v22
	v_add_u32_e32 v94, s21, v17
	s_cmp_lg_u32 s19, 0
	v_mad_u64_u32 v[64:65], s[20:21], v64, s14, v[2:3]
	v_mad_u64_u32 v[66:67], s[20:21], v66, s14, v[2:3]
	v_mad_u64_u32 v[68:69], s[20:21], v68, s14, v[2:3]
	v_mad_u64_u32 v[70:71], s[20:21], v70, s14, v[2:3]
	v_mad_u64_u32 v[72:73], s[20:21], v72, s14, v[2:3]
	v_mad_u64_u32 v[74:75], s[20:21], v74, s14, v[2:3]
	v_mad_u64_u32 v[76:77], s[20:21], v76, s14, v[2:3]
	v_mad_u64_u32 v[78:79], s[20:21], v78, s14, v[2:3]
	v_mad_u64_u32 v[80:81], s[20:21], v80, s14, v[2:3]
	v_mad_u64_u32 v[82:83], s[20:21], v82, s14, v[2:3]
	v_mad_u64_u32 v[84:85], s[20:21], v84, s14, v[2:3]
	v_mad_u64_u32 v[86:87], s[20:21], v86, s14, v[2:3]
	v_mad_u64_u32 v[88:89], s[20:21], v88, s14, v[2:3]
	v_mad_u64_u32 v[90:91], s[20:21], v90, s14, v[2:3]
	v_mad_u64_u32 v[92:93], s[20:21], v92, s14, v[2:3]
	v_mad_u64_u32 v[94:95], s[20:21], v94, s14, v[2:3]
	s_waitcnt vmcnt(0)
	v_pk_mul_f32 v[48:49], v[26:27], v[48:49]
	v_pk_mul_f32 v[50:51], v[26:27], v[50:51]
	v_pk_mul_f32 v[52:53], v[26:27], v[52:53]
	v_pk_mul_f32 v[54:55], v[26:27], v[54:55]
	v_pk_mul_f32 v[56:57], v[26:27], v[56:57]
	v_pk_mul_f32 v[58:59], v[26:27], v[58:59]
	v_pk_mul_f32 v[60:61], v[26:27], v[60:61]
	v_pk_mul_f32 v[62:63], v[26:27], v[62:63]
	ds_write_b32 v64, v48
	ds_write_b32 v66, v49
	ds_write_b32 v68, v50
	ds_write_b32 v70, v51
	ds_write_b32 v72, v52
	ds_write_b32 v74, v53
	ds_write_b32 v76, v54
	ds_write_b32 v78, v55
	ds_write_b32 v80, v56
	ds_write_b32 v82, v57
	ds_write_b32 v84, v58
	ds_write_b32 v86, v59
	ds_write_b32 v88, v60
	ds_write_b32 v90, v61
	ds_write_b32 v92, v62
	ds_write_b32 v94, v63
	s_cbranch_scc1 .LBB0_33
	s_waitcnt lgkmcnt(0)
	ds_read_b32 v19, v42
	ds_read_b32 v21, v42 offset:132
	ds_read_b32 v23, v42 offset:264
	ds_read_b32 v25, v42 offset:396
	ds_read_b32 v26, v42 offset:528
	ds_read_b32 v27, v42 offset:660
	ds_read_b32 v30, v42 offset:792
	ds_read_b32 v31, v42 offset:924
	s_mul_hi_i32 s17, s7, 0x1c00000
	s_mul_i32 s7, s7, 0x1c00000
	s_add_u32 s18, s8, s7
	s_addc_u32 s17, s9, s17
	s_ashr_i32 s7, s6, 31
	s_lshl_b64 s[6:7], s[6:7], 1
	s_add_u32 s6, s18, s6
	s_waitcnt lgkmcnt(0)
	v_cvt_pk_bf16_f32 v26, v26, v27
	v_cvt_pk_bf16_f32 v27, v30, v31
	v_add_u32_e32 v30, s0, v41
	s_addc_u32 s7, s17, s7
	v_lshlrev_b32_e32 v6, 1, v4
	v_ashrrev_i32_e32 v31, 31, v30
	v_lshl_add_u64 v[28:29], s[6:7], 0, v[6:7]
	v_lshlrev_b64 v[30:31], 12, v[30:31]
	v_cvt_pk_bf16_f32 v24, v19, v21
	v_cvt_pk_bf16_f32 v25, v23, v25
	v_lshl_add_u64 v[30:31], v[28:29], 0, v[30:31]
	global_store_dwordx4 v[30:31], v[24:27], off
	ds_read_b32 v6, v42 offset:32
	ds_read_b32 v19, v42 offset:164
	ds_read_b32 v21, v42 offset:296
	ds_read_b32 v23, v42 offset:428
	ds_read_b32 v26, v42 offset:560
	ds_read_b32 v27, v42 offset:692
	ds_read_b32 v30, v42 offset:824
	ds_read_b32 v31, v42 offset:956
	s_waitcnt lgkmcnt(0)
	v_cvt_pk_bf16_f32 v24, v6, v19
	v_cvt_pk_bf16_f32 v25, v21, v23
	v_cvt_pk_bf16_f32 v26, v26, v27
	v_cvt_pk_bf16_f32 v27, v30, v31
	v_add_u32_e32 v30, s0, v43
	v_ashrrev_i32_e32 v31, 31, v30
	v_lshlrev_b64 v[30:31], 12, v[30:31]
	v_lshl_add_u64 v[30:31], v[28:29], 0, v[30:31]
	global_store_dwordx4 v[30:31], v[24:27], off
	ds_read_b32 v6, v42 offset:64
	ds_read_b32 v19, v42 offset:196
	ds_read_b32 v21, v42 offset:328
	ds_read_b32 v23, v42 offset:460
	ds_read_b32 v26, v42 offset:592
	ds_read_b32 v27, v42 offset:724
	ds_read_b32 v30, v42 offset:856
	ds_read_b32 v31, v42 offset:988
	s_waitcnt lgkmcnt(0)
	v_cvt_pk_bf16_f32 v24, v6, v19
	v_cvt_pk_bf16_f32 v25, v21, v23
	v_cvt_pk_bf16_f32 v26, v26, v27
	v_cvt_pk_bf16_f32 v27, v30, v31
	v_add_u32_e32 v30, s0, v44
	v_ashrrev_i32_e32 v31, 31, v30
	v_lshlrev_b64 v[30:31], 12, v[30:31]
	v_lshl_add_u64 v[30:31], v[28:29], 0, v[30:31]
	global_store_dwordx4 v[30:31], v[24:27], off
	ds_read_b32 v6, v42 offset:96
	ds_read_b32 v19, v42 offset:228
	ds_read_b32 v21, v42 offset:360
	ds_read_b32 v23, v42 offset:492
	ds_read_b32 v26, v42 offset:624
	ds_read_b32 v27, v42 offset:756
	ds_read_b32 v30, v42 offset:888
	ds_read_b32 v31, v42 offset:1020
	s_waitcnt lgkmcnt(0)
	v_cvt_pk_bf16_f32 v24, v6, v19
	v_cvt_pk_bf16_f32 v25, v21, v23
	v_cvt_pk_bf16_f32 v26, v26, v27
	v_cvt_pk_bf16_f32 v27, v30, v31
	v_add_u32_e32 v30, s0, v45
	v_ashrrev_i32_e32 v31, 31, v30
	v_lshlrev_b64 v[30:31], 12, v[30:31]
	v_lshl_add_u64 v[28:29], v[28:29], 0, v[30:31]
	global_store_dwordx4 v[28:29], v[24:27], off
	s_waitcnt lgkmcnt(0)
	s_branch .LBB0_17

.LBB0_37:
	v_add_co_u32_e32 v60, vcc, 0xfffff000, v26
	global_load_dwordx4 v[0:3], v[26:27], off nt
	s_nop 0
	v_addc_co_u32_e32 v61, vcc, -1, v27, vcc
	global_load_dwordx4 v[4:7], v[26:27], off offset:-2048 nt
	global_load_dwordx4 v[36:39], v[26:27], off offset:-3072 nt
	global_load_dwordx4 v[40:43], v[60:61], off offset:-1024 nt
	global_load_dwordx4 v[44:47], v[26:27], off offset:-4096 nt
	global_load_dwordx4 v[48:51], v[60:61], off offset:-3072 nt
	global_load_dwordx4 v[52:55], v[60:61], off offset:-2048 nt
	global_load_dwordx4 v[8:11], v[26:27], off offset:-1024 nt
	global_load_dwordx4 v[56:59], v[12:13], off
	s_add_i32 s11, s11, s68
	s_cmpk_gt_i32 s11, 0xfff
	v_lshl_add_u64 v[26:27], v[26:27], 0, s[8:9]
	s_waitcnt vmcnt(0)
	v_mul_f32_e32 v78, v45, v45
	v_mul_f32_e32 v70, v2, v2
	v_pk_mul_f32 v[60:61], v[6:7], v[6:7]
	v_pk_mul_f32 v[62:63], v[4:5], v[4:5]
	v_mul_f32_e32 v64, v9, v9
	v_mul_f32_e32 v66, v11, v11
	v_mul_f32_e32 v71, v3, v3
	v_pk_mov_b32 v[68:69], v[62:63], v[60:61] op_sel:[1,0]
	v_mov_b32_e32 v63, v61
	v_pk_fma_f32 v[60:61], v[8:9], v[8:9], v[64:65] op_sel_hi:[1,1,0]
	v_pk_fma_f32 v[64:65], v[10:11], v[10:11], v[66:67] op_sel_hi:[1,1,0]
	v_pk_mul_f32 v[66:67], v[42:43], v[42:43]
	v_pk_add_f32 v[62:63], v[68:69], v[62:63]
	v_pk_mul_f32 v[68:69], v[40:41], v[40:41]
	v_mov_b32_e32 v61, v70
	v_mov_b32_e32 v65, v71
	v_mov_b32_e32 v72, v49
	v_mov_b32_e32 v73, v53
	v_mov_b32_e32 v76, v51
	v_mov_b32_e32 v77, v55
	v_mov_b32_e32 v70, v48
	v_mov_b32_e32 v71, v52
	v_mov_b32_e32 v74, v50
	v_mov_b32_e32 v75, v54
	v_pk_mov_b32 v[82:83], v[68:69], v[66:67] op_sel:[1,0]
	v_mov_b32_e32 v69, v67
	v_pk_add_f32 v[60:61], v[60:61], v[64:65]
	v_pk_mul_f32 v[64:65], v[72:73], v[72:73]
	v_pk_mul_f32 v[66:67], v[76:77], v[76:77]
	v_pk_fma_f32 v[64:65], v[70:71], v[70:71], v[64:65]
	v_pk_fma_f32 v[66:67], v[74:75], v[74:75], v[66:67]
	v_mul_f32_e32 v79, v38, v38
	v_mul_f32_e32 v81, v39, v39
	v_mul_f32_e32 v80, v47, v47
	v_pk_add_f32 v[68:69], v[82:83], v[68:69]
	v_pk_add_f32 v[64:65], v[64:65], v[66:67]
	v_mul_f32_e32 v84, v37, v37
	v_mul_f32_e32 v85, v36, v36
	v_pk_fma_f32 v[72:73], v[44:45], v[44:45], v[78:79] op_sel_hi:[1,1,0]
	v_pk_fma_f32 v[76:77], v[46:47], v[46:47], v[80:81] op_sel_hi:[1,1,0]
	v_pk_add_f32 v[68:69], v[68:69], v[68:69] op_sel:[0,1] op_sel_hi:[1,0]
	v_pk_add_f32 v[64:65], v[64:65], v[64:65] op_sel:[0,1] op_sel_hi:[1,0]
	v_mov_b32_e32 v73, v79
	v_mov_b32_e32 v77, v81
	v_mov_b32_e32 v69, v84
	v_mov_b32_e32 v65, v85
	v_pk_add_f32 v[66:67], v[72:73], v[76:77]
	v_pk_add_f32 v[64:65], v[64:65], v[68:69]
	v_mul_f32_e32 v86, v1, v1
	v_pk_add_f32 v[64:65], v[64:65], v[66:67]
	v_mul_f32_e32 v87, v0, v0
	v_pk_add_f32 v[62:63], v[62:63], v[62:63] op_sel:[0,1] op_sel_hi:[1,0]
	v_pk_add_f32 v[64:65], v[64:65], v[64:65] op_sel:[0,1] op_sel_hi:[1,0]
	v_mov_b32_e32 v63, v86
	v_mov_b32_e32 v65, v87
	v_pk_add_f32 v[62:63], v[64:65], v[62:63]
	s_nop 0
	v_pk_add_f32 v[60:61], v[62:63], v[60:61]
	s_nop 0
	v_add_f32_e32 v60, v60, v61
	ds_bpermute_b32 v61, v28, v60
	s_waitcnt lgkmcnt(0)
	v_add_f32_e32 v60, v60, v61
	ds_bpermute_b32 v61, v29, v60
	s_waitcnt lgkmcnt(0)
	v_add_f32_e32 v60, v60, v61
	ds_bpermute_b32 v61, v30, v60
	s_waitcnt lgkmcnt(0)
	v_add_f32_e32 v60, v60, v61
	ds_bpermute_b32 v61, v31, v60
	s_waitcnt lgkmcnt(0)
	v_add_f32_e32 v60, v60, v61
	ds_bpermute_b32 v61, v32, v60
	s_waitcnt lgkmcnt(0)
	v_add_f32_e32 v60, v60, v61
	ds_bpermute_b32 v61, v33, v60
	s_waitcnt lgkmcnt(0)
	v_add_f32_e32 v60, v60, v61
	v_fmamk_f32 v60, v60, 0x3a000000, v34
	v_mul_f32_e32 v61, 0x4f800000, v60
	v_cmp_gt_f32_e32 vcc, s10, v60
	s_nop 1
	v_cndmask_b32_e32 v60, v60, v61, vcc
	v_sqrt_f32_e32 v61, v60
	s_nop 0
	v_add_u32_e32 v62, -1, v61
	v_add_u32_e32 v63, 1, v61
	v_fma_f32 v64, -v62, v61, v60
	v_fma_f32 v65, -v63, v61, v60
	v_cmp_ge_f32_e64 s[0:1], 0, v64
	s_nop 1
	v_cndmask_b32_e64 v61, v61, v62, s[0:1]
	v_cmp_lt_f32_e64 s[0:1], 0, v65
	s_nop 1
	v_cndmask_b32_e64 v61, v61, v63, s[0:1]
	v_mul_f32_e32 v62, 0x37800000, v61
	v_cndmask_b32_e32 v61, v61, v62, vcc
	v_cmp_class_f32_e32 vcc, v60, v35
	s_nop 1
	v_cndmask_b32_e32 v60, v61, v60, vcc
	v_div_scale_f32 v61, s[0:1], v60, v60, 1.0
	v_rcp_f32_e32 v63, v61
	v_div_scale_f32 v62, vcc, 1.0, v60, 1.0
	v_fma_f32 v64, -v61, v63, 1.0
	v_fmac_f32_e32 v63, v64, v63
	v_mul_f32_e32 v64, v62, v63
	v_fma_f32 v65, -v61, v64, v62
	v_fmac_f32_e32 v64, v65, v63
	v_fma_f32 v61, -v61, v64, v62
	v_div_fmas_f32 v61, v61, v63, v64
	v_div_fixup_f32 v60, v61, v60, 1.0
	v_pk_mul_f32 v[48:49], v[48:49], v[60:61] op_sel_hi:[1,0]
	v_pk_mul_f32 v[50:51], v[50:51], v[60:61] op_sel_hi:[1,0]
	v_pk_mul_f32 v[48:49], v[56:57], v[48:49]
	v_pk_mul_f32 v[50:51], v[58:59], v[50:51]
	v_cvt_pk_bf16_f32 v48, v48, v49
	v_cvt_pk_bf16_f32 v49, v50, v51
	global_store_dwordx2 v[24:25], v[48:49], off
	global_load_dwordx4 v[48:51], v[12:13], off offset:1024
	v_pk_mul_f32 v[52:53], v[52:53], v[60:61] op_sel_hi:[1,0]
	v_pk_mul_f32 v[54:55], v[54:55], v[60:61] op_sel_hi:[1,0]
	v_pk_mul_f32 v[40:41], v[40:41], v[60:61] op_sel_hi:[1,0]
	v_pk_mul_f32 v[42:43], v[42:43], v[60:61] op_sel_hi:[1,0]
	v_pk_mul_f32 v[44:45], v[44:45], v[60:61] op_sel_hi:[1,0]
	v_pk_mul_f32 v[46:47], v[46:47], v[60:61] op_sel_hi:[1,0]
	v_pk_mul_f32 v[36:37], v[36:37], v[60:61] op_sel_hi:[1,0]
	v_pk_mul_f32 v[38:39], v[38:39], v[60:61] op_sel_hi:[1,0]
	v_pk_mul_f32 v[4:5], v[4:5], v[60:61] op_sel_hi:[1,0]
	v_pk_mul_f32 v[6:7], v[6:7], v[60:61] op_sel_hi:[1,0]
	v_pk_mul_f32 v[8:9], v[8:9], v[60:61] op_sel_hi:[1,0]
	v_pk_mul_f32 v[10:11], v[10:11], v[60:61] op_sel_hi:[1,0]
	v_pk_mul_f32 v[0:1], v[0:1], v[60:61] op_sel_hi:[1,0]
	v_pk_mul_f32 v[2:3], v[2:3], v[60:61] op_sel_hi:[1,0]
	s_waitcnt vmcnt(0)
	v_pk_mul_f32 v[48:49], v[48:49], v[52:53]
	v_pk_mul_f32 v[50:51], v[50:51], v[54:55]
	v_cvt_pk_bf16_f32 v48, v48, v49
	v_cvt_pk_bf16_f32 v49, v50, v51
	global_store_dwordx2 v[24:25], v[48:49], off offset:512
	global_load_dwordx4 v[48:51], v[12:13], off offset:2048
	s_waitcnt vmcnt(0)
	v_pk_mul_f32 v[40:41], v[48:49], v[40:41]
	v_pk_mul_f32 v[42:43], v[50:51], v[42:43]
	v_cvt_pk_bf16_f32 v40, v40, v41
	v_cvt_pk_bf16_f32 v41, v42, v43
	global_store_dwordx2 v[24:25], v[40:41], off offset:1024
	global_load_dwordx4 v[40:43], v[12:13], off offset:3072
	s_waitcnt vmcnt(0)
	v_pk_mul_f32 v[40:41], v[44:45], v[40:41]
	v_pk_mul_f32 v[42:43], v[46:47], v[42:43]
	v_cvt_pk_bf16_f32 v40, v40, v41
	v_cvt_pk_bf16_f32 v41, v42, v43
	global_store_dwordx2 v[24:25], v[40:41], off offset:1536
	global_load_dwordx4 v[40:43], v[14:15], off
	s_waitcnt vmcnt(0)
	v_pk_mul_f32 v[36:37], v[36:37], v[40:41]
	v_pk_mul_f32 v[38:39], v[38:39], v[42:43]
	v_cvt_pk_bf16_f32 v36, v36, v37
	v_cvt_pk_bf16_f32 v37, v38, v39
	global_store_dwordx2 v[24:25], v[36:37], off offset:2048
	global_load_dwordx4 v[36:39], v[16:17], off
	s_waitcnt vmcnt(0)
	v_pk_mul_f32 v[4:5], v[4:5], v[36:37]
	v_pk_mul_f32 v[6:7], v[6:7], v[38:39]
	v_cvt_pk_bf16_f32 v4, v4, v5
	v_cvt_pk_bf16_f32 v5, v6, v7
	global_store_dwordx2 v[24:25], v[4:5], off offset:2560
	global_load_dwordx4 v[4:7], v[18:19], off
	s_waitcnt vmcnt(0)
	v_pk_mul_f32 v[4:5], v[8:9], v[4:5]
	v_pk_mul_f32 v[6:7], v[10:11], v[6:7]
	v_cvt_pk_bf16_f32 v4, v4, v5
	v_cvt_pk_bf16_f32 v5, v6, v7
	global_store_dwordx2 v[24:25], v[4:5], off offset:3072
	global_load_dwordx4 v[4:7], v[22:23], off
	s_waitcnt vmcnt(0)
	v_pk_mul_f32 v[0:1], v[0:1], v[4:5]
	v_pk_mul_f32 v[2:3], v[2:3], v[6:7]
	v_cvt_pk_bf16_f32 v0, v0, v1
	v_cvt_pk_bf16_f32 v1, v2, v3
	global_store_dwordx2 v[24:25], v[0:1], off offset:3584
	v_lshl_add_u64 v[24:25], v[24:25], 0, s[6:7]
	s_cbranch_scc0 .LBB0_37

.LBB0_40:
	v_add_co_u32_e32 v60, vcc, 0xfffff000, v34
	global_load_dwordx4 v[4:7], v[34:35], off offset:-3072 nt
	global_load_dwordx4 v[8:11], v[34:35], off offset:-2048 nt
	global_load_dwordx4 v[0:3], v[34:35], off nt
	v_addc_co_u32_e32 v61, vcc, -1, v35, vcc
	global_load_dwordx4 v[44:47], v[60:61], off offset:-3072 nt
	global_load_dwordx4 v[48:51], v[60:61], off offset:-2048 nt
	global_load_dwordx4 v[52:55], v[60:61], off offset:-1024 nt
	global_load_dwordx4 v[16:19], v[34:35], off offset:-4096 nt
	global_load_dwordx4 v[12:15], v[34:35], off offset:-1024 nt
	global_load_dwordx4 v[56:59], v[22:23], off
	s_add_i32 s11, s11, s68
	s_cmpk_gt_i32 s11, 0x7fff
	v_lshl_add_u64 v[34:35], v[34:35], 0, s[8:9]
	s_waitcnt vmcnt(0)
	v_mov_b32_e32 v76, v47
	v_pk_mul_f32 v[60:61], v[10:11], v[10:11]
	v_pk_mul_f32 v[62:63], v[8:9], v[8:9]
	v_mul_f32_e32 v43, v2, v2
	v_mul_f32_e32 v64, v13, v13
	v_mul_f32_e32 v66, v15, v15
	v_mul_f32_e32 v72, v3, v3
	v_pk_mov_b32 v[68:69], v[62:63], v[60:61] op_sel:[1,0]
	v_mov_b32_e32 v63, v61
	v_pk_fma_f32 v[60:61], v[12:13], v[12:13], v[64:65] op_sel_hi:[1,1,0]
	v_pk_fma_f32 v[64:65], v[14:15], v[14:15], v[66:67] op_sel_hi:[1,1,0]
	v_pk_mul_f32 v[70:71], v[54:55], v[54:55]
	v_pk_add_f32 v[62:63], v[68:69], v[62:63]
	v_pk_mul_f32 v[68:69], v[52:53], v[52:53]
	v_mov_b32_e32 v61, v43
	v_mov_b32_e32 v65, v72
	v_mov_b32_e32 v72, v45
	v_mov_b32_e32 v73, v49
	v_mov_b32_e32 v77, v51
	v_mov_b32_e32 v66, v44
	v_mov_b32_e32 v67, v48
	v_mov_b32_e32 v74, v46
	v_mov_b32_e32 v75, v50
	v_pk_mov_b32 v[82:83], v[68:69], v[70:71] op_sel:[1,0]
	v_mov_b32_e32 v69, v71
	v_pk_add_f32 v[60:61], v[60:61], v[64:65]
	v_pk_mul_f32 v[64:65], v[72:73], v[72:73]
	v_pk_mul_f32 v[70:71], v[76:77], v[76:77]
	v_pk_fma_f32 v[64:65], v[66:67], v[66:67], v[64:65]
	v_pk_fma_f32 v[66:67], v[74:75], v[74:75], v[70:71]
	v_mul_f32_e32 v79, v4, v4
	v_mul_f32_e32 v81, v6, v6
	v_mul_f32_e32 v78, v17, v17
	v_mul_f32_e32 v80, v19, v19
	v_pk_add_f32 v[68:69], v[82:83], v[68:69]
	v_pk_add_f32 v[64:65], v[64:65], v[66:67]
	v_mul_f32_e32 v84, v7, v7
	v_mul_f32_e32 v85, v5, v5
	v_pk_fma_f32 v[72:73], v[16:17], v[16:17], v[78:79] op_sel_hi:[1,1,0]
	v_pk_fma_f32 v[76:77], v[18:19], v[18:19], v[80:81] op_sel_hi:[1,1,0]
	v_pk_add_f32 v[66:67], v[68:69], v[68:69] op_sel:[0,1] op_sel_hi:[1,0]
	v_pk_add_f32 v[64:65], v[64:65], v[64:65] op_sel:[0,1] op_sel_hi:[1,0]
	v_mov_b32_e32 v73, v81
	v_mov_b32_e32 v77, v84
	v_mov_b32_e32 v67, v85
	v_mov_b32_e32 v65, v79
	v_pk_add_f32 v[68:69], v[72:73], v[76:77]
	v_pk_add_f32 v[64:65], v[64:65], v[66:67]
	v_mul_f32_e32 v86, v0, v0
	v_pk_add_f32 v[64:65], v[64:65], v[68:69]
	v_mul_f32_e32 v87, v1, v1
	v_pk_add_f32 v[62:63], v[62:63], v[62:63] op_sel:[0,1] op_sel_hi:[1,0]
	v_pk_add_f32 v[64:65], v[64:65], v[64:65] op_sel:[0,1] op_sel_hi:[1,0]
	v_mov_b32_e32 v63, v87
	v_mov_b32_e32 v65, v86
	v_pk_add_f32 v[62:63], v[64:65], v[62:63]
	s_nop 0
	v_pk_add_f32 v[60:61], v[62:63], v[60:61]
	s_nop 0
	v_add_f32_e32 v43, v60, v61
	ds_bpermute_b32 v60, v36, v43
	s_waitcnt lgkmcnt(0)
	v_add_f32_e32 v43, v43, v60
	ds_bpermute_b32 v60, v37, v43
	s_waitcnt lgkmcnt(0)
	v_add_f32_e32 v43, v43, v60
	ds_bpermute_b32 v60, v38, v43
	s_waitcnt lgkmcnt(0)
	v_add_f32_e32 v43, v43, v60
	ds_bpermute_b32 v60, v39, v43
	s_waitcnt lgkmcnt(0)
	v_add_f32_e32 v43, v43, v60
	ds_bpermute_b32 v60, v40, v43
	s_waitcnt lgkmcnt(0)
	v_add_f32_e32 v43, v43, v60
	ds_bpermute_b32 v60, v41, v43
	s_waitcnt lgkmcnt(0)
	v_add_f32_e32 v43, v43, v60
	v_fmamk_f32 v43, v43, 0x3a000000, v21
	v_mul_f32_e32 v60, 0x4f800000, v43
	v_cmp_gt_f32_e32 vcc, s10, v43
	s_nop 1
	v_cndmask_b32_e32 v43, v43, v60, vcc
	v_sqrt_f32_e32 v60, v43
	s_nop 0
	v_add_u32_e32 v61, -1, v60
	v_add_u32_e32 v62, 1, v60
	v_fma_f32 v63, -v61, v60, v43
	v_fma_f32 v64, -v62, v60, v43
	v_cmp_ge_f32_e64 s[0:1], 0, v63
	s_nop 1
	v_cndmask_b32_e64 v60, v60, v61, s[0:1]
	v_cmp_lt_f32_e64 s[0:1], 0, v64
	s_nop 1
	v_cndmask_b32_e64 v60, v60, v62, s[0:1]
	v_mul_f32_e32 v61, 0x37800000, v60
	v_cndmask_b32_e32 v60, v60, v61, vcc
	v_cmp_class_f32_e32 vcc, v43, v42
	s_nop 1
	v_cndmask_b32_e32 v43, v60, v43, vcc
	v_div_scale_f32 v60, s[0:1], v43, v43, 1.0
	v_rcp_f32_e32 v62, v60
	v_div_scale_f32 v61, vcc, 1.0, v43, 1.0
	v_fma_f32 v63, -v60, v62, 1.0
	v_fmac_f32_e32 v62, v63, v62
	v_mul_f32_e32 v63, v61, v62
	v_fma_f32 v64, -v60, v63, v61
	v_fmac_f32_e32 v63, v64, v62
	v_fma_f32 v60, -v60, v63, v61
	v_div_fmas_f32 v60, v60, v62, v63
	v_div_fixup_f32 v60, v60, v43, 1.0
	v_pk_mul_f32 v[44:45], v[44:45], v[60:61] op_sel_hi:[1,0]
	v_pk_mul_f32 v[46:47], v[46:47], v[60:61] op_sel_hi:[1,0]
	v_pk_mul_f32 v[44:45], v[56:57], v[44:45]
	v_pk_mul_f32 v[46:47], v[58:59], v[46:47]
	v_cvt_pk_bf16_f32 v44, v44, v45
	v_cvt_pk_bf16_f32 v45, v46, v47
	global_store_dwordx2 v[32:33], v[44:45], off
	global_load_dwordx4 v[44:47], v[22:23], off offset:1024
	v_pk_mul_f32 v[48:49], v[48:49], v[60:61] op_sel_hi:[1,0]
	v_pk_mul_f32 v[50:51], v[50:51], v[60:61] op_sel_hi:[1,0]
	v_pk_mul_f32 v[16:17], v[16:17], v[60:61] op_sel_hi:[1,0]
	v_pk_mul_f32 v[18:19], v[18:19], v[60:61] op_sel_hi:[1,0]
	v_pk_mul_f32 v[4:5], v[4:5], v[60:61] op_sel_hi:[1,0]
	v_pk_mul_f32 v[6:7], v[6:7], v[60:61] op_sel_hi:[1,0]
	v_pk_mul_f32 v[8:9], v[8:9], v[60:61] op_sel_hi:[1,0]
	v_pk_mul_f32 v[10:11], v[10:11], v[60:61] op_sel_hi:[1,0]
	v_pk_mul_f32 v[0:1], v[0:1], v[60:61] op_sel_hi:[1,0]
	v_pk_mul_f32 v[2:3], v[2:3], v[60:61] op_sel_hi:[1,0]
	s_waitcnt vmcnt(0)
	v_pk_mul_f32 v[44:45], v[44:45], v[48:49]
	v_pk_mul_f32 v[46:47], v[46:47], v[50:51]
	v_cvt_pk_bf16_f32 v44, v44, v45
	v_cvt_pk_bf16_f32 v45, v46, v47
	global_store_dwordx2 v[32:33], v[44:45], off offset:512
	global_load_dwordx4 v[44:47], v[22:23], off offset:2048
	v_pk_mul_f32 v[48:49], v[52:53], v[60:61] op_sel_hi:[1,0]
	v_pk_mul_f32 v[50:51], v[54:55], v[60:61] op_sel_hi:[1,0]
	s_waitcnt vmcnt(0)
	v_pk_mul_f32 v[44:45], v[44:45], v[48:49]
	v_pk_mul_f32 v[46:47], v[46:47], v[50:51]
	v_cvt_pk_bf16_f32 v44, v44, v45
	v_cvt_pk_bf16_f32 v45, v46, v47
	global_store_dwordx2 v[32:33], v[44:45], off offset:1024
	global_load_dwordx4 v[44:47], v[22:23], off offset:3072
	s_waitcnt vmcnt(0)
	v_pk_mul_f32 v[16:17], v[16:17], v[44:45]
	v_pk_mul_f32 v[18:19], v[18:19], v[46:47]
	v_cvt_pk_bf16_f32 v16, v16, v17
	v_cvt_pk_bf16_f32 v17, v18, v19
	global_store_dwordx2 v[32:33], v[16:17], off offset:1536
	global_load_dwordx4 v[16:19], v[24:25], off
	s_waitcnt vmcnt(0)
	v_pk_mul_f32 v[4:5], v[4:5], v[16:17]
	v_pk_mul_f32 v[6:7], v[6:7], v[18:19]
	v_cvt_pk_bf16_f32 v4, v4, v5
	v_cvt_pk_bf16_f32 v5, v6, v7
	global_store_dwordx2 v[32:33], v[4:5], off offset:2048
	global_load_dwordx4 v[4:7], v[26:27], off
	s_waitcnt vmcnt(0)
	v_pk_mul_f32 v[4:5], v[8:9], v[4:5]
	v_pk_mul_f32 v[6:7], v[10:11], v[6:7]
	v_cvt_pk_bf16_f32 v4, v4, v5
	v_cvt_pk_bf16_f32 v5, v6, v7
	global_store_dwordx2 v[32:33], v[4:5], off offset:2560
	global_load_dwordx4 v[4:7], v[28:29], off
	v_pk_mul_f32 v[8:9], v[12:13], v[60:61] op_sel_hi:[1,0]
	v_pk_mul_f32 v[10:11], v[14:15], v[60:61] op_sel_hi:[1,0]
	s_waitcnt vmcnt(0)
	v_pk_mul_f32 v[4:5], v[8:9], v[4:5]
	v_pk_mul_f32 v[6:7], v[10:11], v[6:7]
	v_cvt_pk_bf16_f32 v4, v4, v5
	v_cvt_pk_bf16_f32 v5, v6, v7
	global_store_dwordx2 v[32:33], v[4:5], off offset:3072
	global_load_dwordx4 v[4:7], v[30:31], off
	s_waitcnt vmcnt(0)
	v_pk_mul_f32 v[0:1], v[0:1], v[4:5]
	v_pk_mul_f32 v[2:3], v[2:3], v[6:7]
	v_cvt_pk_bf16_f32 v0, v0, v1
	v_cvt_pk_bf16_f32 v1, v2, v3
	global_store_dwordx2 v[32:33], v[0:1], off offset:3584
	v_lshl_add_u64 v[32:33], v[32:33], 0, s[6:7]
	s_cbranch_scc0 .LBB0_40

.LBB0_43:
	s_or_b64 exec, exec, s[0:1]
	v_mul_f32_e32 v14, v4, v4
	v_fmamk_f32 v15, v14, 0xb94c1982, v1
	v_fmaak_f32 v15, v14, v15, 0xbe2aaa9d
	v_mul_f32_e32 v15, v14, v15
	v_fmac_f32_e32 v4, v4, v15
	v_fmamk_f32 v15, v14, 0x37d75334, v8
	v_fmaak_f32 v15, v14, v15, 0x3d2aabf7
	v_fmaak_f32 v15, v14, v15, 0xbf000004
	v_fma_f32 v14, v14, v15, 1.0
	v_lshlrev_b32_e32 v15, 30, v13
	v_and_b32_e32 v13, 1, v13
	v_cmp_eq_u32_e32 vcc, 0, v13
	v_xor_b32_e32 v12, v12, v11
	v_and_b32_e32 v16, 0x80000000, v15
	v_cndmask_b32_e32 v13, v14, v4, vcc
	v_xor_b32_e32 v4, 0x80000000, v4
	v_xor_b32_e32 v12, v12, v13
	v_cndmask_b32_e32 v4, v4, v14, vcc
	v_xor_b32_e32 v12, v12, v16
	v_bitop3_b32 v4, v4, v15, s28 bitop3:0x78
	v_cmp_class_f32_e64 vcc, v11, s29
	v_add_u32_e32 v0, s10, v0
	s_nop 0
	v_cndmask_b32_e32 v4, v10, v4, vcc
	v_cndmask_b32_e32 v11, v10, v12, vcc
	v_add_co_u32_e32 v12, vcc, 0xfff80000, v2
	s_nop 1
	v_addc_co_u32_e32 v13, vcc, -1, v3, vcc
	v_cmp_lt_i32_e32 vcc, s30, v0
	global_store_dword v[12:13], v4, off
	global_store_dword v[2:3], v11, off
	s_or_b64 s[14:15], vcc, s[14:15]
	v_lshl_add_u64 v[2:3], v[2:3], 0, s[12:13]
	s_andn2_b64 exec, exec, s[14:15]
	s_cbranch_execz .LBB0_48

.LBB0_123:
	v_lshl_add_u32 v154, s30, 8, v147
	v_lshl_or_b32 v144, s68, 8, v149
	v_ashrrev_i32_e32 v155, 31, v154
	v_ashrrev_i32_e32 v145, 31, v144
	v_lshlrev_b64 v[156:157], 13, v[154:155]
	v_lshl_add_u64 v[156:157], s[6:7], 0, v[156:157]
	v_lshlrev_b64 v[158:159], 1, v[144:145]
	v_lshl_add_u64 v[144:145], v[156:157], 0, v[158:159]
	v_cvt_pk_bf16_f32 v124, v124, v125
	v_cvt_pk_bf16_f32 v125, v126, v127
	v_cvt_pk_bf16_f32 v126, v120, v121
	v_cvt_pk_bf16_f32 v127, v122, v123
	global_store_dwordx4 v[144:145], v[124:127], off
	v_cvt_pk_bf16_f32 v112, v112, v113
	v_cvt_pk_bf16_f32 v113, v114, v115
	v_cvt_pk_bf16_f32 v114, v104, v105
	v_or_b32_e32 v104, 16, v154
	v_ashrrev_i32_e32 v105, 31, v104
	v_lshlrev_b64 v[104:105], 13, v[104:105]
	v_lshl_add_u64 v[104:105], s[6:7], 0, v[104:105]
	v_cvt_pk_bf16_f32 v115, v106, v107
	global_store_dwordx4 v[144:145], v[112:115], off offset:256
	s_nop 1
	v_lshl_add_u64 v[112:113], v[104:105], 0, v[158:159]
	v_cvt_pk_bf16_f32 v104, v116, v117
	v_cvt_pk_bf16_f32 v105, v118, v119
	v_cvt_pk_bf16_f32 v106, v108, v109
	v_cvt_pk_bf16_f32 v107, v110, v111
	global_store_dwordx4 v[112:113], v[104:107], off
	v_cvt_pk_bf16_f32 v96, v96, v97
	v_cvt_pk_bf16_f32 v97, v98, v99
	v_cvt_pk_bf16_f32 v98, v88, v89
	v_or_b32_e32 v88, 32, v154
	v_ashrrev_i32_e32 v89, 31, v88
	v_lshlrev_b64 v[88:89], 13, v[88:89]
	v_lshl_add_u64 v[88:89], s[6:7], 0, v[88:89]
	v_cvt_pk_bf16_f32 v99, v90, v91
	global_store_dwordx4 v[112:113], v[96:99], off offset:256
	s_nop 1
	v_lshl_add_u64 v[96:97], v[88:89], 0, v[158:159]
	v_cvt_pk_bf16_f32 v88, v100, v101
	v_cvt_pk_bf16_f32 v89, v102, v103
	v_cvt_pk_bf16_f32 v90, v92, v93
	v_cvt_pk_bf16_f32 v91, v94, v95
	global_store_dwordx4 v[96:97], v[88:91], off
	v_cvt_pk_bf16_f32 v80, v80, v81
	v_cvt_pk_bf16_f32 v81, v82, v83
	v_cvt_pk_bf16_f32 v82, v72, v73
	v_or_b32_e32 v72, 48, v154
	v_ashrrev_i32_e32 v73, 31, v72
	v_lshlrev_b64 v[72:73], 13, v[72:73]
	v_lshl_add_u64 v[72:73], s[6:7], 0, v[72:73]
	v_cvt_pk_bf16_f32 v83, v74, v75
	global_store_dwordx4 v[96:97], v[80:83], off offset:256
	s_nop 1
	v_lshl_add_u64 v[80:81], v[72:73], 0, v[158:159]
	v_cvt_pk_bf16_f32 v72, v84, v85
	v_cvt_pk_bf16_f32 v73, v86, v87
	v_cvt_pk_bf16_f32 v74, v76, v77
	v_cvt_pk_bf16_f32 v75, v78, v79
	global_store_dwordx4 v[80:81], v[72:75], off
	v_cvt_pk_bf16_f32 v68, v68, v69
	v_cvt_pk_bf16_f32 v69, v70, v71
	v_cvt_pk_bf16_f32 v70, v64, v65
	v_cvt_pk_bf16_f32 v71, v66, v67
	global_store_dwordx4 v[80:81], v[68:71], off offset:256
	v_cvt_pk_bf16_f32 v60, v60, v61
	v_cvt_pk_bf16_f32 v61, v62, v63
	v_cvt_pk_bf16_f32 v62, v56, v57
	v_add_co_u32_e32 v56, vcc, s64, v144
	v_lshl_add_u64 v[64:65], v[144:145], 0, s[12:13]
	s_nop 0
	v_addc_co_u32_e32 v57, vcc, 0, v145, vcc
	v_cvt_pk_bf16_f32 v63, v58, v59
	global_store_dwordx4 v[56:57], v[60:63], off
	v_cvt_pk_bf16_f32 v48, v48, v49
	v_cvt_pk_bf16_f32 v49, v50, v51
	v_cvt_pk_bf16_f32 v50, v40, v41
	v_cvt_pk_bf16_f32 v51, v42, v43
	global_store_dwordx4 v[64:65], v[48:51], off offset:256
	v_cvt_pk_bf16_f32 v40, v52, v53
	v_cvt_pk_bf16_f32 v41, v54, v55
	v_cvt_pk_bf16_f32 v42, v44, v45
	v_add_co_u32_e32 v44, vcc, s65, v144
	s_nop 0
	v_lshl_add_u64 v[48:49], v[144:145], 0, s[14:15]
	v_addc_co_u32_e32 v45, vcc, 0, v145, vcc
	v_cvt_pk_bf16_f32 v43, v46, v47
	global_store_dwordx4 v[44:45], v[40:43], off
	v_cvt_pk_bf16_f32 v32, v32, v33
	v_cvt_pk_bf16_f32 v33, v34, v35
	v_cvt_pk_bf16_f32 v34, v24, v25
	v_cvt_pk_bf16_f32 v35, v26, v27
	global_store_dwordx4 v[48:49], v[32:35], off offset:256
	v_cvt_pk_bf16_f32 v24, v36, v37
	v_cvt_pk_bf16_f32 v25, v38, v39
	v_cvt_pk_bf16_f32 v26, v28, v29
	v_add_co_u32_e32 v28, vcc, s66, v144
	s_nop 0
	v_lshl_add_u64 v[32:33], v[144:145], 0, s[16:17]
	v_addc_co_u32_e32 v29, vcc, 0, v145, vcc
	v_cvt_pk_bf16_f32 v27, v30, v31
	global_store_dwordx4 v[28:29], v[24:27], off
	v_cvt_pk_bf16_f32 v16, v16, v17
	v_cvt_pk_bf16_f32 v17, v18, v19
	v_cvt_pk_bf16_f32 v18, v8, v9
	v_cvt_pk_bf16_f32 v19, v10, v11
	global_store_dwordx4 v[32:33], v[16:19], off offset:256
	v_cvt_pk_bf16_f32 v8, v20, v21
	v_cvt_pk_bf16_f32 v9, v22, v23
	v_cvt_pk_bf16_f32 v10, v12, v13
	v_add_co_u32_e32 v12, vcc, s67, v144
	s_nop 0
	v_lshl_add_u64 v[16:17], v[144:145], 0, s[18:19]
	v_addc_co_u32_e32 v13, vcc, 0, v145, vcc
	s_andn2_b64 vcc, exec, s[0:1]
	s_mov_b64 s[0:1], -1
	v_cvt_pk_bf16_f32 v11, v14, v15
	global_store_dwordx4 v[12:13], v[8:11], off
	v_cvt_pk_bf16_f32 v4, v4, v5
	v_cvt_pk_bf16_f32 v5, v6, v7
	v_cvt_pk_bf16_f32 v6, v0, v1
	v_cvt_pk_bf16_f32 v7, v2, v3
	global_store_dwordx4 v[16:17], v[4:7], off offset:256
	s_cbranch_vccnz .LBB0_112
	s_andn2_b64 vcc, exec, s[4:5]
	s_cbranch_vccnz .LBB0_111
	s_barrier
	s_branch .LBB0_111

.LBB0_346:
	s_add_u32 s74, s6, 0xd200000
	s_addc_u32 s34, s7, 0
	s_add_u32 s1, s6, 0xd400000
	v_writelane_b32 v255, s1, 8
	s_addc_u32 s1, s7, 0
	s_add_u32 s90, s6, 0x13400000
	v_mov_b64_e32 v[8:9], s[96:97]
	s_addc_u32 s91, s7, 0
	v_mad_u64_u32 v[8:9], s[6:7], v4, s43, v[8:9]
	v_mov_b32_e32 v4, v9
	v_mad_u64_u32 v[4:5], s[6:7], v5, s43, v[4:5]
	v_writelane_b32 v255, s1, 9
	v_mov_b32_e32 v9, v4
	s_ashr_i32 s1, s0, 31
	v_lshrrev_b32_e32 v7, 1, v2
	v_lshl_add_u64 v[4:5], s[0:1], 1, v[8:9]
	v_and_b32_e32 v160, 16, v7
	v_mov_b32_e32 v161, v1
	v_lshl_add_u64 v[4:5], v[4:5], 0, v[160:161]
	global_load_dwordx4 v[124:127], v[4:5], off
	global_load_dwordx4 v[120:123], v[4:5], off offset:32
	global_load_dwordx4 v[116:119], v[4:5], off offset:64
	global_load_dwordx4 v[112:115], v[4:5], off offset:96
	global_load_dwordx4 v[108:111], v[4:5], off offset:128
	global_load_dwordx4 v[104:107], v[4:5], off offset:160
	global_load_dwordx4 v[100:103], v[4:5], off offset:192
	global_load_dwordx4 v[96:99], v[4:5], off offset:224
	v_readlane_b32 s0, v253, 3
	v_lshrrev_b32_e32 v7, 5, v169
	v_cmp_gt_u32_e64 s[6:7], 32, v169
	v_or_b32_e32 v4, s0, v6
	v_readlane_b32 s0, v253, 5
	v_lshlrev_b32_e32 v9, 2, v7
	v_writelane_b32 v255, s6, 10
	v_lshl_add_u32 v162, v4, 4, s0
	v_and_b32_e32 v4, 7, v2
	v_readlane_b32 s0, v253, 4
	s_movk_i32 s1, 0x90
	v_lshrrev_b32_e32 v164, 3, v169
	v_mov_b32_e32 v5, s0
	v_lshlrev_b32_e32 v166, 3, v4
	v_lshlrev_b32_e32 v184, 4, v4
	v_writelane_b32 v255, s7, 11
	v_cmp_eq_u32_e64 s[88:89], 0, v4
	v_sub_u32_e32 v4, v9, v6
	v_mad_u32_u24 v175, v6, s1, v5
	v_add_u32_e32 v185, s0, v184
	v_mad_u32_u24 v189, v164, s1, v5
	v_readlane_b32 s0, v255, 6
	v_add_u32_e32 v193, 64, v4
	v_lshlrev_b32_e32 v4, 4, v7
	v_lshlrev_b32_e32 v3, 2, v3
	v_lshrrev_b32_e32 v2, 2, v2
	v_sub_u32_e64 v8, v158, 8 clamp
	v_readlane_b32 s1, v255, 7
	v_sub_u32_e32 v3, v4, v3
	v_mul_u32_u24_e32 v4, 0x7c, v0
	v_and_b32_e32 v2, 8, v2
	v_or_b32_e32 v172, 24, v164
	v_min_u32_e32 v8, 48, v8
	v_or_b32_e32 v10, s18, v9
	s_lshl_b32 s6, s0, 11
	v_readlane_b32 s0, v254, 28
	v_sub_u32_e32 v3, v3, v4
	v_readlane_b32 s1, v254, 30
	s_mov_b32 s57, 4
	v_or_b32_e32 v173, s31, v6
	v_mov_b32_e32 v159, v1
	v_mov_b32_e32 v163, v1
	v_or_b32_e32 v168, 8, v164
	v_or_b32_e32 v170, 16, v164
	v_mul_u32_u24_e32 v186, 0x90, v164
	v_or_b32_e32 v174, 64, v166
	v_sub_u32_e32 v187, v10, v8
	v_lshlrev_b32_e32 v188, 3, v7
	v_or_b32_e32 v176, 64, v164
	v_mov_b32_e32 v177, v1
	v_or_b32_e32 v178, 0x48, v164
	v_mov_b32_e32 v179, v1
	v_and_or_b32 v180, v172, 15, 64
	v_mov_b32_e32 v181, v1
	s_mov_b32 s64, 0
	v_add_u32_e32 v190, 0x480, v189
	v_add_u32_e32 v191, 0x900, v189
	v_add_u32_e32 v192, 0xd80, v189
	v_or_b32_e32 v194, s0, v0
	v_add_u32_e32 v195, s1, v3
	v_add_u32_e32 v196, s0, v0
	v_add_u32_e32 v197, v175, v2
	s_mov_b32 s7, 0
	s_mov_b32 s58, s66
	s_waitcnt vmcnt(0)
	s_branch .LBB0_349

.LBB0_356:
	v_and_b32_e32 v14, 31, v169
	v_lshrrev_b32_e32 v15, 5, v169
	v_lshlrev_b32_e32 v2, 2, v169
	v_and_b32_e32 v2, 12, v2
	v_bfe_u32 v3, v169, 2, 2
	v_or_b32_e32 v2, v2, v3
	v_xor_b32_e32 v250, v15, v2
	v_lshlrev_b32_e32 v250, 4, v250
	v_lshl_add_u32 v248, v14, 8, v250
	v_lshl_or_b32 v14, v15, 2, v3
	v_lshlrev_b32_e32 v2, 2, v3
	v_or_b32_e32 v2, v2, v15
	v_bfe_u32 v250, v169, 1, 1
	v_lshrrev_b32_e32 v251, 3, v169
	v_and_or_b32 v250, v251, 2, v250
	v_xor_b32_e32 v250, v250, v2
	v_lshlrev_b32_e32 v250, 4, v250
	v_lshl_add_u32 v250, v14, 8, v250
	v_lshlrev_b32_e32 v251, 3, v169
	v_and_b32_e32 v251, 8, v251
	v_add_u32_e32 v249, v250, v251
	v_add_u32_e32 v249, 0x2000, v249
	v_mov_b32_e32 v14, v1
	v_mov_b32_e32 v15, v1
	v_mov_b32_e32 v0, v1
	v_mov_b32_e32 v2, v1
	v_mov_b32_e32 v3, v1
	v_mov_b32_e32 v4, v1
	v_mov_b32_e32 v5, v1
	v_mov_b32_e32 v6, v1
	v_mov_b32_e32 v7, v1
	v_mov_b32_e32 v8, v1
	v_mov_b32_e32 v9, v1
	v_mov_b32_e32 v10, v1
	v_mov_b32_e32 v11, v1
	v_mov_b32_e32 v12, v1
	v_mov_b32_e32 v13, v1
	v_mov_b64_e32 v[64:65], v[14:15]
	v_mov_b64_e32 v[48:49], v[14:15]
	v_mov_b64_e32 v[32:33], v[14:15]
	s_waitcnt vmcnt(8) lgkmcnt(0)
	v_mov_b64_e32 v[82:83], v[124:125]
	v_mov_b64_e32 v[86:87], v[120:121]
	v_mov_b64_e32 v[90:91], v[116:117]
	v_mov_b64_e32 v[130:131], v[114:115]
	v_mov_b64_e32 v[134:135], v[110:111]
	v_mov_b64_e32 v[138:139], v[106:107]
	v_mov_b64_e32 v[142:143], v[102:103]
	v_mov_b64_e32 v[146:147], v[98:99]
	s_bitcmp1_b32 s56, 0
	v_mov_b64_e32 v[62:63], v[12:13]
	v_mov_b64_e32 v[60:61], v[10:11]
	v_mov_b64_e32 v[58:59], v[8:9]
	v_mov_b64_e32 v[56:57], v[6:7]
	v_mov_b64_e32 v[54:55], v[4:5]
	v_mov_b64_e32 v[52:53], v[2:3]
	v_mov_b64_e32 v[50:51], v[0:1]
	v_mov_b64_e32 v[46:47], v[12:13]
	v_mov_b64_e32 v[44:45], v[10:11]
	v_mov_b64_e32 v[42:43], v[8:9]
	v_mov_b64_e32 v[40:41], v[6:7]
	v_mov_b64_e32 v[38:39], v[4:5]
	v_mov_b64_e32 v[36:37], v[2:3]
	v_mov_b64_e32 v[34:35], v[0:1]
	v_mov_b64_e32 v[30:31], v[12:13]
	v_mov_b64_e32 v[28:29], v[10:11]
	v_mov_b64_e32 v[26:27], v[8:9]
	v_mov_b64_e32 v[24:25], v[6:7]
	v_mov_b64_e32 v[22:23], v[4:5]
	v_mov_b64_e32 v[20:21], v[2:3]
	v_mov_b64_e32 v[18:19], v[0:1]
	v_mov_b64_e32 v[16:17], v[14:15]
	v_mov_b64_e32 v[84:85], v[126:127]
	v_mov_b64_e32 v[88:89], v[122:123]
	v_mov_b64_e32 v[92:93], v[118:119]
	v_mov_b64_e32 v[128:129], v[112:113]
	v_mov_b64_e32 v[132:133], v[108:109]
	v_mov_b64_e32 v[136:137], v[104:105]
	v_mov_b64_e32 v[140:141], v[100:101]
	v_mov_b64_e32 v[144:145], v[96:97]
	s_cselect_b64 s[80:81], -1, 0
	s_mov_b32 s77, 0
	v_mov_b32_e32 v199, 0xc61c4000
	v_mov_b32_e32 v198, 0
	s_mov_b64 s[26:27], s[4:5]
	s_mov_b64 s[12:13], s[86:87]
	v_mov_b32_e32 v94, v182
	v_mov_b32_e32 v183, v171
	s_mov_b32 s98, s61
	s_mov_b32 s50, s68
	s_mov_b32 s67, s51
	s_mov_b32 s69, s52
	s_mov_b32 s65, s57
	s_mov_b32 s53, s70
	s_mov_b32 s71, s60
	s_mov_b32 s19, s54
	s_mov_b32 s63, s55
	s_mov_b32 s59, s64
	v_mov_b64_e32 v[14:15], v[12:13]
	v_mov_b64_e32 v[12:13], v[10:11]
	v_mov_b64_e32 v[10:11], v[8:9]
	v_mov_b64_e32 v[8:9], v[6:7]
	v_mov_b64_e32 v[6:7], v[4:5]
	v_mov_b64_e32 v[4:5], v[2:3]
	v_mov_b64_e32 v[2:3], v[0:1]
	s_cmp_gt_i32 s7, -1
	s_cbranch_scc0 .Lpf_skip_d
	s_add_i32 s16, s7, s82
	s_add_i32 s17, s16, -3
	s_cmp_gt_i32 s16, 2
	s_cselect_b32 s16, s17, s16
	s_cmp_eq_u32 s16, 0
	s_cbranch_scc1 .Lpf_na_d
	s_cmp_eq_u32 s16, 1
	s_cbranch_scc1 .Lpf_mem_d
	s_mul_hi_i32 s16, s62, 0x2aaaaaab
	s_lshr_b32 s17, s16, 31
	s_ashr_i32 s16, s16, 7
	s_add_i32 s16, s16, s17
	s_add_i32 s79, s16, 1
	s_mulk_i32 s16, 0x300
	s_sub_i32 s16, s62, s16
	s_mul_i32 s17, s16, 0x2aab
	s_lshr_b32 s28, s17, 31
	s_ashr_i32 s17, s17, 19
	s_add_i32 s17, s17, s28
	s_mul_i32 s28, s17, 48
	s_sub_i32 s16, s16, s28
	s_sext_i32_i16 s21, s16
	s_and_b32 s32, s21, 7
	s_sext_i32_i16 s16, s17
	s_cmp_lg_u32 s79, 2
	s_cbranch_scc0 .Lpf_d2_d
	s_add_i32 s17, s62, 0x2ff
	s_lshr_b32 s28, s32, 1
	s_and_b32 s29, s21, 1
	s_cmpk_lt_u32 s17, 0x5ff
	s_cselect_b32 s100, s28, 0
	s_cselect_b32 s101, s29, s32
	s_ashr_i32 s17, s16, 31
	s_lshl_b64 s[28:29], s[16:17], 11
	s_cmp_eq_u32 s79, 0
	v_lshl_add_u32 v68, s101, 8, v173
	v_ashrrev_i32_e32 v69, 31, v68
	s_cselect_b32 s17, 0, 2
	v_lshlrev_b64 v[68:69], s17, v[68:69]
	s_or_b32 s28, s28, s100
	v_lshl_add_u64 v[68:69], s[28:29], 0, v[68:69]
	s_branch .Lpf_d3_d

.LBB0_432:
	s_or_b64 exec, exec, s[0:1]
	s_ashr_i32 s10, s73, 3
	v_mov_b64_e32 v[34:35], s[24:25]
	s_lshl_b32 s14, s10, 7
	v_mad_u64_u32 v[36:37], s[0:1], s20, v164, v[34:35]
	s_mul_i32 s28, s72, 0x3000000
	s_ashr_i32 s15, s14, 31
	s_ashr_i32 s11, s10, 31
	v_readlane_b32 s0, v255, 8
	s_mul_hi_i32 s17, s72, 0x3000000
	s_add_u32 s80, s0, s28
	v_readlane_b32 s0, v255, 9
	s_addc_u32 s81, s0, s17
	v_mov_b64_e32 v[34:35], s[80:81]
	s_waitcnt lgkmcnt(0)
	v_add_u32_e32 v42, v189, v184
	v_mad_u64_u32 v[34:35], s[0:1], v36, s94, v[34:35]
	ds_read_b128 v[38:41], v42
	v_mov_b32_e32 v0, v35
	v_mad_u64_u32 v[44:45], s[0:1], v37, s94, v[0:1]
	v_mov_b32_e32 v35, v44
	v_lshl_add_u64 v[34:35], s[14:15], 1, v[34:35]
	v_lshlrev_b32_e32 v0, 1, v166
	s_mul_hi_i32 s16, s72, 0xc0000
	s_mul_i32 s72, s72, 0xc0000
	v_lshl_add_u64 v[34:35], v[34:35], 0, v[0:1]
	s_waitcnt lgkmcnt(0)
	global_store_dwordx4 v[34:35], v[38:41], off
	s_and_saveexec_b64 s[0:1], s[88:89]
	s_cbranch_execz .LBB0_434
	s_add_u32 s28, s74, s72
	s_addc_u32 s29, s34, s16
	ds_read_b32 v40, v189 offset:128
	v_mad_u64_u32 v[38:39], s[28:29], v36, 24, s[28:29]
	v_mov_b32_e32 v36, v39
	v_mad_u64_u32 v[36:37], s[28:29], v37, 24, v[36:37]
	v_mov_b32_e32 v39, v36
	v_lshl_add_u64 v[36:37], s[10:11], 2, v[38:39]
	s_waitcnt lgkmcnt(0)
	global_store_dword v[36:37], v40, off
.LBB0_434:
	s_or_b64 exec, exec, s[0:1]
	v_mov_b64_e32 v[36:37], s[24:25]
	v_mad_u64_u32 v[38:39], s[0:1], s20, v168, v[36:37]
	v_mov_b64_e32 v[36:37], s[80:81]
	v_add_u32_e32 v43, v190, v184
	v_mad_u64_u32 v[36:37], s[0:1], v38, s94, v[36:37]
	ds_read_b128 v[44:47], v43
	v_mov_b32_e32 v40, v37
	v_mad_u64_u32 v[40:41], s[0:1], v39, s94, v[40:41]
	v_mov_b32_e32 v37, v40
	v_lshl_add_u64 v[36:37], s[14:15], 1, v[36:37]
	v_lshl_add_u64 v[36:37], v[36:37], 0, v[0:1]
	s_waitcnt lgkmcnt(0)
	global_store_dwordx4 v[36:37], v[44:47], off
	s_and_saveexec_b64 s[0:1], s[88:89]
	s_cbranch_execz .LBB0_436
	s_add_u32 s28, s74, s72
	s_addc_u32 s29, s34, s16
	ds_read_b32 v44, v190 offset:128
	v_mad_u64_u32 v[40:41], s[28:29], v38, 24, s[28:29]
	v_mov_b32_e32 v38, v41
	v_mad_u64_u32 v[38:39], s[28:29], v39, 24, v[38:39]
	v_mov_b32_e32 v41, v38
	v_lshl_add_u64 v[38:39], s[10:11], 2, v[40:41]
	s_waitcnt lgkmcnt(0)
	global_store_dword v[38:39], v44, off
.LBB0_436:
	s_or_b64 exec, exec, s[0:1]
	v_mov_b64_e32 v[38:39], s[24:25]
	v_mad_u64_u32 v[40:41], s[0:1], s20, v170, v[38:39]
	v_mov_b64_e32 v[38:39], s[80:81]
	v_add_u32_e32 v44, v191, v184
	v_mad_u64_u32 v[38:39], s[0:1], v40, s94, v[38:39]
	ds_read_b128 v[46:49], v44
	v_mov_b32_e32 v52, v39
	v_mad_u64_u32 v[52:53], s[0:1], v41, s94, v[52:53]
	v_mov_b32_e32 v39, v52
	v_lshl_add_u64 v[38:39], s[14:15], 1, v[38:39]
	v_lshl_add_u64 v[38:39], v[38:39], 0, v[0:1]
	s_waitcnt lgkmcnt(0)
	global_store_dwordx4 v[38:39], v[46:49], off
	s_and_saveexec_b64 s[0:1], s[88:89]
	s_cbranch_execz .LBB0_438
	s_add_u32 s28, s74, s72
	s_addc_u32 s29, s34, s16
	ds_read_b32 v45, v191 offset:128
	v_mad_u64_u32 v[46:47], s[28:29], v40, 24, s[28:29]
	v_mov_b32_e32 v40, v47
	v_mad_u64_u32 v[40:41], s[28:29], v41, 24, v[40:41]
	v_mov_b32_e32 v47, v40
	v_lshl_add_u64 v[40:41], s[10:11], 2, v[46:47]
	s_waitcnt lgkmcnt(0)
	global_store_dword v[40:41], v45, off
.LBB0_438:
	s_or_b64 exec, exec, s[0:1]
	v_mov_b64_e32 v[40:41], s[24:25]
	v_mad_u64_u32 v[40:41], s[0:1], s20, v172, v[40:41]
	v_mov_b64_e32 v[46:47], s[80:81]
	v_add_u32_e32 v45, v192, v184
	v_mad_u64_u32 v[46:47], s[0:1], v40, s94, v[46:47]
	ds_read_b128 v[52:55], v45
	v_mov_b32_e32 v48, v47
	v_mad_u64_u32 v[48:49], s[0:1], v41, s94, v[48:49]
	v_mov_b32_e32 v47, v48
	v_lshl_add_u64 v[48:49], s[14:15], 1, v[46:47]
	v_lshl_add_u64 v[46:47], v[48:49], 0, v[0:1]
	s_waitcnt lgkmcnt(0)
	global_store_dwordx4 v[46:47], v[52:55], off
	s_and_saveexec_b64 s[0:1], s[88:89]
	s_cbranch_execz .LBB0_440
	s_add_u32 s14, s74, s72
	s_addc_u32 s15, s34, s16
	ds_read_b32 v51, v192 offset:128
	v_mad_u64_u32 v[46:47], s[14:15], v40, 24, s[14:15]
	v_mov_b32_e32 v0, v47
	v_mad_u64_u32 v[40:41], s[14:15], v41, 24, v[0:1]
	v_mov_b32_e32 v47, v40
	v_lshl_add_u64 v[40:41], s[10:11], 2, v[46:47]
	s_waitcnt lgkmcnt(0)
	global_store_dword v[40:41], v51, off
.LBB0_440:
	s_or_b64 exec, exec, s[0:1]
	v_mov_b32_e32 v67, v66
	v_pk_mul_f32 v[18:19], v[18:19], v[66:67]
	v_pk_mul_f32 v[20:21], v[20:21], v[66:67]
	v_pk_mul_f32 v[2:3], v[2:3], v[66:67]
	v_pk_mul_f32 v[4:5], v[4:5], v[66:67]
	v_cvt_pk_bf16_f32 v18, v18, v19
	v_cvt_pk_bf16_f32 v19, v20, v21
	v_pk_mul_f32 v[20:21], v[22:23], v[66:67]
	v_pk_mul_f32 v[22:23], v[24:25], v[66:67]
	v_cvt_pk_bf16_f32 v2, v2, v3
	v_cvt_pk_bf16_f32 v3, v4, v5
	v_pk_mul_f32 v[4:5], v[6:7], v[66:67]
	v_pk_mul_f32 v[6:7], v[8:9], v[66:67]
	v_cvt_pk_bf16_f32 v20, v20, v21
	v_cvt_pk_bf16_f32 v21, v22, v23
	v_cvt_pk_bf16_f32 v4, v4, v5
	v_cvt_pk_bf16_f32 v5, v6, v7
	ds_write2_b64 v50, v[18:19], v[20:21] offset1:2
	v_pk_mul_f32 v[18:19], v[26:27], v[66:67]
	v_pk_mul_f32 v[20:21], v[28:29], v[66:67]
	ds_write2_b64 v50, v[2:3], v[4:5] offset0:8 offset1:10
	v_pk_mul_f32 v[2:3], v[10:11], v[66:67]
	v_pk_mul_f32 v[4:5], v[12:13], v[66:67]
	v_cvt_pk_bf16_f32 v18, v18, v19
	v_cvt_pk_bf16_f32 v19, v20, v21
	v_pk_mul_f32 v[20:21], v[30:31], v[66:67]
	v_pk_mul_f32 v[22:23], v[32:33], v[66:67]
	v_cvt_pk_bf16_f32 v2, v2, v3
	v_cvt_pk_bf16_f32 v3, v4, v5
	v_pk_mul_f32 v[4:5], v[14:15], v[66:67]
	v_pk_mul_f32 v[6:7], v[16:17], v[66:67]
	v_cvt_pk_bf16_f32 v20, v20, v21
	v_cvt_pk_bf16_f32 v21, v22, v23
	v_cvt_pk_bf16_f32 v4, v4, v5
	v_cvt_pk_bf16_f32 v5, v6, v7
	ds_write2_b64 v50, v[18:19], v[20:21] offset0:4 offset1:6
	ds_write2_b64 v50, v[2:3], v[4:5] offset0:12 offset1:14
	s_waitcnt lgkmcnt(0)
	ds_read_b128 v[2:5], v42
	s_waitcnt lgkmcnt(0)
	global_store_dwordx4 v[34:35], v[2:5], off offset:128
	ds_read_b128 v[2:5], v43
	s_waitcnt lgkmcnt(0)
	global_store_dwordx4 v[36:37], v[2:5], off offset:128
	ds_read_b128 v[2:5], v44
	s_waitcnt lgkmcnt(0)
	global_store_dwordx4 v[38:39], v[2:5], off offset:128
	ds_read_b128 v[2:5], v45
	s_branch .Ltail_nc
.LBB0_441:
	v_and_b32_e32 v14, 31, v169
	v_lshrrev_b32_e32 v15, 5, v169
	v_lshlrev_b32_e32 v2, 2, v169
	v_and_b32_e32 v2, 12, v2
	v_bfe_u32 v3, v169, 2, 2
	v_or_b32_e32 v2, v2, v3
	v_xor_b32_e32 v250, v15, v2
	v_lshlrev_b32_e32 v250, 4, v250
	v_lshl_add_u32 v204, v14, 8, v250
	v_lshl_or_b32 v14, v15, 2, v3
	v_lshlrev_b32_e32 v2, 2, v3
	v_or_b32_e32 v2, v2, v15
	v_bfe_u32 v250, v169, 1, 1
	v_lshrrev_b32_e32 v251, 3, v169
	v_and_or_b32 v250, v251, 2, v250
	v_xor_b32_e32 v250, v250, v2
	v_lshlrev_b32_e32 v250, 4, v250
	v_lshl_add_u32 v250, v14, 8, v250
	v_lshlrev_b32_e32 v251, 3, v169
	v_and_b32_e32 v251, 8, v251
	v_add_u32_e32 v215, v250, v251
	v_add_u32_e32 v215, 0x2000, v215
	v_mov_b32_e32 v14, v1
	v_mov_b32_e32 v15, v1
	v_mov_b32_e32 v0, v1
	s_waitcnt lgkmcnt(0)
	v_mov_b32_e32 v2, v1
	v_mov_b32_e32 v3, v1
	v_mov_b32_e32 v4, v1
	v_mov_b32_e32 v5, v1
	v_mov_b32_e32 v6, v1
	v_mov_b32_e32 v7, v1
	v_mov_b32_e32 v8, v1
	v_mov_b32_e32 v9, v1
	v_mov_b32_e32 v10, v1
	v_mov_b32_e32 v11, v1
	v_mov_b32_e32 v12, v1
	v_mov_b32_e32 v13, v1
	v_mov_b64_e32 v[64:65], v[14:15]
	v_mov_b64_e32 v[48:49], v[14:15]
	v_mov_b64_e32 v[32:33], v[14:15]
	s_waitcnt vmcnt(8)
	v_mov_b64_e32 v[82:83], v[124:125]
	v_mov_b64_e32 v[86:87], v[120:121]
	v_mov_b64_e32 v[90:91], v[116:117]
	v_mov_b64_e32 v[130:131], v[114:115]
	v_mov_b64_e32 v[134:135], v[110:111]
	v_mov_b64_e32 v[138:139], v[106:107]
	v_mov_b64_e32 v[142:143], v[102:103]
	v_mov_b64_e32 v[146:147], v[98:99]
	s_bitcmp1_b32 s56, 0
	v_mov_b64_e32 v[62:63], v[12:13]
	v_mov_b64_e32 v[60:61], v[10:11]
	v_mov_b64_e32 v[58:59], v[8:9]
	v_mov_b64_e32 v[56:57], v[6:7]
	v_mov_b64_e32 v[54:55], v[4:5]
	v_mov_b64_e32 v[52:53], v[2:3]
	v_mov_b64_e32 v[50:51], v[0:1]
	v_mov_b64_e32 v[46:47], v[12:13]
	v_mov_b64_e32 v[44:45], v[10:11]
	v_mov_b64_e32 v[42:43], v[8:9]
	v_mov_b64_e32 v[40:41], v[6:7]
	v_mov_b64_e32 v[38:39], v[4:5]
	v_mov_b64_e32 v[36:37], v[2:3]
	v_mov_b64_e32 v[34:35], v[0:1]
	v_mov_b64_e32 v[30:31], v[12:13]
	v_mov_b64_e32 v[28:29], v[10:11]
	v_mov_b64_e32 v[26:27], v[8:9]
	v_mov_b64_e32 v[24:25], v[6:7]
	v_mov_b64_e32 v[22:23], v[4:5]
	v_mov_b64_e32 v[20:21], v[2:3]
	v_mov_b64_e32 v[18:19], v[0:1]
	v_mov_b64_e32 v[16:17], v[14:15]
	v_mov_b64_e32 v[84:85], v[126:127]
	v_mov_b64_e32 v[88:89], v[122:123]
	v_mov_b64_e32 v[92:93], v[118:119]
	v_mov_b64_e32 v[128:129], v[112:113]
	v_mov_b64_e32 v[132:133], v[108:109]
	v_mov_b64_e32 v[136:137], v[104:105]
	v_mov_b64_e32 v[140:141], v[100:101]
	v_mov_b64_e32 v[144:145], v[96:97]
	s_cselect_b64 s[10:11], -1, 0
	v_mov_b32_e32 v199, 0xc61c4000
	v_mov_b32_e32 v198, 0
	s_mov_b32 s24, 8
	s_mov_b64 s[26:27], s[4:5]
	s_mov_b64 s[12:13], s[86:87]
	v_mov_b32_e32 v94, v182
	v_mov_b32_e32 v183, v171
	s_mov_b32 s98, s61
	s_mov_b32 s50, s68
	s_mov_b32 s67, s51
	s_mov_b32 s69, s52
	s_mov_b32 s65, s57
	s_mov_b32 s53, s70
	s_mov_b32 s71, s60
	s_mov_b32 s19, s54
	s_mov_b32 s63, s55
	s_mov_b32 s59, s64
	v_mov_b64_e32 v[14:15], v[12:13]
	v_mov_b64_e32 v[12:13], v[10:11]
	v_mov_b64_e32 v[10:11], v[8:9]
	v_mov_b64_e32 v[8:9], v[6:7]
	v_mov_b64_e32 v[6:7], v[4:5]
	v_mov_b64_e32 v[4:5], v[2:3]
	v_mov_b64_e32 v[2:3], v[0:1]
	s_cmp_gt_i32 s7, -1
	s_cbranch_scc0 .Lpf_skip_m
	s_add_i32 s0, s7, s82
	s_add_i32 s1, s0, -3
	s_cmp_gt_i32 s0, 2
	s_cselect_b32 s0, s1, s0
	s_cmp_eq_u32 s0, 0
	s_cbranch_scc1 .Lpf_na_m
	s_cmp_eq_u32 s0, 1
	s_cbranch_scc1 .Lpf_mem_m
	s_mul_hi_i32 s0, s62, 0x2aaaaaab
	s_lshr_b32 s1, s0, 31
	s_ashr_i32 s0, s0, 7
	s_add_i32 s0, s0, s1
	s_add_i32 s16, s0, 1
	s_mulk_i32 s0, 0x300
	s_sub_i32 s0, s62, s0
	s_mul_i32 s1, s0, 0x2aab
	s_lshr_b32 s8, s1, 31
	s_ashr_i32 s1, s1, 19
	s_add_i32 s1, s1, s8
	s_mul_i32 s8, s1, 48
	s_sub_i32 s0, s0, s8
	s_sext_i32_i16 s14, s0
	s_and_b32 s15, s14, 7
	s_sext_i32_i16 s0, s1
	s_cmp_lg_u32 s16, 2
	s_cbranch_scc0 .Lpf_d2_m
	s_add_i32 s1, s62, 0x2ff
	s_lshr_b32 s8, s15, 1
	s_and_b32 s9, s14, 1
	s_cmpk_lt_u32 s1, 0x5ff
	s_cselect_b32 s28, s8, 0
	s_cselect_b32 s29, s9, s15
	s_ashr_i32 s1, s0, 31
	s_lshl_b64 s[8:9], s[0:1], 11
	s_cmp_eq_u32 s16, 0
	v_lshl_add_u32 v68, s29, 8, v173
	v_ashrrev_i32_e32 v69, 31, v68
	s_cselect_b32 s1, 0, 2
	v_lshlrev_b64 v[68:69], s1, v[68:69]
	s_or_b32 s8, s8, s28
	v_lshl_add_u64 v[68:69], s[8:9], 0, v[68:69]
	s_branch .Lpf_d3_m

.LBB0_496:
	s_waitcnt lgkmcnt(0)
	v_add_f32_e32 v0, v68, v69
	v_rcp_f32_e32 v66, v0
	s_ashr_i32 s0, s58, 5
	s_lshl_b32 s10, s58, 8
	s_ashr_i32 s1, s0, 31
	s_and_b32 s10, s10, 0x700
	s_lshl_b64 s[0:1], s[0:1], 11
	s_add_i32 s10, s10, s31
	v_pk_mul_f32 v[34:35], v[34:35], v[66:67] op_sel_hi:[1,0]
	v_pk_mul_f32 v[36:37], v[36:37], v[66:67] op_sel_hi:[1,0]
	s_add_u32 s16, s0, s10
	v_cvt_pk_bf16_f32 v34, v34, v35
	v_cvt_pk_bf16_f32 v35, v36, v37
	v_pk_mul_f32 v[36:37], v[38:39], v[66:67] op_sel_hi:[1,0]
	v_pk_mul_f32 v[38:39], v[40:41], v[66:67] op_sel_hi:[1,0]
	s_addc_u32 s0, s1, 0
	v_cvt_pk_bf16_f32 v36, v36, v37
	v_cvt_pk_bf16_f32 v37, v38, v39
	s_lshl_b32 s1, s58, 5
	v_pk_mul_f32 v[50:51], v[50:51], v[66:67] op_sel_hi:[1,0]
	v_pk_mul_f32 v[52:53], v[52:53], v[66:67] op_sel_hi:[1,0]
	ds_write2_b64 v197, v[34:35], v[36:37] offset0:8 offset1:10
	v_pk_mul_f32 v[34:35], v[42:43], v[66:67] op_sel_hi:[1,0]
	v_pk_mul_f32 v[36:37], v[44:45], v[66:67] op_sel_hi:[1,0]
	s_and_b32 s10, s1, 0x300
	v_cvt_pk_bf16_f32 v50, v50, v51
	v_cvt_pk_bf16_f32 v51, v52, v53
	v_pk_mul_f32 v[52:53], v[54:55], v[66:67] op_sel_hi:[1,0]
	v_pk_mul_f32 v[54:55], v[56:57], v[66:67] op_sel_hi:[1,0]
	v_cvt_pk_bf16_f32 v34, v34, v35
	v_cvt_pk_bf16_f32 v35, v36, v37
	v_pk_mul_f32 v[36:37], v[46:47], v[66:67] op_sel_hi:[1,0]
	v_pk_mul_f32 v[38:39], v[48:49], v[66:67] op_sel_hi:[1,0]
	s_add_u32 s14, s96, s10
	v_cvt_pk_bf16_f32 v52, v52, v53
	v_cvt_pk_bf16_f32 v53, v54, v55
	v_cvt_pk_bf16_f32 v36, v36, v37
	v_cvt_pk_bf16_f32 v37, v38, v39
	s_addc_u32 s15, s97, 0
	ds_write2_b64 v197, v[50:51], v[52:53] offset1:2
	v_pk_mul_f32 v[50:51], v[58:59], v[66:67] op_sel_hi:[1,0]
	v_pk_mul_f32 v[52:53], v[60:61], v[66:67] op_sel_hi:[1,0]
	v_pk_mul_f32 v[54:55], v[64:65], v[66:67] op_sel_hi:[1,0]
	ds_write2_b64 v197, v[34:35], v[36:37] offset0:12 offset1:14
	v_or_b32_e32 v64, s16, v164
	v_mov_b64_e32 v[34:35], s[14:15]
	v_cvt_pk_bf16_f32 v50, v50, v51
	v_cvt_pk_bf16_f32 v51, v52, v53
	v_pk_mul_f32 v[52:53], v[62:63], v[66:67] op_sel_hi:[1,0]
	v_mad_u64_u32 v[36:37], s[14:15], v64, s43, v[34:35]
	v_cvt_pk_bf16_f32 v52, v52, v53
	v_cvt_pk_bf16_f32 v53, v54, v55
	v_mad_i32_i24 v37, s0, v211, v37
	s_mov_b64 s[24:25], 0x3400
	ds_write2_b64 v197, v[50:51], v[52:53] offset0:4 offset1:6
	v_lshl_add_u64 v[42:43], v[36:37], 0, s[24:25]
	v_lshlrev_b32_e32 v0, 1, v166
	s_waitcnt lgkmcnt(0)
	v_lshl_add_u64 v[36:37], v[42:43], 0, v[0:1]
	global_load_dwordx4 v[50:53], v[36:37], off
	v_or_b32_e32 v72, s16, v168
	v_mad_u64_u32 v[36:37], s[14:15], v72, s43, v[34:35]
	v_mad_i32_i24 v37, s0, v211, v37
	v_lshl_add_u64 v[48:49], v[36:37], 0, s[24:25]
	v_lshl_add_u64 v[36:37], v[48:49], 0, v[0:1]
	global_load_dwordx4 v[68:71], v[36:37], off
	v_or_b32_e32 v56, s16, v170
	v_or_b32_e32 v54, s16, v172
	v_mad_u64_u32 v[38:39], s[14:15], v56, s43, v[34:35]
	v_mad_u64_u32 v[34:35], s[14:15], v54, s43, v[34:35]
	v_mad_i32_i24 v39, s0, v211, v39
	v_mad_i32_i24 v35, s0, v211, v35
	v_lshl_add_u64 v[44:45], v[38:39], 0, s[24:25]
	v_lshl_add_u64 v[46:47], v[34:35], 0, s[24:25]
	v_add_u32_e32 v58, v185, v186
	v_lshl_add_u64 v[34:35], v[44:45], 0, v[0:1]
	v_lshl_add_u64 v[36:37], v[46:47], 0, v[0:1]
	ds_read_b128 v[60:63], v58
	global_load_dwordx4 v[38:41], v[34:35], off
	s_nop 0
	global_load_dwordx4 v[34:37], v[36:37], off
	v_lshlrev_b32_e32 v232, 1, v174
	v_mov_b32_e32 v233, 0
	v_lshl_add_u64 v[234:235], v[42:43], 0, v[232:233]
	global_load_dwordx4 v[216:219], v[234:235], off
	v_lshl_add_u64 v[234:235], v[48:49], 0, v[232:233]
	global_load_dwordx4 v[220:223], v[234:235], off
	v_lshl_add_u64 v[234:235], v[44:45], 0, v[232:233]
	global_load_dwordx4 v[224:227], v[234:235], off
	v_lshl_add_u64 v[234:235], v[46:47], 0, v[232:233]
	global_load_dwordx4 v[228:231], v[234:235], off
	v_mov_b32_e32 v65, s0
	s_mov_b32 s11, s99
	v_mov_b32_e32 v73, s0
	s_waitcnt lgkmcnt(0)
	v_lshlrev_b32_e32 v74, 16, v60
	v_and_b32_e32 v75, 0xffff0000, v60
	v_lshlrev_b32_e32 v60, 16, v61
	v_and_b32_e32 v61, 0xffff0000, v61
	v_pk_mul_f32 v[18:19], v[18:19], v[66:67] op_sel_hi:[1,0]
	v_pk_mul_f32 v[20:21], v[20:21], v[66:67] op_sel_hi:[1,0]
	v_pk_mul_f32 v[2:3], v[2:3], v[66:67] op_sel_hi:[1,0]
	v_pk_mul_f32 v[4:5], v[4:5], v[66:67] op_sel_hi:[1,0]
	v_cvt_pk_bf16_f32 v18, v18, v19
	v_cvt_pk_bf16_f32 v19, v20, v21
	v_pk_mul_f32 v[20:21], v[22:23], v[66:67] op_sel_hi:[1,0]
	v_pk_mul_f32 v[22:23], v[24:25], v[66:67] op_sel_hi:[1,0]
	v_cvt_pk_bf16_f32 v2, v2, v3
	v_cvt_pk_bf16_f32 v3, v4, v5
	v_pk_mul_f32 v[4:5], v[6:7], v[66:67] op_sel_hi:[1,0]
	v_pk_mul_f32 v[6:7], v[8:9], v[66:67] op_sel_hi:[1,0]
	v_cvt_pk_bf16_f32 v20, v20, v21
	v_cvt_pk_bf16_f32 v21, v22, v23
	v_cvt_pk_bf16_f32 v4, v4, v5
	v_cvt_pk_bf16_f32 v5, v6, v7
	v_pk_mul_f32 v[22:23], v[32:33], v[66:67] op_sel_hi:[1,0]
	v_pk_mul_f32 v[6:7], v[16:17], v[66:67] op_sel_hi:[1,0]
	s_waitcnt vmcnt(0)
	v_lshlrev_b32_e32 v76, 16, v50
	v_and_b32_e32 v77, 0xffff0000, v50
	v_mul_f32_e32 v55, 0xbfb8aa3b, v76
	v_mul_f32_e32 v57, 0xbfb8aa3b, v77
	v_exp_f32_e32 v55, v55
	v_exp_f32_e32 v57, v57
	v_lshlrev_b32_e32 v50, 16, v51
	v_and_b32_e32 v51, 0xffff0000, v51
	v_add_f32_e32 v55, 1.0, v55
	v_add_f32_e32 v57, 1.0, v57
	v_rcp_f32_e32 v78, v55
	v_rcp_f32_e32 v79, v57
	v_mul_f32_e32 v55, 0xbfb8aa3b, v51
	v_mul_f32_e32 v59, 0xbfb8aa3b, v50
	v_exp_f32_e32 v55, v55
	v_exp_f32_e32 v59, v59
	v_pk_mul_f32 v[76:77], v[78:79], v[76:77]
	v_add_f32_e32 v55, 1.0, v55
	v_pk_mul_f32 v[74:75], v[76:77], v[74:75]
	v_lshlrev_b32_e32 v76, 16, v52
	v_and_b32_e32 v77, 0xffff0000, v52
	v_mul_f32_e32 v52, 0xbfb8aa3b, v76
	v_add_f32_e32 v57, 1.0, v59
	v_rcp_f32_e32 v79, v55
	v_exp_f32_e32 v52, v52
	v_mul_f32_e32 v55, 0xbfb8aa3b, v77
	v_rcp_f32_e32 v78, v57
	v_exp_f32_e32 v55, v55
	v_add_f32_e32 v52, 1.0, v52
	v_pk_mul_f32 v[50:51], v[78:79], v[50:51]
	v_rcp_f32_e32 v78, v52
	v_add_f32_e32 v52, 1.0, v55
	v_rcp_f32_e32 v79, v52
	v_lshlrev_b32_e32 v52, 16, v53
	v_and_b32_e32 v53, 0xffff0000, v53
	v_mul_f32_e32 v55, 0xbfb8aa3b, v52
	v_exp_f32_e32 v55, v55
	v_mul_f32_e32 v57, 0xbfb8aa3b, v53
	v_exp_f32_e32 v57, v57
	v_pk_mul_f32 v[76:77], v[78:79], v[76:77]
	v_add_f32_e32 v55, 1.0, v55
	v_rcp_f32_e32 v78, v55
	v_add_f32_e32 v55, 1.0, v57
	v_rcp_f32_e32 v79, v55
	v_pk_mul_f32 v[50:51], v[50:51], v[60:61]
	v_lshlrev_b32_e32 v60, 16, v62
	v_and_b32_e32 v61, 0xffff0000, v62
	v_pk_mul_f32 v[76:77], v[76:77], v[60:61]
	v_lshlrev_b32_e32 v60, 16, v63
	v_and_b32_e32 v61, 0xffff0000, v63
	v_pk_mul_f32 v[52:53], v[78:79], v[52:53]
	v_cvt_pk_bf16_f32 v62, v76, v77
	v_pk_mul_f32 v[52:53], v[52:53], v[60:61]
	v_cvt_pk_bf16_f32 v61, v50, v51
	v_lshlrev_b64 v[50:51], 12, v[64:65]
	v_lshlrev_b32_e32 v64, 16, v68
	v_cvt_pk_bf16_f32 v63, v52, v53
	v_and_b32_e32 v65, 0xffff0000, v68
	v_mul_f32_e32 v53, 0xbfb8aa3b, v64
	v_exp_f32_e32 v55, v53
	v_mul_f32_e32 v53, 0xbfb8aa3b, v65
	v_exp_f32_e32 v57, v53
	v_cvt_pk_bf16_f32 v60, v74, v75
	v_add_f32_e32 v55, 1.0, v55
	v_rcp_f32_e32 v74, v55
	v_add_f32_e32 v55, 1.0, v57
	v_lshlrev_b32_e32 v68, 16, v69
	v_rcp_f32_e32 v75, v55
	v_and_b32_e32 v69, 0xffff0000, v69
	v_mul_f32_e32 v55, 0xbfb8aa3b, v68
	v_lshl_add_u64 v[50:51], s[90:91], 0, v[50:51]
	v_exp_f32_e32 v55, v55
	v_mul_f32_e32 v57, 0xbfb8aa3b, v69
	v_lshl_add_u64 v[50:51], v[50:51], 0, s[10:11]
	v_exp_f32_e32 v57, v57
	v_lshl_add_u64 v[50:51], v[50:51], 0, v[0:1]
	global_store_dwordx4 v[50:51], v[60:63], off offset:3072
	ds_read_b128 v[60:63], v58 offset:1152
	v_add_f32_e32 v55, 1.0, v55
	v_pk_mul_f32 v[64:65], v[74:75], v[64:65]
	v_rcp_f32_e32 v74, v55
	v_add_f32_e32 v55, 1.0, v57
	v_rcp_f32_e32 v75, v55
	s_waitcnt lgkmcnt(0)
	v_lshlrev_b32_e32 v52, 16, v60
	v_and_b32_e32 v53, 0xffff0000, v60
	v_pk_mul_f32 v[52:53], v[64:65], v[52:53]
	v_pk_mul_f32 v[64:65], v[74:75], v[68:69]
	v_lshlrev_b32_e32 v68, 16, v70
	v_and_b32_e32 v69, 0xffff0000, v70
	v_mul_f32_e32 v55, 0xbfb8aa3b, v68
	v_exp_f32_e32 v55, v55
	v_mul_f32_e32 v57, 0xbfb8aa3b, v69
	v_exp_f32_e32 v57, v57
	v_lshlrev_b32_e32 v70, 16, v71
	v_add_f32_e32 v55, 1.0, v55
	v_rcp_f32_e32 v74, v55
	v_add_f32_e32 v55, 1.0, v57
	v_rcp_f32_e32 v75, v55
	v_and_b32_e32 v71, 0xffff0000, v71
	v_mul_f32_e32 v55, 0xbfb8aa3b, v70
	v_exp_f32_e32 v55, v55
	v_mul_f32_e32 v57, 0xbfb8aa3b, v71
	v_exp_f32_e32 v57, v57
	v_pk_mul_f32 v[68:69], v[74:75], v[68:69]
	v_add_f32_e32 v55, 1.0, v55
	v_rcp_f32_e32 v74, v55
	v_add_f32_e32 v55, 1.0, v57
	v_rcp_f32_e32 v75, v55
	v_lshlrev_b32_e32 v60, 16, v61
	v_and_b32_e32 v61, 0xffff0000, v61
	v_pk_mul_f32 v[64:65], v[64:65], v[60:61]
	v_lshlrev_b32_e32 v60, 16, v62
	v_and_b32_e32 v61, 0xffff0000, v62
	v_pk_mul_f32 v[68:69], v[68:69], v[60:61]
	v_lshlrev_b32_e32 v60, 16, v63
	v_and_b32_e32 v61, 0xffff0000, v63
	v_pk_mul_f32 v[62:63], v[74:75], v[70:71]
	v_mov_b32_e32 v57, s0
	v_pk_mul_f32 v[70:71], v[62:63], v[60:61]
	v_cvt_pk_bf16_f32 v62, v68, v69
	v_lshlrev_b32_e32 v68, 16, v38
	v_and_b32_e32 v69, 0xffff0000, v38
	v_mul_f32_e32 v38, 0xbfb8aa3b, v68
	v_exp_f32_e32 v38, v38
	v_mul_f32_e32 v55, 0xbfb8aa3b, v69
	v_cvt_pk_bf16_f32 v60, v52, v53
	v_lshlrev_b64 v[52:53], 12, v[72:73]
	v_exp_f32_e32 v55, v55
	v_lshl_add_u64 v[52:53], s[90:91], 0, v[52:53]
	v_lshl_add_u64 v[52:53], v[52:53], 0, s[10:11]
	v_cvt_pk_bf16_f32 v61, v64, v65
	v_cvt_pk_bf16_f32 v63, v70, v71
	v_lshl_add_u64 v[52:53], v[52:53], 0, v[0:1]
	v_add_f32_e32 v38, 1.0, v38
	global_store_dwordx4 v[52:53], v[60:63], off offset:3072
	v_rcp_f32_e32 v70, v38
	v_add_f32_e32 v38, 1.0, v55
	ds_read_b128 v[60:63], v58 offset:2304
	v_rcp_f32_e32 v71, v38
	v_lshlrev_b32_e32 v38, 16, v39
	v_and_b32_e32 v39, 0xffff0000, v39
	v_mul_f32_e32 v55, 0xbfb8aa3b, v38
	v_exp_f32_e32 v55, v55
	v_mul_f32_e32 v59, 0xbfb8aa3b, v39
	v_exp_f32_e32 v59, v59
	s_waitcnt lgkmcnt(0)
	v_lshlrev_b32_e32 v64, 16, v60
	v_and_b32_e32 v65, 0xffff0000, v60
	v_pk_mul_f32 v[68:69], v[70:71], v[68:69]
	v_add_f32_e32 v55, 1.0, v55
	v_pk_mul_f32 v[64:65], v[68:69], v[64:65]
	v_lshlrev_b32_e32 v68, 16, v40
	v_rcp_f32_e32 v70, v55
	v_add_f32_e32 v55, 1.0, v59
	v_and_b32_e32 v69, 0xffff0000, v40
	v_mul_f32_e32 v40, 0xbfb8aa3b, v68
	v_rcp_f32_e32 v71, v55
	v_exp_f32_e32 v40, v40
	v_mul_f32_e32 v55, 0xbfb8aa3b, v69
	v_exp_f32_e32 v55, v55
	v_pk_mul_f32 v[38:39], v[70:71], v[38:39]
	v_add_f32_e32 v40, 1.0, v40
	v_rcp_f32_e32 v70, v40
	v_add_f32_e32 v40, 1.0, v55
	v_rcp_f32_e32 v71, v40
	v_lshlrev_b32_e32 v40, 16, v41
	v_and_b32_e32 v41, 0xffff0000, v41
	v_mul_f32_e32 v55, 0xbfb8aa3b, v40
	v_exp_f32_e32 v55, v55
	v_mul_f32_e32 v59, 0xbfb8aa3b, v41
	v_exp_f32_e32 v59, v59
	v_pk_mul_f32 v[68:69], v[70:71], v[68:69]
	v_add_f32_e32 v55, 1.0, v55
	v_rcp_f32_e32 v70, v55
	v_add_f32_e32 v55, 1.0, v59
	v_rcp_f32_e32 v71, v55
	v_lshlrev_b32_e32 v60, 16, v61
	v_and_b32_e32 v61, 0xffff0000, v61
	v_pk_mul_f32 v[38:39], v[38:39], v[60:61]
	v_lshlrev_b32_e32 v60, 16, v62
	v_and_b32_e32 v61, 0xffff0000, v62
	v_pk_mul_f32 v[68:69], v[68:69], v[60:61]
	v_lshlrev_b32_e32 v60, 16, v63
	v_and_b32_e32 v61, 0xffff0000, v63
	v_pk_mul_f32 v[40:41], v[70:71], v[40:41]
	v_cvt_pk_bf16_f32 v62, v68, v69
	v_pk_mul_f32 v[40:41], v[40:41], v[60:61]
	v_cvt_pk_bf16_f32 v61, v38, v39
	v_lshlrev_b64 v[38:39], 12, v[56:57]
	v_lshlrev_b32_e32 v56, 16, v34
	v_lshl_add_u64 v[38:39], s[90:91], 0, v[38:39]
	v_and_b32_e32 v57, 0xffff0000, v34
	v_mul_f32_e32 v34, 0xbfb8aa3b, v56
	v_cvt_pk_bf16_f32 v63, v40, v41
	v_lshl_add_u64 v[38:39], v[38:39], 0, s[10:11]
	v_exp_f32_e32 v34, v34
	v_mul_f32_e32 v41, 0xbfb8aa3b, v57
	v_cvt_pk_bf16_f32 v60, v64, v65
	v_lshl_add_u64 v[38:39], v[38:39], 0, v[0:1]
	v_exp_f32_e32 v59, v41
	global_store_dwordx4 v[38:39], v[60:63], off offset:3072
	ds_read_b128 v[60:63], v58 offset:3456
	v_add_f32_e32 v34, 1.0, v34
	v_rcp_f32_e32 v64, v34
	v_add_f32_e32 v34, 1.0, v59
	v_rcp_f32_e32 v65, v34
	v_lshlrev_b32_e32 v34, 16, v35
	v_and_b32_e32 v35, 0xffff0000, v35
	v_mul_f32_e32 v59, 0xbfb8aa3b, v34
	s_waitcnt lgkmcnt(0)
	v_lshlrev_b32_e32 v40, 16, v60
	v_and_b32_e32 v41, 0xffff0000, v60
	v_exp_f32_e32 v59, v59
	v_mul_f32_e32 v60, 0xbfb8aa3b, v35
	v_exp_f32_e32 v60, v60
	v_pk_mul_f32 v[56:57], v[64:65], v[56:57]
	v_add_f32_e32 v59, 1.0, v59
	v_rcp_f32_e32 v64, v59
	v_add_f32_e32 v59, 1.0, v60
	v_rcp_f32_e32 v65, v59
	v_lshlrev_b32_e32 v60, 16, v36
	v_pk_mul_f32 v[40:41], v[56:57], v[40:41]
	v_lshlrev_b32_e32 v56, 16, v61
	v_and_b32_e32 v57, 0xffff0000, v61
	v_pk_mul_f32 v[34:35], v[64:65], v[34:35]
	v_and_b32_e32 v61, 0xffff0000, v36
	v_mul_f32_e32 v36, 0xbfb8aa3b, v60
	v_pk_mul_f32 v[34:35], v[34:35], v[56:57]
	v_exp_f32_e32 v36, v36
	v_mul_f32_e32 v57, 0xbfb8aa3b, v61
	v_exp_f32_e32 v59, v57
	v_lshlrev_b32_e32 v56, 16, v62
	v_add_f32_e32 v36, 1.0, v36
	v_rcp_f32_e32 v64, v36
	v_add_f32_e32 v36, 1.0, v59
	v_rcp_f32_e32 v65, v36
	v_lshlrev_b32_e32 v36, 16, v37
	v_and_b32_e32 v37, 0xffff0000, v37
	v_mul_f32_e32 v59, 0xbfb8aa3b, v36
	v_and_b32_e32 v57, 0xffff0000, v62
	v_exp_f32_e32 v59, v59
	v_mul_f32_e32 v62, 0xbfb8aa3b, v37
	v_exp_f32_e32 v62, v62
	v_pk_mul_f32 v[60:61], v[64:65], v[60:61]
	v_add_f32_e32 v59, 1.0, v59
	v_rcp_f32_e32 v64, v59
	v_add_f32_e32 v59, 1.0, v62
	v_rcp_f32_e32 v65, v59
	v_mov_b32_e32 v55, s0
	v_pk_mul_f32 v[56:57], v[60:61], v[56:57]
	v_lshlrev_b32_e32 v60, 16, v63
	v_and_b32_e32 v61, 0xffff0000, v63
	v_pk_mul_f32 v[36:37], v[64:65], v[36:37]
	v_cvt_pk_bf16_f32 v62, v56, v57
	v_pk_mul_f32 v[36:37], v[36:37], v[60:61]
	v_cvt_pk_bf16_f32 v61, v34, v35
	v_lshlrev_b64 v[34:35], 12, v[54:55]
	v_lshl_add_u64 v[34:35], s[90:91], 0, v[34:35]
	v_lshl_add_u64 v[34:35], v[34:35], 0, s[10:11]
	v_cvt_pk_bf16_f32 v60, v40, v41
	v_cvt_pk_bf16_f32 v63, v36, v37
	v_lshl_add_u64 v[36:37], v[34:35], 0, v[0:1]
	global_store_dwordx4 v[36:37], v[60:63], off offset:3072
	ds_write2_b64 v197, v[18:19], v[20:21] offset1:2
	v_pk_mul_f32 v[18:19], v[26:27], v[66:67] op_sel_hi:[1,0]
	v_pk_mul_f32 v[20:21], v[28:29], v[66:67] op_sel_hi:[1,0]
	ds_write2_b64 v197, v[2:3], v[4:5] offset0:8 offset1:10
	v_pk_mul_f32 v[2:3], v[10:11], v[66:67] op_sel_hi:[1,0]
	v_pk_mul_f32 v[4:5], v[12:13], v[66:67] op_sel_hi:[1,0]
	v_cvt_pk_bf16_f32 v18, v18, v19
	v_cvt_pk_bf16_f32 v19, v20, v21
	v_pk_mul_f32 v[20:21], v[30:31], v[66:67] op_sel_hi:[1,0]
	v_cvt_pk_bf16_f32 v2, v2, v3
	v_cvt_pk_bf16_f32 v3, v4, v5
	v_pk_mul_f32 v[4:5], v[14:15], v[66:67] op_sel_hi:[1,0]
	v_cvt_pk_bf16_f32 v20, v20, v21
	v_cvt_pk_bf16_f32 v21, v22, v23
	v_cvt_pk_bf16_f32 v4, v4, v5
	v_cvt_pk_bf16_f32 v5, v6, v7
	ds_write2_b64 v197, v[18:19], v[20:21] offset0:4 offset1:6
	ds_write2_b64 v197, v[2:3], v[4:5] offset0:12 offset1:14
	v_lshlrev_b32_e32 v0, 1, v174
	s_waitcnt lgkmcnt(0)
	v_lshl_add_u64 v[2:3], v[42:43], 0, v[0:1]
	v_mov_b32_e32 v10, v216
	v_mov_b32_e32 v11, v217
	v_mov_b32_e32 v12, v218
	v_mov_b32_e32 v13, v219
	v_lshl_add_u64 v[2:3], v[48:49], 0, v[0:1]
	v_mov_b32_e32 v14, v220
	v_mov_b32_e32 v15, v221
	v_mov_b32_e32 v16, v222
	v_mov_b32_e32 v17, v223
	v_lshl_add_u64 v[2:3], v[44:45], 0, v[0:1]
	v_lshl_add_u64 v[4:5], v[46:47], 0, v[0:1]
	ds_read_b128 v[18:21], v58
	v_mov_b32_e32 v6, v224
	v_mov_b32_e32 v7, v225
	v_mov_b32_e32 v8, v226
	v_mov_b32_e32 v9, v227
	s_nop 0
	v_mov_b32_e32 v2, v228
	v_mov_b32_e32 v3, v229
	v_mov_b32_e32 v4, v230
	v_mov_b32_e32 v5, v231
	s_mov_b64 s[0:1], 0xc00
	v_lshl_add_u64 v[48:49], v[34:35], 0, s[0:1]
	s_waitcnt lgkmcnt(0)
	v_lshlrev_b32_e32 v22, 16, v18
	v_and_b32_e32 v23, 0xffff0000, v18
	s_waitcnt vmcnt(4)
	v_lshlrev_b32_e32 v24, 16, v10
	v_and_b32_e32 v25, 0xffff0000, v10
	v_mul_f32_e32 v0, 0xbfb8aa3b, v24
	v_exp_f32_e32 v0, v0
	v_mul_f32_e32 v10, 0xbfb8aa3b, v25
	v_exp_f32_e32 v10, v10
	v_add_f32_e32 v0, 1.0, v0
	v_rcp_f32_e32 v26, v0
	v_add_f32_e32 v0, 1.0, v10
	v_lshlrev_b32_e32 v10, 16, v11
	v_rcp_f32_e32 v27, v0
	v_and_b32_e32 v11, 0xffff0000, v11
	v_mul_f32_e32 v0, 0xbfb8aa3b, v10
	v_exp_f32_e32 v0, v0
	v_mul_f32_e32 v18, 0xbfb8aa3b, v11
	v_exp_f32_e32 v18, v18
	v_pk_mul_f32 v[24:25], v[26:27], v[24:25]
	v_add_f32_e32 v0, 1.0, v0
	v_rcp_f32_e32 v26, v0
	v_add_f32_e32 v0, 1.0, v18
	v_rcp_f32_e32 v27, v0
	v_pk_mul_f32 v[22:23], v[24:25], v[22:23]
	v_lshlrev_b32_e32 v24, 16, v12
	v_lshlrev_b32_e32 v18, 16, v19
	v_and_b32_e32 v19, 0xffff0000, v19
	v_pk_mul_f32 v[10:11], v[26:27], v[10:11]
	v_and_b32_e32 v25, 0xffff0000, v12
	v_mul_f32_e32 v0, 0xbfb8aa3b, v24
	v_pk_mul_f32 v[18:19], v[10:11], v[18:19]
	v_exp_f32_e32 v0, v0
	v_mul_f32_e32 v11, 0xbfb8aa3b, v25
	v_exp_f32_e32 v12, v11
	v_lshlrev_b32_e32 v10, 16, v20
	v_add_f32_e32 v0, 1.0, v0
	v_rcp_f32_e32 v26, v0
	v_add_f32_e32 v0, 1.0, v12
	v_lshlrev_b32_e32 v12, 16, v13
	v_rcp_f32_e32 v27, v0
	v_and_b32_e32 v13, 0xffff0000, v13
	v_mul_f32_e32 v0, 0xbfb8aa3b, v12
	v_and_b32_e32 v11, 0xffff0000, v20
	v_exp_f32_e32 v0, v0
	v_mul_f32_e32 v20, 0xbfb8aa3b, v13
	v_exp_f32_e32 v20, v20
	v_pk_mul_f32 v[24:25], v[26:27], v[24:25]
	v_add_f32_e32 v0, 1.0, v0
	v_rcp_f32_e32 v26, v0
	v_add_f32_e32 v0, 1.0, v20
	v_rcp_f32_e32 v27, v0
	v_pk_mul_f32 v[24:25], v[24:25], v[10:11]
	v_lshlrev_b32_e32 v10, 16, v21
	v_and_b32_e32 v11, 0xffff0000, v21
	v_pk_mul_f32 v[12:13], v[26:27], v[12:13]
	s_nop 0
	v_pk_mul_f32 v[20:21], v[12:13], v[10:11]
	v_cvt_pk_bf16_f32 v10, v22, v23
	v_cvt_pk_bf16_f32 v13, v20, v21
	v_lshlrev_b32_e32 v20, 16, v14
	v_and_b32_e32 v21, 0xffff0000, v14
	v_mul_f32_e32 v0, 0xbfb8aa3b, v20
	v_cvt_pk_bf16_f32 v11, v18, v19
	v_cvt_pk_bf16_f32 v12, v24, v25
	v_exp_f32_e32 v0, v0
	v_mul_f32_e32 v14, 0xbfb8aa3b, v21
	global_store_dwordx4 v[50:51], v[10:13], off offset:3200
	v_exp_f32_e32 v14, v14
	ds_read_b128 v[10:13], v58 offset:1152
	v_add_f32_e32 v0, 1.0, v0
	v_rcp_f32_e32 v22, v0
	v_add_f32_e32 v0, 1.0, v14
	v_lshlrev_b32_e32 v14, 16, v15
	v_rcp_f32_e32 v23, v0
	v_and_b32_e32 v15, 0xffff0000, v15
	v_mul_f32_e32 v0, 0xbfb8aa3b, v14
	s_waitcnt lgkmcnt(0)
	v_lshlrev_b32_e32 v18, 16, v10
	v_and_b32_e32 v19, 0xffff0000, v10
	v_exp_f32_e32 v0, v0
	v_mul_f32_e32 v10, 0xbfb8aa3b, v15
	v_exp_f32_e32 v10, v10
	v_pk_mul_f32 v[20:21], v[22:23], v[20:21]
	v_add_f32_e32 v0, 1.0, v0
	v_rcp_f32_e32 v22, v0
	v_add_f32_e32 v0, 1.0, v10
	v_rcp_f32_e32 v23, v0
	v_pk_mul_f32 v[18:19], v[20:21], v[18:19]
	v_lshlrev_b32_e32 v20, 16, v16
	v_lshlrev_b32_e32 v10, 16, v11
	v_and_b32_e32 v11, 0xffff0000, v11
	v_pk_mul_f32 v[14:15], v[22:23], v[14:15]
	v_and_b32_e32 v21, 0xffff0000, v16
	v_mul_f32_e32 v0, 0xbfb8aa3b, v20
	v_pk_mul_f32 v[14:15], v[14:15], v[10:11]
	v_exp_f32_e32 v0, v0
	v_mul_f32_e32 v11, 0xbfb8aa3b, v21
	v_exp_f32_e32 v16, v11
	v_lshlrev_b32_e32 v10, 16, v12
	v_add_f32_e32 v0, 1.0, v0
	v_rcp_f32_e32 v22, v0
	v_add_f32_e32 v0, 1.0, v16
	v_lshlrev_b32_e32 v16, 16, v17
	v_rcp_f32_e32 v23, v0
	v_and_b32_e32 v17, 0xffff0000, v17
	v_mul_f32_e32 v0, 0xbfb8aa3b, v16
	v_and_b32_e32 v11, 0xffff0000, v12
	v_exp_f32_e32 v0, v0
	v_mul_f32_e32 v12, 0xbfb8aa3b, v17
	v_exp_f32_e32 v12, v12
	v_pk_mul_f32 v[20:21], v[22:23], v[20:21]
	v_add_f32_e32 v0, 1.0, v0
	v_rcp_f32_e32 v22, v0
	v_add_f32_e32 v0, 1.0, v12
	v_rcp_f32_e32 v23, v0
	v_pk_mul_f32 v[20:21], v[20:21], v[10:11]
	v_lshlrev_b32_e32 v10, 16, v13
	v_and_b32_e32 v11, 0xffff0000, v13
	v_pk_mul_f32 v[12:13], v[22:23], v[16:17]
	s_nop 0
	v_pk_mul_f32 v[16:17], v[12:13], v[10:11]
	v_cvt_pk_bf16_f32 v10, v18, v19
	v_cvt_pk_bf16_f32 v13, v16, v17
	v_lshlrev_b32_e32 v16, 16, v6
	v_and_b32_e32 v17, 0xffff0000, v6
	v_mul_f32_e32 v0, 0xbfb8aa3b, v16
	v_cvt_pk_bf16_f32 v11, v14, v15
	v_cvt_pk_bf16_f32 v12, v20, v21
	v_exp_f32_e32 v0, v0
	v_mul_f32_e32 v6, 0xbfb8aa3b, v17
	global_store_dwordx4 v[52:53], v[10:13], off offset:3200
	v_exp_f32_e32 v6, v6
	ds_read_b128 v[10:13], v58 offset:2304
	v_add_f32_e32 v0, 1.0, v0
	v_rcp_f32_e32 v18, v0
	v_add_f32_e32 v0, 1.0, v6
	v_lshlrev_b32_e32 v6, 16, v7
	v_rcp_f32_e32 v19, v0
	v_and_b32_e32 v7, 0xffff0000, v7
	v_mul_f32_e32 v0, 0xbfb8aa3b, v6
	s_waitcnt lgkmcnt(0)
	v_lshlrev_b32_e32 v14, 16, v10
	v_and_b32_e32 v15, 0xffff0000, v10
	v_exp_f32_e32 v0, v0
	v_mul_f32_e32 v10, 0xbfb8aa3b, v7
	v_exp_f32_e32 v10, v10
	v_pk_mul_f32 v[16:17], v[18:19], v[16:17]
	v_add_f32_e32 v0, 1.0, v0
	v_rcp_f32_e32 v18, v0
	v_add_f32_e32 v0, 1.0, v10
	v_rcp_f32_e32 v19, v0
	v_pk_mul_f32 v[14:15], v[16:17], v[14:15]
	v_lshlrev_b32_e32 v16, 16, v8
	v_lshlrev_b32_e32 v10, 16, v11
	v_and_b32_e32 v11, 0xffff0000, v11
	v_pk_mul_f32 v[6:7], v[18:19], v[6:7]
	v_and_b32_e32 v17, 0xffff0000, v8
	v_mul_f32_e32 v0, 0xbfb8aa3b, v16
	v_pk_mul_f32 v[10:11], v[6:7], v[10:11]
	v_exp_f32_e32 v0, v0
	v_mul_f32_e32 v7, 0xbfb8aa3b, v17
	v_exp_f32_e32 v8, v7
	v_lshlrev_b32_e32 v6, 16, v12
	v_add_f32_e32 v0, 1.0, v0
	v_rcp_f32_e32 v18, v0
	v_add_f32_e32 v0, 1.0, v8
	v_lshlrev_b32_e32 v8, 16, v9
	v_rcp_f32_e32 v19, v0
	v_and_b32_e32 v9, 0xffff0000, v9
	v_mul_f32_e32 v0, 0xbfb8aa3b, v8
	v_and_b32_e32 v7, 0xffff0000, v12
	v_exp_f32_e32 v0, v0
	v_mul_f32_e32 v12, 0xbfb8aa3b, v9
	v_exp_f32_e32 v12, v12
	v_pk_mul_f32 v[16:17], v[18:19], v[16:17]
	v_add_f32_e32 v0, 1.0, v0
	v_rcp_f32_e32 v18, v0
	v_add_f32_e32 v0, 1.0, v12
	v_rcp_f32_e32 v19, v0
	v_pk_mul_f32 v[16:17], v[16:17], v[6:7]
	v_lshlrev_b32_e32 v6, 16, v13
	v_and_b32_e32 v7, 0xffff0000, v13
	v_pk_mul_f32 v[8:9], v[18:19], v[8:9]
	s_nop 0
	v_pk_mul_f32 v[12:13], v[8:9], v[6:7]
	v_cvt_pk_bf16_f32 v6, v14, v15
	v_cvt_pk_bf16_f32 v9, v12, v13
	v_lshlrev_b32_e32 v12, 16, v2
	v_and_b32_e32 v13, 0xffff0000, v2
	v_mul_f32_e32 v0, 0xbfb8aa3b, v12
	v_cvt_pk_bf16_f32 v7, v10, v11
	v_cvt_pk_bf16_f32 v8, v16, v17
	v_exp_f32_e32 v0, v0
	v_mul_f32_e32 v2, 0xbfb8aa3b, v13
	global_store_dwordx4 v[38:39], v[6:9], off offset:3200
	v_exp_f32_e32 v2, v2
	ds_read_b128 v[6:9], v58 offset:3456
	v_add_f32_e32 v0, 1.0, v0
	v_rcp_f32_e32 v14, v0
	v_add_f32_e32 v0, 1.0, v2
	v_lshlrev_b32_e32 v2, 16, v3
	v_rcp_f32_e32 v15, v0
	v_and_b32_e32 v3, 0xffff0000, v3
	v_mul_f32_e32 v0, 0xbfb8aa3b, v2
	s_waitcnt lgkmcnt(0)
	v_lshlrev_b32_e32 v10, 16, v6
	v_and_b32_e32 v11, 0xffff0000, v6
	v_exp_f32_e32 v0, v0
	v_mul_f32_e32 v6, 0xbfb8aa3b, v3
	v_exp_f32_e32 v6, v6
	v_pk_mul_f32 v[12:13], v[14:15], v[12:13]
	v_add_f32_e32 v0, 1.0, v0
	v_rcp_f32_e32 v14, v0
	v_add_f32_e32 v0, 1.0, v6
	v_rcp_f32_e32 v15, v0
	v_pk_mul_f32 v[10:11], v[12:13], v[10:11]
	v_lshlrev_b32_e32 v12, 16, v4
	v_lshlrev_b32_e32 v6, 16, v7
	v_and_b32_e32 v7, 0xffff0000, v7
	v_pk_mul_f32 v[2:3], v[14:15], v[2:3]
	v_and_b32_e32 v13, 0xffff0000, v4
	v_mul_f32_e32 v0, 0xbfb8aa3b, v12
	v_pk_mul_f32 v[6:7], v[2:3], v[6:7]
	v_exp_f32_e32 v0, v0
	v_mul_f32_e32 v3, 0xbfb8aa3b, v13
	v_exp_f32_e32 v4, v3
	v_lshlrev_b32_e32 v2, 16, v8
	v_add_f32_e32 v0, 1.0, v0
	v_rcp_f32_e32 v14, v0
	v_add_f32_e32 v0, 1.0, v4
	v_lshlrev_b32_e32 v4, 16, v5
	v_rcp_f32_e32 v15, v0
	v_and_b32_e32 v5, 0xffff0000, v5
	v_mul_f32_e32 v0, 0xbfb8aa3b, v4
	v_and_b32_e32 v3, 0xffff0000, v8
	v_exp_f32_e32 v0, v0
	v_mul_f32_e32 v8, 0xbfb8aa3b, v5
	v_exp_f32_e32 v8, v8
	v_pk_mul_f32 v[12:13], v[14:15], v[12:13]
	v_add_f32_e32 v0, 1.0, v0
	v_rcp_f32_e32 v14, v0
	v_add_f32_e32 v0, 1.0, v8
	v_rcp_f32_e32 v15, v0
	v_pk_mul_f32 v[12:13], v[12:13], v[2:3]
	v_lshlrev_b32_e32 v2, 16, v9
	v_and_b32_e32 v3, 0xffff0000, v9
	v_pk_mul_f32 v[4:5], v[14:15], v[4:5]
	s_nop 0
	v_pk_mul_f32 v[8:9], v[4:5], v[2:3]
	v_cvt_pk_bf16_f32 v2, v10, v11
	v_cvt_pk_bf16_f32 v3, v6, v7
	v_cvt_pk_bf16_f32 v4, v12, v13
	v_cvt_pk_bf16_f32 v5, v8, v9
	s_cbranch_execnz .Ltail_nc
.LBB0_497:
	s_mul_hi_i32 s0, s58, 0x2aaaaaab
	s_lshr_b32 s1, s0, 31
	s_ashr_i32 s0, s0, 3
	s_add_i32 s20, s0, s1
	s_mul_i32 s0, s20, 48
	s_sub_i32 s10, s58, s0
	s_lshl_b32 s1, s10, 2
	s_and_b32 s0, s1, 28
	v_sub_u32_e64 v0, s0, 1 clamp
	s_max_u32 s19, s0, 4
	v_readfirstlane_b32 s11, v0
	s_min_u32 s21, s11, 24
	v_readlane_b32 s11, v254, 28
	s_or_b32 s16, s0, s11
	s_ashr_i32 s17, s10, 3
	s_sub_i32 s10, s21, s19
	s_cmp_lt_i32 s10, -11
	s_waitcnt vmcnt(8) lgkmcnt(0)
	s_cbranch_scc1 .LBB0_607
	v_sub_u32_e64 v0, s16, 4 clamp
	v_min_u32_e32 v130, 24, v0
	v_add_u32_e32 v0, s0, v196
	v_sub_u32_e64 v2, s16, 3 clamp
	s_mul_i32 s10, s17, 0x744
	s_mul_i32 s11, s19, 0x7c
	s_bfe_u32 s1, s1, 0x30002
	v_sub_u32_e64 v0, v0, 4 clamp
	v_min_u32_e32 v2, 24, v2
	s_add_i32 s10, s10, s11
	s_mulk_i32 s1, 0x1f0
	v_min_u32_e32 v0, 24, v0
	v_mov_b32_e32 v14, v1
	v_mov_b32_e32 v15, v1
	v_add_u32_e32 v129, 8, v2
	s_sub_i32 s1, s10, s1
	v_sub_u32_e32 v132, -4, v0
	v_mov_b32_e32 v0, v1
	v_mov_b32_e32 v2, v1
	v_mov_b32_e32 v3, v1
	v_mov_b32_e32 v4, v1
	v_mov_b32_e32 v5, v1
	v_mov_b32_e32 v6, v1
	v_mov_b32_e32 v7, v1
	v_mov_b32_e32 v8, v1
	v_mov_b32_e32 v9, v1
	v_mov_b32_e32 v10, v1
	v_mov_b32_e32 v11, v1
	v_mov_b32_e32 v12, v1
	v_mov_b32_e32 v13, v1
	v_mov_b64_e32 v[78:79], v[14:15]
	v_mov_b64_e32 v[62:63], v[14:15]
	v_mov_b64_e32 v[46:47], v[14:15]
	v_mov_b64_e32 v[30:31], v[14:15]
	s_add_i32 s21, s21, 12
	v_add_u32_e32 v131, s1, v195
	v_mov_b32_e32 v133, 0xc61c4000
	v_mov_b32_e32 v128, 0
	s_mov_b32 s98, s61
	v_mov_b64_e32 v[76:77], v[12:13]
	v_mov_b64_e32 v[74:75], v[10:11]
	v_mov_b64_e32 v[72:73], v[8:9]
	v_mov_b64_e32 v[70:71], v[6:7]
	v_mov_b64_e32 v[68:69], v[4:5]
	v_mov_b64_e32 v[66:67], v[2:3]
	v_mov_b64_e32 v[64:65], v[0:1]
	v_mov_b64_e32 v[60:61], v[12:13]
	v_mov_b64_e32 v[58:59], v[10:11]
	v_mov_b64_e32 v[56:57], v[8:9]
	v_mov_b64_e32 v[54:55], v[6:7]
	v_mov_b64_e32 v[52:53], v[4:5]
	v_mov_b64_e32 v[50:51], v[2:3]
	v_mov_b64_e32 v[48:49], v[0:1]
	v_mov_b64_e32 v[44:45], v[12:13]
	v_mov_b64_e32 v[42:43], v[10:11]
	v_mov_b64_e32 v[40:41], v[8:9]
	v_mov_b64_e32 v[38:39], v[6:7]
	v_mov_b64_e32 v[36:37], v[4:5]
	v_mov_b64_e32 v[34:35], v[2:3]
	v_mov_b64_e32 v[32:33], v[0:1]
	v_mov_b64_e32 v[28:29], v[12:13]
	v_mov_b64_e32 v[26:27], v[10:11]
	v_mov_b64_e32 v[24:25], v[8:9]
	v_mov_b64_e32 v[22:23], v[6:7]
	v_mov_b64_e32 v[20:21], v[4:5]
	v_mov_b64_e32 v[18:19], v[2:3]
	v_mov_b64_e32 v[16:17], v[0:1]
	v_and_b32_e32 v232, 31, v169
	v_add_u32_e32 v232, s18, v232
	v_lshrrev_b32_e32 v233, 5, v169
	v_lshlrev_b32_e32 v234, 2, v232
	v_and_b32_e32 v234, 12, v234
	v_bfe_u32 v235, v232, 2, 2
	v_or_b32_e32 v234, v234, v235
	v_xor_b32_e32 v234, v233, v234
	v_lshlrev_b32_e32 v234, 4, v234
	v_lshl_add_u32 v248, v232, 8, v234
	v_lshl_add_u32 v232, v233, 2, s18
	v_lshrrev_b32_e32 v234, 2, v169
	v_and_or_b32 v232, v234, 3, v232
	v_bfe_u32 v234, v169, 1, 1
	v_lshrrev_b32_e32 v235, 3, v169
	v_and_or_b32 v234, v235, 2, v234
	v_lshlrev_b32_e32 v235, 3, v169
	v_and_b32_e32 v235, 8, v235
	v_lshlrev_b32_e32 v236, 2, v232
	v_and_b32_e32 v236, 12, v236
	v_bfe_u32 v251, v232, 2, 2
	v_or_b32_e32 v236, v236, v251
	v_xor_b32_e32 v236, v234, v236
	v_lshlrev_b32_e32 v236, 4, v236
	v_lshl_add_u32 v236, v232, 8, v236
	v_add_u32_e32 v249, v236, v235
	v_add_u32_e32 v232, 8, v232
	v_lshlrev_b32_e32 v236, 2, v232
	v_and_b32_e32 v236, 12, v236
	v_bfe_u32 v251, v232, 2, 2
	v_or_b32_e32 v236, v236, v251
	v_xor_b32_e32 v236, v234, v236
	v_lshlrev_b32_e32 v236, 4, v236
	v_lshl_add_u32 v236, v232, 8, v236
	v_add_u32_e32 v250, v236, v235

.LBB0_622:
	v_mov_b64_e32 v[6:7], s[96:97]
	v_mad_u64_u32 v[6:7], s[10:11], v2, s43, v[6:7]
	v_mov_b32_e32 v0, v7
	v_mad_u64_u32 v[2:3], s[10:11], v3, s43, v[0:1]
	v_mov_b32_e32 v7, v2
	s_ashr_i32 s1, s0, 31
	v_lshl_add_u64 v[2:3], s[0:1], 1, v[6:7]
	v_lshl_add_u64 v[2:3], v[2:3], 0, v[160:161]
	global_load_dwordx4 v[124:127], v[2:3], off
	global_load_dwordx4 v[120:123], v[2:3], off offset:32
	global_load_dwordx4 v[116:119], v[2:3], off offset:64
	global_load_dwordx4 v[112:115], v[2:3], off offset:96
	global_load_dwordx4 v[108:111], v[2:3], off offset:128
	global_load_dwordx4 v[104:107], v[2:3], off offset:160
	global_load_dwordx4 v[100:103], v[2:3], off offset:192
	global_load_dwordx4 v[96:99], v[2:3], off offset:224
.LBB0_623:
	s_waitcnt lgkmcnt(0)
	v_add_f32_e32 v0, v128, v4
	v_rcp_f32_e32 v14, v0
	v_add_u32_e32 v80, v175, v188
	s_ashr_i32 s21, s20, 31
	s_lshl_b32 s0, s17, 7
	v_pk_mul_f32 v[2:3], v[64:65], v[14:15] op_sel_hi:[1,0]
	v_pk_mul_f32 v[4:5], v[66:67], v[14:15] op_sel_hi:[1,0]
	v_cvt_pk_bf16_f32 v2, v2, v3
	v_cvt_pk_bf16_f32 v3, v4, v5
	v_pk_mul_f32 v[4:5], v[68:69], v[14:15] op_sel_hi:[1,0]
	v_pk_mul_f32 v[6:7], v[70:71], v[14:15] op_sel_hi:[1,0]
	v_cvt_pk_bf16_f32 v4, v4, v5
	v_cvt_pk_bf16_f32 v5, v6, v7
	ds_write2_b64 v80, v[2:3], v[4:5] offset1:2
	v_pk_mul_f32 v[2:3], v[72:73], v[14:15] op_sel_hi:[1,0]
	v_pk_mul_f32 v[4:5], v[74:75], v[14:15] op_sel_hi:[1,0]
	s_lshl_b64 s[10:11], s[20:21], 11
	v_readlane_b32 s1, v254, 3
	v_cvt_pk_bf16_f32 v2, v2, v3
	v_cvt_pk_bf16_f32 v3, v4, v5
	v_pk_mul_f32 v[4:5], v[76:77], v[14:15] op_sel_hi:[1,0]
	v_pk_mul_f32 v[6:7], v[78:79], v[14:15] op_sel_hi:[1,0]
	s_add_u32 s1, s10, s1
	v_cvt_pk_bf16_f32 v4, v4, v5
	v_cvt_pk_bf16_f32 v5, v6, v7
	s_addc_u32 s11, s11, 0
	s_lshl_b32 s10, s16, 6
	ds_write2_b64 v80, v[2:3], v[4:5] offset0:4 offset1:6
	v_pk_mul_f32 v[2:3], v[48:49], v[14:15] op_sel_hi:[1,0]
	v_pk_mul_f32 v[4:5], v[50:51], v[14:15] op_sel_hi:[1,0]
	s_add_u32 s10, s1, s10
	v_cvt_pk_bf16_f32 v2, v2, v3
	v_cvt_pk_bf16_f32 v3, v4, v5
	v_pk_mul_f32 v[4:5], v[52:53], v[14:15] op_sel_hi:[1,0]
	v_pk_mul_f32 v[6:7], v[54:55], v[14:15] op_sel_hi:[1,0]
	s_addc_u32 s11, s11, 0
	s_ashr_i32 s1, s0, 31
	v_cvt_pk_bf16_f32 v4, v4, v5
	v_cvt_pk_bf16_f32 v5, v6, v7
	ds_write2_b64 v80, v[2:3], v[4:5] offset0:8 offset1:10
	v_pk_mul_f32 v[2:3], v[56:57], v[14:15] op_sel_hi:[1,0]
	v_pk_mul_f32 v[4:5], v[58:59], v[14:15] op_sel_hi:[1,0]
	s_lshl_b64 s[12:13], s[0:1], 1
	v_cvt_pk_bf16_f32 v2, v2, v3
	v_cvt_pk_bf16_f32 v3, v4, v5
	v_pk_mul_f32 v[4:5], v[60:61], v[14:15] op_sel_hi:[1,0]
	v_pk_mul_f32 v[6:7], v[62:63], v[14:15] op_sel_hi:[1,0]
	s_add_u32 s0, s96, s12
	v_cvt_pk_bf16_f32 v4, v4, v5
	v_cvt_pk_bf16_f32 v5, v6, v7
	s_addc_u32 s1, s97, s13
	ds_write2_b64 v80, v[2:3], v[4:5] offset0:12 offset1:14
	v_or_b32_e32 v68, s10, v164
	v_mov_b64_e32 v[2:3], s[0:1]
	v_mad_u64_u32 v[4:5], s[0:1], v68, s43, v[2:3]
	v_mad_i32_i24 v5, s11, v211, v5
	s_mov_b64 s[14:15], 0x1200
	v_lshl_add_u64 v[56:57], v[4:5], 0, s[14:15]
	v_lshlrev_b32_e32 v0, 1, v166
	s_waitcnt lgkmcnt(0)
	v_lshl_add_u64 v[4:5], v[56:57], 0, v[0:1]
	global_load_dwordx4 v[48:51], v[4:5], off
	v_or_b32_e32 v66, s10, v168
	v_mad_u64_u32 v[4:5], s[0:1], v66, s43, v[2:3]
	v_mad_i32_i24 v5, s11, v211, v5
	v_lshl_add_u64 v[58:59], v[4:5], 0, s[14:15]
	v_lshl_add_u64 v[4:5], v[58:59], 0, v[0:1]
	global_load_dwordx4 v[10:13], v[4:5], off
	v_add_u32_e32 v15, v185, v186
	ds_read_b128 v[52:55], v15
	v_lshl_add_u64 v[64:65], s[10:11], 0, v[176:177]
	v_mad_u64_u32 v[4:5], s[0:1], v64, s43, v[2:3]
	v_mad_i32_i24 v5, v65, s43, v5
	s_waitcnt lgkmcnt(0)
	v_lshlrev_b32_e32 v70, 16, v52
	v_and_b32_e32 v71, 0xffff0000, v52
	v_lshl_add_u64 v[60:61], v[4:5], 0, s[14:15]
	v_lshl_add_u64 v[4:5], v[60:61], 0, v[0:1]
	global_load_dwordx4 v[6:9], v[4:5], off
	v_lshlrev_b32_e32 v52, 16, v53
	v_and_b32_e32 v53, 0xffff0000, v53
	v_mov_b32_e32 v69, s11
	v_lshl_add_u64 v[4:5], s[10:11], 0, v[178:179]
	v_mad_u64_u32 v[2:3], s[0:1], v4, s43, v[2:3]
	v_mad_i32_i24 v3, v5, s43, v3
	v_lshl_add_u64 v[62:63], v[2:3], 0, s[14:15]
	v_lshl_add_u64 v[2:3], v[62:63], 0, v[0:1]
	global_load_dwordx4 v[2:5], v[2:3], off
	v_lshlrev_b32_e32 v232, 1, v174
	v_mov_b32_e32 v233, 0
	v_lshl_add_u64 v[234:235], v[56:57], 0, v[232:233]
	global_load_dwordx4 v[216:219], v[234:235], off
	v_lshl_add_u64 v[234:235], v[58:59], 0, v[232:233]
	global_load_dwordx4 v[220:223], v[234:235], off
	v_lshl_add_u64 v[234:235], v[60:61], 0, v[232:233]
	global_load_dwordx4 v[224:227], v[234:235], off
	v_lshl_add_u64 v[234:235], v[62:63], 0, v[232:233]
	global_load_dwordx4 v[228:231], v[234:235], off
	v_mov_b32_e32 v67, s11
	s_waitcnt vmcnt(0)
	v_mov_b32_e32 v147, v99
	v_mov_b32_e32 v146, v98
	v_mov_b32_e32 v145, v97
	v_mov_b32_e32 v144, v96
	v_mov_b32_e32 v143, v103
	v_mov_b32_e32 v142, v102
	v_mov_b32_e32 v141, v101
	v_mov_b32_e32 v140, v100
	v_mov_b32_e32 v139, v107
	v_mov_b32_e32 v138, v106
	v_mov_b32_e32 v137, v105
	v_mov_b32_e32 v136, v104
	v_mov_b32_e32 v135, v111
	v_mov_b32_e32 v134, v110
	v_mov_b32_e32 v133, v109
	v_mov_b32_e32 v132, v108
	v_mov_b32_e32 v131, v115
	v_mov_b32_e32 v130, v114
	v_mov_b32_e32 v129, v113
	v_mov_b32_e32 v128, v112
	v_mov_b32_e32 v93, v119
	v_mov_b32_e32 v92, v118
	v_mov_b32_e32 v91, v117
	v_mov_b32_e32 v90, v116
	v_mov_b32_e32 v89, v123
	v_mov_b32_e32 v88, v122
	v_mov_b32_e32 v87, v121
	v_mov_b32_e32 v86, v120
	v_mov_b32_e32 v85, v127
	v_mov_b32_e32 v84, v126
	v_mov_b32_e32 v83, v125
	v_mov_b32_e32 v82, v124
	s_mov_b32 s59, s64
	s_mov_b32 s63, s55
	s_mov_b32 s19, s54
	s_mov_b32 s71, s60
	s_mov_b32 s53, s70
	s_mov_b32 s65, s57
	s_mov_b32 s69, s52
	s_mov_b32 s67, s51
	s_mov_b32 s50, s68
	s_mov_b32 s98, s61
	v_mov_b32_e32 v183, v171
	s_mov_b32 s21, s56
	v_mov_b32_e32 v94, v182
	s_mov_b64 s[26:27], s[4:5]
	v_lshlrev_b32_e32 v72, 16, v48
	v_and_b32_e32 v73, 0xffff0000, v48
	v_mul_f32_e32 v48, 0xbfb8aa3b, v72
	v_exp_f32_e32 v48, v48
	s_nop 0
	v_add_f32_e32 v48, 1.0, v48
	v_rcp_f32_e32 v74, v48
	v_mul_f32_e32 v48, 0xbfb8aa3b, v73
	v_exp_f32_e32 v48, v48
	s_nop 0
	v_add_f32_e32 v48, 1.0, v48
	v_rcp_f32_e32 v75, v48
	v_lshlrev_b32_e32 v48, 16, v49
	v_and_b32_e32 v49, 0xffff0000, v49
	v_pk_mul_f32 v[72:73], v[74:75], v[72:73]
	s_nop 0
	v_pk_mul_f32 v[70:71], v[72:73], v[70:71]
	v_mul_f32_e32 v72, 0xbfb8aa3b, v48
	v_mul_f32_e32 v73, 0xbfb8aa3b, v49
	v_exp_f32_e32 v72, v72
	v_exp_f32_e32 v73, v73
	v_add_f32_e32 v72, 1.0, v72
	v_add_f32_e32 v73, 1.0, v73
	v_rcp_f32_e32 v72, v72
	v_rcp_f32_e32 v73, v73
	s_nop 0
	v_pk_mul_f32 v[48:49], v[72:73], v[48:49]
	v_lshlrev_b32_e32 v72, 16, v50
	v_and_b32_e32 v73, 0xffff0000, v50
	v_mul_f32_e32 v50, 0xbfb8aa3b, v72
	v_exp_f32_e32 v50, v50
	v_pk_mul_f32 v[48:49], v[48:49], v[52:53]
	v_lshlrev_b32_e32 v52, 16, v54
	v_and_b32_e32 v53, 0xffff0000, v54
	v_add_f32_e32 v50, 1.0, v50
	v_rcp_f32_e32 v74, v50
	v_mul_f32_e32 v50, 0xbfb8aa3b, v73
	v_exp_f32_e32 v50, v50
	s_nop 0
	v_add_f32_e32 v50, 1.0, v50
	v_rcp_f32_e32 v75, v50
	v_lshlrev_b32_e32 v50, 16, v51
	v_and_b32_e32 v51, 0xffff0000, v51
	v_mul_f32_e32 v54, 0xbfb8aa3b, v50
	v_pk_mul_f32 v[72:73], v[74:75], v[72:73]
	v_exp_f32_e32 v54, v54
	v_pk_mul_f32 v[72:73], v[72:73], v[52:53]
	v_lshlrev_b32_e32 v52, 16, v55
	v_and_b32_e32 v53, 0xffff0000, v55
	v_mul_f32_e32 v55, 0xbfb8aa3b, v51
	v_exp_f32_e32 v55, v55
	v_add_f32_e32 v54, 1.0, v54
	v_rcp_f32_e32 v54, v54
	v_add_f32_e32 v55, 1.0, v55
	v_rcp_f32_e32 v55, v55
	s_nop 0
	v_pk_mul_f32 v[50:51], v[54:55], v[50:51]
	s_nop 0
	v_pk_mul_f32 v[50:51], v[50:51], v[52:53]
	v_cvt_pk_bf16_f32 v53, v48, v49
	v_lshlrev_b64 v[48:49], 12, v[68:69]
	v_lshlrev_b32_e32 v68, 16, v10
	v_and_b32_e32 v69, 0xffff0000, v10
	v_mul_f32_e32 v10, 0xbfb8aa3b, v68
	v_exp_f32_e32 v10, v10
	v_cvt_pk_bf16_f32 v52, v70, v71
	v_lshl_add_u64 v[48:49], s[90:91], 0, v[48:49]
	v_lshl_add_u64 v[48:49], v[48:49], 0, s[12:13]
	v_add_f32_e32 v10, 1.0, v10
	v_rcp_f32_e32 v70, v10
	v_mul_f32_e32 v10, 0xbfb8aa3b, v69
	v_exp_f32_e32 v10, v10
	v_cvt_pk_bf16_f32 v54, v72, v73
	v_cvt_pk_bf16_f32 v55, v50, v51
	v_lshl_add_u64 v[50:51], v[48:49], 0, v[0:1]
	global_store_dwordx4 v[50:51], v[52:55], off
	ds_read_b128 v[52:55], v15 offset:1152
	v_add_f32_e32 v10, 1.0, v10
	v_rcp_f32_e32 v71, v10
	v_lshlrev_b32_e32 v10, 16, v11
	v_and_b32_e32 v11, 0xffff0000, v11
	s_waitcnt lgkmcnt(0)
	v_lshlrev_b32_e32 v48, 16, v52
	v_and_b32_e32 v49, 0xffff0000, v52
	v_pk_mul_f32 v[68:69], v[70:71], v[68:69]
	v_lshlrev_b32_e32 v52, 16, v53
	v_pk_mul_f32 v[48:49], v[68:69], v[48:49]
	v_mul_f32_e32 v68, 0xbfb8aa3b, v10
	v_mul_f32_e32 v69, 0xbfb8aa3b, v11
	v_exp_f32_e32 v68, v68
	v_exp_f32_e32 v69, v69
	v_and_b32_e32 v53, 0xffff0000, v53
	v_add_f32_e32 v68, 1.0, v68
	v_add_f32_e32 v69, 1.0, v69
	v_rcp_f32_e32 v68, v68
	v_rcp_f32_e32 v69, v69
	s_nop 0
	v_pk_mul_f32 v[10:11], v[68:69], v[10:11]
	v_lshlrev_b32_e32 v68, 16, v12
	v_and_b32_e32 v69, 0xffff0000, v12
	v_mul_f32_e32 v12, 0xbfb8aa3b, v68
	v_exp_f32_e32 v12, v12
	v_pk_mul_f32 v[52:53], v[10:11], v[52:53]
	v_lshlrev_b32_e32 v10, 16, v54
	v_and_b32_e32 v11, 0xffff0000, v54
	v_add_f32_e32 v12, 1.0, v12
	v_rcp_f32_e32 v70, v12
	v_mul_f32_e32 v12, 0xbfb8aa3b, v69
	v_exp_f32_e32 v12, v12
	s_nop 0
	v_add_f32_e32 v12, 1.0, v12
	v_rcp_f32_e32 v71, v12
	v_lshlrev_b32_e32 v12, 16, v13
	v_and_b32_e32 v13, 0xffff0000, v13
	v_mul_f32_e32 v54, 0xbfb8aa3b, v12
	v_pk_mul_f32 v[68:69], v[70:71], v[68:69]
	v_exp_f32_e32 v54, v54
	v_pk_mul_f32 v[68:69], v[68:69], v[10:11]
	v_lshlrev_b32_e32 v10, 16, v55
	v_and_b32_e32 v11, 0xffff0000, v55
	v_mul_f32_e32 v55, 0xbfb8aa3b, v13
	v_exp_f32_e32 v55, v55
	v_add_f32_e32 v54, 1.0, v54
	v_rcp_f32_e32 v54, v54
	v_add_f32_e32 v55, 1.0, v55
	v_rcp_f32_e32 v55, v55
	s_nop 0
	v_pk_mul_f32 v[12:13], v[54:55], v[12:13]
	s_nop 0
	v_pk_mul_f32 v[54:55], v[12:13], v[10:11]
	v_cvt_pk_bf16_f32 v10, v48, v49
	v_cvt_pk_bf16_f32 v13, v54, v55
	v_lshlrev_b32_e32 v54, 16, v6
	v_and_b32_e32 v55, 0xffff0000, v6
	v_mul_f32_e32 v6, 0xbfb8aa3b, v54
	v_exp_f32_e32 v6, v6
	v_lshlrev_b64 v[48:49], 12, v[66:67]
	v_lshl_add_u64 v[48:49], s[90:91], 0, v[48:49]
	v_lshl_add_u64 v[48:49], v[48:49], 0, s[12:13]
	v_add_f32_e32 v6, 1.0, v6
	v_rcp_f32_e32 v66, v6
	v_mul_f32_e32 v6, 0xbfb8aa3b, v55
	v_exp_f32_e32 v6, v6
	v_cvt_pk_bf16_f32 v11, v52, v53
	v_cvt_pk_bf16_f32 v12, v68, v69
	v_lshl_add_u64 v[52:53], v[48:49], 0, v[0:1]
	global_store_dwordx4 v[52:53], v[10:13], off
	ds_read_b128 v[10:13], v15 offset:2304
	v_add_f32_e32 v6, 1.0, v6
	v_rcp_f32_e32 v67, v6
	v_lshlrev_b32_e32 v6, 16, v7
	v_and_b32_e32 v7, 0xffff0000, v7
	s_waitcnt lgkmcnt(0)
	v_lshlrev_b32_e32 v48, 16, v10
	v_and_b32_e32 v49, 0xffff0000, v10
	v_pk_mul_f32 v[54:55], v[66:67], v[54:55]
	v_lshlrev_b32_e32 v10, 16, v11
	v_pk_mul_f32 v[48:49], v[54:55], v[48:49]
	v_mul_f32_e32 v54, 0xbfb8aa3b, v6
	v_mul_f32_e32 v55, 0xbfb8aa3b, v7
	v_exp_f32_e32 v54, v54
	v_exp_f32_e32 v55, v55
	v_and_b32_e32 v11, 0xffff0000, v11
	v_add_f32_e32 v54, 1.0, v54
	v_add_f32_e32 v55, 1.0, v55
	v_rcp_f32_e32 v54, v54
	v_rcp_f32_e32 v55, v55
	s_nop 0
	v_pk_mul_f32 v[6:7], v[54:55], v[6:7]
	v_lshlrev_b32_e32 v54, 16, v8
	v_and_b32_e32 v55, 0xffff0000, v8
	v_mul_f32_e32 v8, 0xbfb8aa3b, v54
	v_exp_f32_e32 v8, v8
	v_pk_mul_f32 v[10:11], v[6:7], v[10:11]
	v_lshlrev_b32_e32 v6, 16, v12
	v_and_b32_e32 v7, 0xffff0000, v12
	v_add_f32_e32 v8, 1.0, v8
	v_rcp_f32_e32 v66, v8
	v_mul_f32_e32 v8, 0xbfb8aa3b, v55
	v_exp_f32_e32 v8, v8
	s_nop 0
	v_add_f32_e32 v8, 1.0, v8
	v_rcp_f32_e32 v67, v8
	v_lshlrev_b32_e32 v8, 16, v9
	v_and_b32_e32 v9, 0xffff0000, v9
	v_mul_f32_e32 v12, 0xbfb8aa3b, v8
	v_pk_mul_f32 v[54:55], v[66:67], v[54:55]
	v_exp_f32_e32 v12, v12
	v_pk_mul_f32 v[54:55], v[54:55], v[6:7]
	v_lshlrev_b32_e32 v6, 16, v13
	v_and_b32_e32 v7, 0xffff0000, v13
	v_mul_f32_e32 v13, 0xbfb8aa3b, v9
	v_exp_f32_e32 v13, v13
	v_add_f32_e32 v12, 1.0, v12
	v_rcp_f32_e32 v12, v12
	v_add_f32_e32 v13, 1.0, v13
	v_rcp_f32_e32 v13, v13
	s_nop 0
	v_pk_mul_f32 v[8:9], v[12:13], v[8:9]
	s_nop 0
	v_pk_mul_f32 v[12:13], v[8:9], v[6:7]
	v_cvt_pk_bf16_f32 v6, v48, v49
	v_cvt_pk_bf16_f32 v9, v12, v13
	v_lshlrev_b32_e32 v12, 16, v2
	v_and_b32_e32 v13, 0xffff0000, v2
	v_mul_f32_e32 v2, 0xbfb8aa3b, v12
	v_exp_f32_e32 v2, v2
	v_cvt_pk_bf16_f32 v7, v10, v11
	v_lshlrev_b64 v[10:11], 12, v[64:65]
	v_lshl_add_u64 v[10:11], s[90:91], 0, v[10:11]
	v_add_f32_e32 v2, 1.0, v2
	v_rcp_f32_e32 v48, v2
	v_mul_f32_e32 v2, 0xbfb8aa3b, v13
	v_exp_f32_e32 v2, v2
	v_lshl_add_u64 v[10:11], v[10:11], 0, s[12:13]
	v_cvt_pk_bf16_f32 v8, v54, v55
	v_lshl_add_u64 v[54:55], v[10:11], 0, v[0:1]
	global_store_dwordx4 v[54:55], v[6:9], off
	ds_read_b128 v[6:9], v15 offset:3456
	v_add_f32_e32 v2, 1.0, v2
	v_rcp_f32_e32 v49, v2
	v_lshlrev_b32_e32 v2, 16, v3
	v_and_b32_e32 v3, 0xffff0000, v3
	s_waitcnt lgkmcnt(0)
	v_lshlrev_b32_e32 v10, 16, v6
	v_and_b32_e32 v11, 0xffff0000, v6
	v_pk_mul_f32 v[12:13], v[48:49], v[12:13]
	v_lshlrev_b32_e32 v6, 16, v7
	v_pk_mul_f32 v[10:11], v[12:13], v[10:11]
	v_mul_f32_e32 v12, 0xbfb8aa3b, v2
	v_mul_f32_e32 v13, 0xbfb8aa3b, v3
	v_exp_f32_e32 v12, v12
	v_exp_f32_e32 v13, v13
	v_and_b32_e32 v7, 0xffff0000, v7
	v_add_f32_e32 v12, 1.0, v12
	v_add_f32_e32 v13, 1.0, v13
	v_rcp_f32_e32 v12, v12
	v_rcp_f32_e32 v13, v13
	s_nop 0
	v_pk_mul_f32 v[2:3], v[12:13], v[2:3]
	v_lshlrev_b32_e32 v12, 16, v4
	v_and_b32_e32 v13, 0xffff0000, v4
	v_mul_f32_e32 v4, 0xbfb8aa3b, v12
	v_exp_f32_e32 v4, v4
	v_pk_mul_f32 v[6:7], v[2:3], v[6:7]
	v_lshlrev_b32_e32 v2, 16, v8
	v_and_b32_e32 v3, 0xffff0000, v8
	v_add_f32_e32 v4, 1.0, v4
	v_rcp_f32_e32 v48, v4
	v_mul_f32_e32 v4, 0xbfb8aa3b, v13
	v_exp_f32_e32 v4, v4
	s_nop 0
	v_add_f32_e32 v4, 1.0, v4
	v_rcp_f32_e32 v49, v4
	v_lshlrev_b32_e32 v4, 16, v5
	v_and_b32_e32 v5, 0xffff0000, v5
	v_mul_f32_e32 v8, 0xbfb8aa3b, v4
	v_pk_mul_f32 v[12:13], v[48:49], v[12:13]
	v_exp_f32_e32 v8, v8
	v_pk_mul_f32 v[12:13], v[12:13], v[2:3]
	v_lshlrev_b32_e32 v2, 16, v9
	v_and_b32_e32 v3, 0xffff0000, v9
	v_mul_f32_e32 v9, 0xbfb8aa3b, v5
	v_exp_f32_e32 v9, v9
	v_add_f32_e32 v8, 1.0, v8
	v_rcp_f32_e32 v8, v8
	v_lshl_add_u64 v[48:49], s[10:11], 0, v[180:181]
	v_add_f32_e32 v9, 1.0, v9
	v_rcp_f32_e32 v9, v9
	s_nop 0
	v_pk_mul_f32 v[4:5], v[8:9], v[4:5]
	s_nop 0
	v_pk_mul_f32 v[8:9], v[4:5], v[2:3]
	v_cvt_pk_bf16_f32 v3, v6, v7
	v_lshlrev_b64 v[6:7], 12, v[48:49]
	v_lshl_add_u64 v[6:7], s[90:91], 0, v[6:7]
	v_lshl_add_u64 v[48:49], v[6:7], 0, s[12:13]
	v_cvt_pk_bf16_f32 v2, v10, v11
	v_cvt_pk_bf16_f32 v4, v12, v13
	v_cvt_pk_bf16_f32 v5, v8, v9
	v_lshl_add_u64 v[6:7], v[48:49], 0, v[0:1]
	global_store_dwordx4 v[6:7], v[2:5], off
	v_pk_mul_f32 v[6:7], v[38:39], v[14:15] op_sel_hi:[1,0]
	v_lshlrev_b32_e32 v0, 1, v174
	v_pk_mul_f32 v[2:3], v[32:33], v[14:15] op_sel_hi:[1,0]
	v_pk_mul_f32 v[4:5], v[34:35], v[14:15] op_sel_hi:[1,0]
	v_cvt_pk_bf16_f32 v2, v2, v3
	v_cvt_pk_bf16_f32 v3, v4, v5
	v_pk_mul_f32 v[4:5], v[36:37], v[14:15] op_sel_hi:[1,0]
	s_mov_b64 s[12:13], s[86:87]
	v_cvt_pk_bf16_f32 v4, v4, v5
	v_cvt_pk_bf16_f32 v5, v6, v7
	ds_write2_b64 v80, v[2:3], v[4:5] offset1:2
	v_pk_mul_f32 v[2:3], v[40:41], v[14:15] op_sel_hi:[1,0]
	v_pk_mul_f32 v[4:5], v[42:43], v[14:15] op_sel_hi:[1,0]
	v_cvt_pk_bf16_f32 v2, v2, v3
	v_cvt_pk_bf16_f32 v3, v4, v5
	v_pk_mul_f32 v[4:5], v[44:45], v[14:15] op_sel_hi:[1,0]
	v_pk_mul_f32 v[6:7], v[46:47], v[14:15] op_sel_hi:[1,0]
	v_cvt_pk_bf16_f32 v4, v4, v5
	v_cvt_pk_bf16_f32 v5, v6, v7
	ds_write2_b64 v80, v[2:3], v[4:5] offset0:4 offset1:6
	v_pk_mul_f32 v[2:3], v[16:17], v[14:15] op_sel_hi:[1,0]
	v_pk_mul_f32 v[4:5], v[18:19], v[14:15] op_sel_hi:[1,0]
	v_cvt_pk_bf16_f32 v2, v2, v3
	v_cvt_pk_bf16_f32 v3, v4, v5
	v_pk_mul_f32 v[4:5], v[20:21], v[14:15] op_sel_hi:[1,0]
	v_pk_mul_f32 v[6:7], v[22:23], v[14:15] op_sel_hi:[1,0]
	v_cvt_pk_bf16_f32 v4, v4, v5
	v_cvt_pk_bf16_f32 v5, v6, v7
	ds_write2_b64 v80, v[2:3], v[4:5] offset0:8 offset1:10
	v_pk_mul_f32 v[2:3], v[24:25], v[14:15] op_sel_hi:[1,0]
	v_pk_mul_f32 v[4:5], v[26:27], v[14:15] op_sel_hi:[1,0]
	v_cvt_pk_bf16_f32 v2, v2, v3
	v_cvt_pk_bf16_f32 v3, v4, v5
	v_pk_mul_f32 v[4:5], v[28:29], v[14:15] op_sel_hi:[1,0]
	v_pk_mul_f32 v[6:7], v[30:31], v[14:15] op_sel_hi:[1,0]
	v_cvt_pk_bf16_f32 v4, v4, v5
	v_cvt_pk_bf16_f32 v5, v6, v7
	ds_write2_b64 v80, v[2:3], v[4:5] offset0:12 offset1:14
	s_waitcnt lgkmcnt(0)
	v_lshl_add_u64 v[2:3], v[56:57], 0, v[0:1]
	v_mov_b32_e32 v16, v216
	v_mov_b32_e32 v17, v217
	v_mov_b32_e32 v18, v218
	v_mov_b32_e32 v19, v219
	v_lshl_add_u64 v[2:3], v[58:59], 0, v[0:1]
	v_mov_b32_e32 v10, v220
	v_mov_b32_e32 v11, v221
	v_mov_b32_e32 v12, v222
	v_mov_b32_e32 v13, v223
	v_lshl_add_u64 v[2:3], v[60:61], 0, v[0:1]
	v_mov_b32_e32 v6, v224
	v_mov_b32_e32 v7, v225
	v_mov_b32_e32 v8, v226
	v_mov_b32_e32 v9, v227
	v_lshl_add_u64 v[2:3], v[62:63], 0, v[0:1]
	ds_read_b128 v[20:23], v15
	v_mov_b32_e32 v2, v228
	v_mov_b32_e32 v3, v229
	v_mov_b32_e32 v4, v230
	v_mov_b32_e32 v5, v231
	s_waitcnt lgkmcnt(0)
	v_lshlrev_b32_e32 v24, 16, v20
	v_and_b32_e32 v25, 0xffff0000, v20
	v_lshlrev_b32_e32 v20, 16, v21
	v_and_b32_e32 v21, 0xffff0000, v21
	s_waitcnt vmcnt(4)
	v_lshlrev_b32_e32 v26, 16, v16
	v_mul_f32_e32 v0, 0xbfb8aa3b, v26
	v_exp_f32_e32 v0, v0
	v_and_b32_e32 v27, 0xffff0000, v16
	v_lshlrev_b32_e32 v16, 16, v17
	v_and_b32_e32 v17, 0xffff0000, v17
	v_add_f32_e32 v0, 1.0, v0
	v_rcp_f32_e32 v28, v0
	v_mul_f32_e32 v0, 0xbfb8aa3b, v27
	v_exp_f32_e32 v0, v0
	s_nop 0
	v_add_f32_e32 v0, 1.0, v0
	v_rcp_f32_e32 v29, v0
	v_mul_f32_e32 v0, 0xbfb8aa3b, v16
	v_exp_f32_e32 v0, v0
	v_pk_mul_f32 v[26:27], v[28:29], v[26:27]
	s_nop 0
	v_pk_mul_f32 v[24:25], v[26:27], v[24:25]
	v_add_f32_e32 v0, 1.0, v0
	v_rcp_f32_e32 v26, v0
	v_mul_f32_e32 v0, 0xbfb8aa3b, v17
	v_exp_f32_e32 v0, v0
	s_nop 0
	v_add_f32_e32 v0, 1.0, v0
	v_rcp_f32_e32 v27, v0
	s_nop 0
	v_pk_mul_f32 v[16:17], v[26:27], v[16:17]
	v_lshlrev_b32_e32 v26, 16, v18
	v_mul_f32_e32 v0, 0xbfb8aa3b, v26
	v_exp_f32_e32 v0, v0
	v_and_b32_e32 v27, 0xffff0000, v18
	v_lshlrev_b32_e32 v18, 16, v19
	v_and_b32_e32 v19, 0xffff0000, v19
	v_add_f32_e32 v0, 1.0, v0
	v_rcp_f32_e32 v28, v0
	v_mul_f32_e32 v0, 0xbfb8aa3b, v27
	v_exp_f32_e32 v0, v0
	v_pk_mul_f32 v[20:21], v[16:17], v[20:21]
	v_lshlrev_b32_e32 v16, 16, v22
	v_and_b32_e32 v17, 0xffff0000, v22
	v_add_f32_e32 v0, 1.0, v0
	v_rcp_f32_e32 v29, v0
	v_mul_f32_e32 v0, 0xbfb8aa3b, v18
	v_exp_f32_e32 v0, v0
	v_pk_mul_f32 v[26:27], v[28:29], v[26:27]
	s_nop 0
	v_pk_mul_f32 v[26:27], v[26:27], v[16:17]
	v_add_f32_e32 v0, 1.0, v0
	v_rcp_f32_e32 v22, v0
	v_mul_f32_e32 v0, 0xbfb8aa3b, v19
	v_exp_f32_e32 v0, v0
	v_lshlrev_b32_e32 v16, 16, v23
	v_and_b32_e32 v17, 0xffff0000, v23
	v_add_f32_e32 v0, 1.0, v0
	v_rcp_f32_e32 v23, v0
	s_nop 0
	v_pk_mul_f32 v[18:19], v[22:23], v[18:19]
	s_nop 0
	v_pk_mul_f32 v[22:23], v[18:19], v[16:17]
	v_cvt_pk_bf16_f32 v16, v24, v25
	v_cvt_pk_bf16_f32 v19, v22, v23
	v_lshlrev_b32_e32 v22, 16, v10
	v_mul_f32_e32 v0, 0xbfb8aa3b, v22
	v_exp_f32_e32 v0, v0
	v_and_b32_e32 v23, 0xffff0000, v10
	v_cvt_pk_bf16_f32 v17, v20, v21
	v_cvt_pk_bf16_f32 v18, v26, v27
	v_add_f32_e32 v0, 1.0, v0
	v_rcp_f32_e32 v24, v0
	v_mul_f32_e32 v0, 0xbfb8aa3b, v23
	v_exp_f32_e32 v0, v0
	global_store_dwordx4 v[50:51], v[16:19], off offset:128
	v_lshlrev_b32_e32 v10, 16, v11
	ds_read_b128 v[16:19], v15 offset:1152
	v_add_f32_e32 v0, 1.0, v0
	v_rcp_f32_e32 v25, v0
	v_mul_f32_e32 v0, 0xbfb8aa3b, v10
	v_exp_f32_e32 v0, v0
	s_waitcnt lgkmcnt(0)
	v_lshlrev_b32_e32 v20, 16, v16
	v_and_b32_e32 v21, 0xffff0000, v16
	v_pk_mul_f32 v[22:23], v[24:25], v[22:23]
	v_and_b32_e32 v11, 0xffff0000, v11
	v_add_f32_e32 v0, 1.0, v0
	v_pk_mul_f32 v[20:21], v[22:23], v[20:21]
	v_rcp_f32_e32 v22, v0
	v_mul_f32_e32 v0, 0xbfb8aa3b, v11
	v_exp_f32_e32 v0, v0
	v_lshlrev_b32_e32 v16, 16, v17
	v_and_b32_e32 v17, 0xffff0000, v17
	v_add_f32_e32 v0, 1.0, v0
	v_rcp_f32_e32 v23, v0
	s_nop 0
	v_pk_mul_f32 v[10:11], v[22:23], v[10:11]
	v_lshlrev_b32_e32 v22, 16, v12
	v_mul_f32_e32 v0, 0xbfb8aa3b, v22
	v_exp_f32_e32 v0, v0
	v_and_b32_e32 v23, 0xffff0000, v12
	v_lshlrev_b32_e32 v12, 16, v13
	v_and_b32_e32 v13, 0xffff0000, v13
	v_add_f32_e32 v0, 1.0, v0
	v_rcp_f32_e32 v24, v0
	v_mul_f32_e32 v0, 0xbfb8aa3b, v23
	v_exp_f32_e32 v0, v0
	v_pk_mul_f32 v[16:17], v[10:11], v[16:17]
	v_lshlrev_b32_e32 v10, 16, v18
	v_and_b32_e32 v11, 0xffff0000, v18
	v_add_f32_e32 v0, 1.0, v0
	v_rcp_f32_e32 v25, v0
	v_mul_f32_e32 v0, 0xbfb8aa3b, v12
	v_exp_f32_e32 v0, v0
	v_pk_mul_f32 v[22:23], v[24:25], v[22:23]
	s_nop 0
	v_pk_mul_f32 v[22:23], v[22:23], v[10:11]
	v_add_f32_e32 v0, 1.0, v0
	v_rcp_f32_e32 v18, v0
	v_mul_f32_e32 v0, 0xbfb8aa3b, v13
	v_exp_f32_e32 v0, v0
	v_lshlrev_b32_e32 v10, 16, v19
	v_and_b32_e32 v11, 0xffff0000, v19
	v_add_f32_e32 v0, 1.0, v0
	v_rcp_f32_e32 v19, v0
	s_nop 0
	v_pk_mul_f32 v[12:13], v[18:19], v[12:13]
	s_nop 0
	v_pk_mul_f32 v[18:19], v[12:13], v[10:11]
	v_cvt_pk_bf16_f32 v10, v20, v21
	v_cvt_pk_bf16_f32 v13, v18, v19
	v_lshlrev_b32_e32 v18, 16, v6
	v_mul_f32_e32 v0, 0xbfb8aa3b, v18
	v_exp_f32_e32 v0, v0
	v_and_b32_e32 v19, 0xffff0000, v6
	v_cvt_pk_bf16_f32 v11, v16, v17
	v_cvt_pk_bf16_f32 v12, v22, v23
	v_add_f32_e32 v0, 1.0, v0
	v_rcp_f32_e32 v20, v0
	v_mul_f32_e32 v0, 0xbfb8aa3b, v19
	v_exp_f32_e32 v0, v0
	global_store_dwordx4 v[52:53], v[10:13], off offset:128
	v_lshlrev_b32_e32 v6, 16, v7
	ds_read_b128 v[10:13], v15 offset:2304
	v_add_f32_e32 v0, 1.0, v0
	v_rcp_f32_e32 v21, v0
	v_mul_f32_e32 v0, 0xbfb8aa3b, v6
	v_exp_f32_e32 v0, v0
	s_waitcnt lgkmcnt(0)
	v_lshlrev_b32_e32 v16, 16, v10
	v_and_b32_e32 v17, 0xffff0000, v10
	v_pk_mul_f32 v[18:19], v[20:21], v[18:19]
	v_and_b32_e32 v7, 0xffff0000, v7
	v_add_f32_e32 v0, 1.0, v0
	v_pk_mul_f32 v[16:17], v[18:19], v[16:17]
	v_rcp_f32_e32 v18, v0
	v_mul_f32_e32 v0, 0xbfb8aa3b, v7
	v_exp_f32_e32 v0, v0
	v_lshlrev_b32_e32 v10, 16, v11
	v_and_b32_e32 v11, 0xffff0000, v11
	v_add_f32_e32 v0, 1.0, v0
	v_rcp_f32_e32 v19, v0
	s_nop 0
	v_pk_mul_f32 v[6:7], v[18:19], v[6:7]
	v_lshlrev_b32_e32 v18, 16, v8
	v_mul_f32_e32 v0, 0xbfb8aa3b, v18
	v_exp_f32_e32 v0, v0
	v_and_b32_e32 v19, 0xffff0000, v8
	v_lshlrev_b32_e32 v8, 16, v9
	v_and_b32_e32 v9, 0xffff0000, v9
	v_add_f32_e32 v0, 1.0, v0
	v_rcp_f32_e32 v20, v0
	v_mul_f32_e32 v0, 0xbfb8aa3b, v19
	v_exp_f32_e32 v0, v0
	v_pk_mul_f32 v[10:11], v[6:7], v[10:11]
	v_lshlrev_b32_e32 v6, 16, v12
	v_and_b32_e32 v7, 0xffff0000, v12
	v_add_f32_e32 v0, 1.0, v0
	v_rcp_f32_e32 v21, v0
	v_mul_f32_e32 v0, 0xbfb8aa3b, v8
	v_exp_f32_e32 v0, v0
	v_pk_mul_f32 v[18:19], v[20:21], v[18:19]
	s_nop 0
	v_pk_mul_f32 v[18:19], v[18:19], v[6:7]
	v_add_f32_e32 v0, 1.0, v0
	v_rcp_f32_e32 v12, v0
	v_mul_f32_e32 v0, 0xbfb8aa3b, v9
	v_exp_f32_e32 v0, v0
	v_lshlrev_b32_e32 v6, 16, v13
	v_and_b32_e32 v7, 0xffff0000, v13
	v_add_f32_e32 v0, 1.0, v0
	v_rcp_f32_e32 v13, v0
	s_nop 0
	v_pk_mul_f32 v[8:9], v[12:13], v[8:9]
	s_nop 0
	v_pk_mul_f32 v[12:13], v[8:9], v[6:7]
	v_cvt_pk_bf16_f32 v6, v16, v17
	v_cvt_pk_bf16_f32 v9, v12, v13
	v_lshlrev_b32_e32 v12, 16, v2
	v_mul_f32_e32 v0, 0xbfb8aa3b, v12
	v_exp_f32_e32 v0, v0
	v_and_b32_e32 v13, 0xffff0000, v2
	v_cvt_pk_bf16_f32 v7, v10, v11
	v_cvt_pk_bf16_f32 v8, v18, v19
	v_add_f32_e32 v0, 1.0, v0
	v_rcp_f32_e32 v14, v0
	v_mul_f32_e32 v0, 0xbfb8aa3b, v13
	v_exp_f32_e32 v0, v0
	global_store_dwordx4 v[54:55], v[6:9], off offset:128
	v_lshlrev_b32_e32 v2, 16, v3
	ds_read_b128 v[6:9], v15 offset:3456
	v_add_f32_e32 v0, 1.0, v0
	v_rcp_f32_e32 v15, v0
	v_mul_f32_e32 v0, 0xbfb8aa3b, v2
	v_exp_f32_e32 v0, v0
	s_waitcnt lgkmcnt(0)
	v_lshlrev_b32_e32 v10, 16, v6
	v_and_b32_e32 v11, 0xffff0000, v6
	v_pk_mul_f32 v[12:13], v[14:15], v[12:13]
	v_and_b32_e32 v3, 0xffff0000, v3
	v_add_f32_e32 v0, 1.0, v0
	v_pk_mul_f32 v[10:11], v[12:13], v[10:11]
	v_rcp_f32_e32 v12, v0
	v_mul_f32_e32 v0, 0xbfb8aa3b, v3
	v_exp_f32_e32 v0, v0
	v_lshlrev_b32_e32 v6, 16, v7
	v_and_b32_e32 v7, 0xffff0000, v7
	v_add_f32_e32 v0, 1.0, v0
	v_rcp_f32_e32 v13, v0
	s_nop 0
	v_pk_mul_f32 v[2:3], v[12:13], v[2:3]
	v_lshlrev_b32_e32 v12, 16, v4
	v_mul_f32_e32 v0, 0xbfb8aa3b, v12
	v_exp_f32_e32 v0, v0
	v_and_b32_e32 v13, 0xffff0000, v4
	v_lshlrev_b32_e32 v4, 16, v5
	v_and_b32_e32 v5, 0xffff0000, v5
	v_add_f32_e32 v0, 1.0, v0
	v_rcp_f32_e32 v14, v0
	v_mul_f32_e32 v0, 0xbfb8aa3b, v13
	v_exp_f32_e32 v0, v0
	v_pk_mul_f32 v[6:7], v[2:3], v[6:7]
	v_lshlrev_b32_e32 v2, 16, v8
	v_and_b32_e32 v3, 0xffff0000, v8
	v_add_f32_e32 v0, 1.0, v0
	v_rcp_f32_e32 v15, v0
	v_mul_f32_e32 v0, 0xbfb8aa3b, v4
	v_exp_f32_e32 v0, v0
	v_pk_mul_f32 v[12:13], v[14:15], v[12:13]
	s_nop 0
	v_pk_mul_f32 v[12:13], v[12:13], v[2:3]
	v_add_f32_e32 v0, 1.0, v0
	v_rcp_f32_e32 v8, v0
	v_mul_f32_e32 v0, 0xbfb8aa3b, v5
	v_exp_f32_e32 v0, v0
	v_lshlrev_b32_e32 v2, 16, v9
	v_and_b32_e32 v3, 0xffff0000, v9
	v_add_f32_e32 v0, 1.0, v0
	v_rcp_f32_e32 v9, v0
	s_nop 0
	v_pk_mul_f32 v[4:5], v[8:9], v[4:5]
	s_nop 0
	v_pk_mul_f32 v[8:9], v[4:5], v[2:3]
	v_cvt_pk_bf16_f32 v2, v10, v11
	v_cvt_pk_bf16_f32 v3, v6, v7
	v_cvt_pk_bf16_f32 v4, v12, v13
	v_cvt_pk_bf16_f32 v5, v8, v9
.LBB0_624:
	v_lshlrev_b32_e32 v0, 1, v166
	s_cmp_lt_i32 s7, 0
	v_lshl_add_u64 v[6:7], v[48:49], 0, v[0:1]
	s_cselect_b64 s[4:5], -1, 0
	s_waitcnt vmcnt(0) lgkmcnt(0)
	v_mov_b32_e32 v99, v147
	v_mov_b32_e32 v98, v146
	v_mov_b32_e32 v97, v145
	v_mov_b32_e32 v96, v144
	v_mov_b32_e32 v103, v143
	v_mov_b32_e32 v102, v142
	v_mov_b32_e32 v101, v141
	v_mov_b32_e32 v100, v140
	v_mov_b32_e32 v107, v139
	v_mov_b32_e32 v106, v138
	v_mov_b32_e32 v105, v137
	v_mov_b32_e32 v104, v136
	v_mov_b32_e32 v111, v135
	v_mov_b32_e32 v110, v134
	v_mov_b32_e32 v109, v133
	v_mov_b32_e32 v108, v132
	v_mov_b32_e32 v115, v131
	v_mov_b32_e32 v114, v130
	v_mov_b32_e32 v113, v129
	v_mov_b32_e32 v112, v128
	v_mov_b32_e32 v119, v93
	v_mov_b32_e32 v118, v92
	v_mov_b32_e32 v117, v91
	v_mov_b32_e32 v116, v90
	v_mov_b32_e32 v123, v89
	v_mov_b32_e32 v122, v88
	v_mov_b32_e32 v121, v87
	v_mov_b32_e32 v120, v86
	v_mov_b32_e32 v127, v85
	v_mov_b32_e32 v126, v84
	v_mov_b32_e32 v125, v83
	v_mov_b32_e32 v124, v82
	global_store_dwordx4 v[6:7], v[2:5], off offset:128
	s_branch .LBB0_348
.Ltail_nc:
	v_lshlrev_b32_e32 v0, 1, v166
	s_cmp_lt_i32 s7, 0
	v_lshl_add_u64 v[6:7], v[48:49], 0, v[0:1]
	s_cselect_b64 s[4:5], -1, 0
	s_waitcnt lgkmcnt(0)
	global_store_dwordx4 v[6:7], v[2:5], off offset:128
	s_branch .LBB0_348

.LBB0_679:
	s_or_b64 exec, exec, s[4:5]
	s_mov_b64 s[10:11], s[40:41]
	s_waitcnt lgkmcnt(0)
	s_barrier
	s_add_u32 s4, s10, 0xd200000
	s_addc_u32 s5, s11, 0
	s_add_u32 s8, s10, 0x13400000
	s_addc_u32 s9, s11, 0
	s_add_u32 s12, s10, 0x1b400000
	s_addc_u32 s13, s11, 0
	v_readlane_b32 s0, v254, 5
	s_add_u32 s0, s12, s0
	v_readlane_b32 s1, v254, 4
	v_mbcnt_lo_u32_b32 v0, -1, 0
	v_mbcnt_hi_u32_b32 v0, -1, v0
	s_addc_u32 s1, s13, s1
	v_add_u32_e32 v6, s69, v0
	v_readlane_b32 s6, v254, 6
	v_readlane_b32 s7, v254, 7
	s_add_u32 s20, s0, s6
	v_bfe_u32 v0, v6, 4, 2
	v_readlane_b32 s0, v252, 52
	s_addc_u32 s21, s1, s7
	v_and_b32_e32 v3, 15, v6
	v_or_b32_e32 v2, s0, v0
	v_lshlrev_b32_e32 v0, 2, v0
	v_readlane_b32 s0, v254, 8
	v_mul_lo_u32 v2, v2, s43
	v_bitop3_b32 v0, v0, v3, s84 bitop3:0x36
	s_add_u32 s0, s20, s0
	v_lshl_or_b32 v118, v0, 4, v2
	v_mov_b32_e32 v119, v1
	s_addc_u32 s1, s21, 0
	v_lshl_add_u64 v[2:3], s[0:1], 0, v[118:119]
	s_mov_b32 s0, 0xfff20000
	s_mov_b32 s1, -1
	v_lshl_add_u64 v[4:5], v[2:3], 0, s[0:1]
	s_mov_b32 s0, 0xfff20600
	s_mov_b32 m0, s85
	s_mov_b32 s1, -1
	global_load_lds_dwordx4 v[4:5], off
	v_lshl_add_u64 v[2:3], v[2:3], 0, s[0:1]
	s_add_i32 m0, s85, 0x2000
	v_readlane_b32 s0, v254, 9
	s_add_u32 s0, s20, s0
	s_addc_u32 s1, s21, 0
	global_load_lds_dwordx4 v[2:3], off
	v_lshl_add_u64 v[2:3], s[0:1], 0, v[118:119]
	s_mov_b32 s0, 0xfff90000
	s_mov_b32 s1, -1
	v_lshl_add_u64 v[4:5], v[2:3], 0, s[0:1]
	s_mov_b32 s0, 0xfff90600
	s_add_i32 m0, s85, 0x4000
	s_mov_b32 s1, -1
	v_readlane_b32 s50, v254, 11
	global_load_lds_dwordx4 v[4:5], off
	v_lshl_add_u64 v[2:3], v[2:3], 0, s[0:1]
	s_add_i32 m0, s85, 0x6000
	s_mul_i32 s0, s50, 0x3800
	s_add_u32 s0, s20, s0
	s_addc_u32 s1, s21, 0
	global_load_lds_dwordx4 v[2:3], off
	v_lshl_add_u64 v[2:3], s[0:1], 0, v[118:119]
	s_add_i32 m0, s85, 0x8000
	v_lshl_add_u64 v[4:5], v[2:3], 0, s[92:93]
	global_load_lds_dwordx4 v118, s[0:1]
	s_add_i32 m0, s85, 0xa000
	s_mov_b64 s[0:1], 0x70000
	global_load_lds_dwordx4 v[4:5], off
	v_lshl_add_u64 v[4:5], v[2:3], 0, s[0:1]
	s_mov_b64 s[0:1], 0x70600
	v_lshl_add_u64 v[2:3], v[2:3], 0, s[0:1]
	v_and_b32_e32 v7, 31, v6
	v_readlane_b32 s0, v254, 12
	s_add_i32 m0, s85, 0xc000
	v_mov_b32_e32 v121, v1
	v_or_b32_e32 v0, s0, v7
	v_readlane_b32 s0, v253, 14
	global_load_lds_dwordx4 v[4:5], off
	s_add_i32 m0, s85, 0xe000
	v_readlane_b32 s1, v253, 15
	global_load_lds_dwordx4 v[2:3], off
	s_nop 0
	v_lshl_add_u64 v[2:3], s[0:1], 0, v[0:1]
	v_mov_b64_e32 v[4:5], s[12:13]
	v_mad_u64_u32 v[4:5], s[0:1], v2, s43, v[4:5]
	v_readlane_b32 s0, v254, 13
	v_mad_i32_i24 v5, v3, s43, v5
	v_readlane_b32 s1, v254, 14
	v_lshrrev_b32_e32 v0, 1, v6
	s_waitcnt vmcnt(4)
	v_and_b32_e32 v120, 16, v0
	v_lshl_add_u64 v[2:3], v[4:5], 0, s[0:1]
	s_waitcnt lgkmcnt(0)
	s_barrier
	v_lshl_add_u64 v[2:3], v[2:3], 0, v[120:121]
	global_load_dwordx4 v[82:85], v[2:3], off
	global_load_dwordx4 v[86:89], v[2:3], off offset:32
	global_load_dwordx4 v[90:93], v[2:3], off offset:64
	global_load_dwordx4 v[94:97], v[2:3], off offset:96
	global_load_dwordx4 v[98:101], v[2:3], off offset:128
	global_load_dwordx4 v[102:105], v[2:3], off offset:160
	global_load_dwordx4 v[106:109], v[2:3], off offset:192
	global_load_dwordx4 v[110:113], v[2:3], off offset:224
	v_readlane_b32 s0, v253, 4
	v_and_b32_e32 v0, 7, v6
	v_lshlrev_b32_e32 v122, 4, v0
	v_mov_b32_e32 v2, s0
	s_movk_i32 s0, 0x90
	v_bfe_u32 v124, v6, 3, 3
	v_mov_b32_e32 v123, v1
	v_mad_u32_u24 v129, v7, s0, v2
	v_mad_u32_u24 v131, v124, s0, v2
	v_lshl_add_u64 v[4:5], s[10:11], 0, v[122:123]
	s_mov_b64 s[0:1], 0xd400000
	v_lshl_add_u64 v[132:133], v[4:5], 0, s[0:1]
	s_mov_b64 s[0:1], 0x10400000
	v_bfe_u32 v3, v6, 5, 1
	v_lshlrev_b32_e32 v0, 3, v0
	v_lshl_add_u64 v[134:135], v[4:5], 0, s[0:1]
	v_readlane_b32 s0, v254, 32
	v_and_b32_e32 v125, 63, v6
	v_lshlrev_b32_e32 v8, 3, v3
	v_or_b32_e32 v2, 64, v0
	v_lshl_add_u32 v3, v3, 2, s0
	s_mov_b32 s19, 4
	v_or_b32_e32 v127, s31, v7
	v_cmp_gt_u32_e64 s[6:7], 32, v125
	v_or_b32_e32 v126, 8, v124
	v_or_b32_e32 v128, 16, v124
	v_or_b32_e32 v130, 24, v124
	v_add_u32_e32 v217, 0x480, v131
	v_add_u32_e32 v218, 0x900, v131
	v_add_u32_e32 v219, 0xd80, v131
	v_sub_u32_e32 v123, v3, v7
	s_mov_b32 s28, 0
	s_mov_b64 s[24:25], 0
	v_lshlrev_b32_e32 v136, 1, v0
	v_lshlrev_b32_e32 v138, 1, v2
	v_add_u32_e32 v220, v129, v8
	s_mov_b32 s51, 4
	s_mov_b32 s49, s66
	s_mov_b32 s48, 0
	s_mov_b32 s29, s66
	v_and_b32_e32 v240, 31, v125
	v_lshrrev_b32_e32 v241, 5, v125
	v_lshlrev_b32_e32 v242, 2, v125
	v_and_b32_e32 v242, 12, v242
	v_bfe_u32 v243, v125, 2, 2
	v_or_b32_e32 v242, v242, v243
	v_xor_b32_e32 v244, v241, v242
	v_lshlrev_b32_e32 v244, 4, v244
	v_lshl_add_u32 v238, v240, 8, v244
	v_lshl_or_b32 v245, v241, 2, v243
	v_lshlrev_b32_e32 v246, 2, v243
	v_or_b32_e32 v246, v246, v241
	v_bfe_u32 v247, v125, 1, 1
	v_lshrrev_b32_e32 v248, 3, v125
	v_and_or_b32 v247, v248, 2, v247
	v_xor_b32_e32 v247, v247, v246
	v_lshlrev_b32_e32 v247, 4, v247
	v_lshl_add_u32 v247, v245, 8, v247
	v_lshlrev_b32_e32 v248, 3, v125
	v_and_b32_e32 v248, 8, v248
	v_add_u32_e32 v239, v247, v248
	v_add_u32_e32 v239, 0x2000, v239
	s_branch .LBB0_681
.LBB0_680:
	s_or_b64 exec, exec, s[0:1]
	s_ashr_i32 s14, s11, 3
	s_lshl_b32 s16, s14, 7
	s_ashr_i32 s11, s10, 31
	s_ashr_i32 s15, s14, 31
	s_ashr_i32 s17, s16, 31
	s_lshl_b64 s[10:11], s[10:11], 11
	s_add_i32 s52, s52, s31
	s_add_u32 s1, s10, s52
	s_addc_u32 s0, s11, 0
	s_lshl_b64 s[86:87], s[16:17], 1
	s_add_u32 s10, s12, s86
	s_addc_u32 s11, s13, s87
	v_or_b32_e32 v196, s1, v124
	v_mov_b64_e32 v[34:35], s[10:11]
	v_mad_u64_u32 v[36:37], s[10:11], v196, s43, v[34:35]
	v_lshl_add_u64 v[42:43], v[134:135], 0, s[86:87]
	v_mad_i32_i24 v37, s0, v211, v37
	s_mov_b64 s[16:17], 0x2a00
	v_lshl_add_u64 v[142:143], v[36:37], 0, s[16:17]
	v_mov_b32_e32 v137, v1
	v_mad_u64_u32 v[146:147], s[10:11], v196, s94, v[42:43]
	s_waitcnt lgkmcnt(0)
	v_lshl_add_u64 v[38:39], v[132:133], 0, s[86:87]
	v_lshl_add_u64 v[36:37], v[142:143], 0, v[136:137]
	v_mad_i32_i24 v147, s0, v214, v147
	global_load_dwordx4 v[70:73], v[36:37], off
	global_load_dwordx4 v[78:81], v[146:147], off
	v_mad_u64_u32 v[144:145], s[10:11], v196, s94, v[38:39]
	v_mad_u64_u32 v[36:37], s[10:11], v196, 24, s[4:5]
	v_mad_i32_i24 v37, s0, 24, v37
	s_lshl_b64 s[10:11], s[14:15], 2
	v_lshl_add_u64 v[156:157], v[36:37], 0, s[10:11]
	v_add_co_u32_e32 v158, vcc, s47, v156
	global_load_dword v0, v[156:157], off
	s_nop 0
	v_addc_co_u32_e32 v159, vcc, 0, v157, vcc
	global_load_dword v200, v[158:159], off
	v_mad_i32_i24 v145, s0, v214, v145
	global_load_dwordx4 v[74:77], v[144:145], off
	v_or_b32_e32 v194, s1, v126
	v_mad_u64_u32 v[36:37], s[14:15], v194, s43, v[34:35]
	v_mad_i32_i24 v37, s0, v211, v37
	v_lshl_add_u64 v[160:161], v[36:37], 0, s[16:17]
	v_lshl_add_u64 v[36:37], v[160:161], 0, v[136:137]
	global_load_dwordx4 v[58:61], v[36:37], off
	v_mad_u64_u32 v[36:37], s[14:15], v194, 24, s[4:5]
	v_mad_i32_i24 v37, s0, 24, v37
	v_lshl_add_u64 v[166:167], v[36:37], 0, s[10:11]
	v_add_co_u32_e32 v168, vcc, s47, v166
	v_or_b32_e32 v192, s1, v128
	s_nop 0
	v_addc_co_u32_e32 v169, vcc, 0, v167, vcc
	v_mad_u64_u32 v[36:37], s[14:15], v192, s43, v[34:35]
	global_load_dword v225, v[166:167], off
	global_load_dword v226, v[168:169], off
	v_mad_i32_i24 v37, s0, v211, v37
	v_lshl_add_u64 v[170:171], v[36:37], 0, s[16:17]
	v_lshl_add_u64 v[36:37], v[170:171], 0, v[136:137]
	global_load_dwordx4 v[46:49], v[36:37], off
	v_mad_u64_u32 v[36:37], s[14:15], v192, 24, s[4:5]
	v_mad_i32_i24 v37, s0, 24, v37
	v_or_b32_e32 v190, s1, v130
	v_lshl_add_u64 v[176:177], v[36:37], 0, s[10:11]
	v_mad_u64_u32 v[114:115], s[14:15], v190, 24, s[4:5]
	v_add_co_u32_e32 v178, vcc, s47, v176
	v_mad_u64_u32 v[34:35], s[14:15], v190, s43, v[34:35]
	v_mad_i32_i24 v115, s0, 24, v115
	v_addc_co_u32_e32 v179, vcc, 0, v177, vcc
	v_mad_i32_i24 v35, s0, v211, v35
	v_lshl_add_u64 v[186:187], v[114:115], 0, s[10:11]
	v_mad_u64_u32 v[162:163], s[14:15], v194, s94, v[38:39]
	v_mad_u64_u32 v[164:165], s[14:15], v194, s94, v[42:43]
	v_mad_u64_u32 v[172:173], s[14:15], v192, s94, v[38:39]
	v_mad_u64_u32 v[174:175], s[14:15], v192, s94, v[42:43]
	v_lshl_add_u64 v[180:181], v[34:35], 0, s[16:17]
	v_mad_u64_u32 v[182:183], s[14:15], v190, s94, v[38:39]
	v_mad_u64_u32 v[184:185], s[14:15], v190, s94, v[42:43]
	v_add_co_u32_e32 v188, vcc, s47, v186
	v_mad_i32_i24 v163, s0, v214, v163
	v_mad_i32_i24 v165, s0, v214, v165
	v_mad_i32_i24 v173, s0, v214, v173
	v_mad_i32_i24 v175, s0, v214, v175
	v_lshl_add_u64 v[34:35], v[180:181], 0, v[136:137]
	v_mad_i32_i24 v183, s0, v214, v183
	v_mad_i32_i24 v185, s0, v214, v185
	v_addc_co_u32_e32 v189, vcc, 0, v187, vcc
	v_add_u32_e32 v221, v131, v122
	global_load_dwordx4 v[62:65], v[162:163], off
	global_load_dwordx4 v[66:69], v[164:165], off
	global_load_dwordx4 v[50:53], v[172:173], off
	global_load_dwordx4 v[54:57], v[174:175], off
	global_load_dword v223, v[176:177], off
	global_load_dword v224, v[178:179], off
	global_load_dwordx4 v[38:41], v[182:183], off
	global_load_dwordx4 v[42:45], v[184:185], off
	global_load_dword v139, v[186:187], off
	global_load_dword v222, v[188:189], off
	s_waitcnt vmcnt(0) lgkmcnt(0)
	v_lshlrev_b32_e32 v234, 16, v70
	global_load_dwordx4 v[34:37], v[34:35], off
	ds_read_b128 v[114:117], v221
	ds_read_b32 v198, v131 offset:128
	v_and_b32_e32 v235, 0xffff0000, v70
	v_mul_f32_e32 v70, 0xbfb8aa3b, v234
	v_exp_f32_e32 v70, v70
	s_waitcnt lgkmcnt(0)
	v_and_b32_e32 v229, 0xffff0000, v114
	v_max3_f32 v201, v198, v0, v200
	v_sub_f32_e32 v198, v198, v201
	v_sub_f32_e32 v0, v0, v201
	v_exp_f32_e32 v199, v198
	v_exp_f32_e32 v198, v0
	v_sub_f32_e32 v0, v200, v201
	v_exp_f32_e32 v0, v0
	v_add_f32_e32 v70, 1.0, v70
	v_add_f32_e32 v200, v199, v198
	v_rcp_f32_e32 v236, v70
	v_add_f32_e32 v200, v0, v200
	v_rcp_f32_e32 v200, v200
	v_mul_f32_e32 v70, 0xbfb8aa3b, v235
	v_exp_f32_e32 v70, v70
	v_lshlrev_b32_e32 v230, 16, v114
	v_mul_f32_e32 v0, v0, v200
	v_pk_mul_f32 v[202:203], v[198:199], v[200:201] op_sel_hi:[1,0]
	v_lshlrev_b32_e32 v200, 16, v117
	v_and_b32_e32 v201, 0xffff0000, v77
	v_lshlrev_b32_e32 v198, 16, v77
	v_and_b32_e32 v199, 0xffff0000, v117
	v_pk_mul_f32 v[200:201], v[202:203], v[200:201] op_sel:[1,0] op_sel_hi:[0,1]
	v_add_f32_e32 v70, 1.0, v70
	v_pk_fma_f32 v[198:199], v[202:203], v[198:199], v[200:201]
	v_lshlrev_b32_e32 v200, 16, v81
	v_and_b32_e32 v201, 0xffff0000, v81
	v_rcp_f32_e32 v237, v70
	v_lshlrev_b32_e32 v70, 16, v71
	v_pk_fma_f32 v[198:199], v[0:1], v[200:201], v[198:199] op_sel_hi:[0,1,1]
	v_lshlrev_b32_e32 v200, 16, v73
	v_and_b32_e32 v201, 0xffff0000, v73
	v_mul_f32_e32 v73, 0xbfb8aa3b, v70
	v_exp_f32_e32 v73, v73
	v_and_b32_e32 v71, 0xffff0000, v71
	v_and_b32_e32 v231, 0xffff0000, v74
	v_lshlrev_b32_e32 v228, 16, v74
	v_add_f32_e32 v73, 1.0, v73
	v_rcp_f32_e32 v114, v73
	v_mul_f32_e32 v73, 0xbfb8aa3b, v71
	v_exp_f32_e32 v73, v73
	v_pk_mul_f32 v[230:231], v[202:203], v[230:231] op_sel:[1,0] op_sel_hi:[0,1]
	v_pk_fma_f32 v[228:229], v[202:203], v[228:229], v[230:231]
	v_and_b32_e32 v231, 0xffff0000, v115
	v_add_f32_e32 v73, 1.0, v73
	v_lshlrev_b32_e32 v74, 16, v115
	v_rcp_f32_e32 v115, v73
	v_lshlrev_b32_e32 v230, 16, v75
	v_and_b32_e32 v75, 0xffff0000, v75
	v_pk_mul_f32 v[74:75], v[202:203], v[74:75] op_sel:[1,0] op_sel_hi:[0,1]
	v_lshlrev_b32_e32 v232, 16, v78
	v_and_b32_e32 v233, 0xffff0000, v78
	v_lshlrev_b32_e32 v78, 16, v79
	v_and_b32_e32 v79, 0xffff0000, v79
	v_pk_fma_f32 v[74:75], v[202:203], v[230:231], v[74:75]
	v_pk_mul_f32 v[70:71], v[114:115], v[70:71]
	v_pk_fma_f32 v[74:75], v[0:1], v[78:79], v[74:75] op_sel_hi:[0,1,1]
	v_pk_mul_f32 v[70:71], v[70:71], v[74:75]
	v_lshlrev_b32_e32 v74, 16, v76
	v_and_b32_e32 v79, 0xffff0000, v76
	v_lshlrev_b32_e32 v76, 16, v80
	v_and_b32_e32 v77, 0xffff0000, v80
	v_lshlrev_b32_e32 v80, 16, v72
	v_and_b32_e32 v81, 0xffff0000, v72
	v_mul_f32_e32 v72, 0xbfb8aa3b, v80
	v_mul_f32_e32 v73, 0xbfb8aa3b, v81
	v_exp_f32_e32 v72, v72
	v_exp_f32_e32 v73, v73
	v_lshlrev_b32_e32 v78, 16, v116
	v_and_b32_e32 v75, 0xffff0000, v116
	v_pk_mul_f32 v[78:79], v[202:203], v[78:79] op_sel:[1,0] op_sel_hi:[0,1]
	v_pk_fma_f32 v[74:75], v[202:203], v[74:75], v[78:79]
	v_pk_fma_f32 v[228:229], v[0:1], v[232:233], v[228:229] op_sel_hi:[0,1,1]
	v_add_f32_e32 v72, 1.0, v72
	v_add_f32_e32 v73, 1.0, v73
	v_pk_fma_f32 v[74:75], v[0:1], v[76:77], v[74:75] op_sel_hi:[0,1,1]
	v_mul_f32_e32 v0, 0xbfb8aa3b, v200
	v_rcp_f32_e32 v72, v72
	v_rcp_f32_e32 v73, v73
	v_exp_f32_e32 v0, v0
	v_mov_b32_e32 v197, s0
	v_pk_mul_f32 v[234:235], v[236:237], v[234:235]
	v_pk_mul_f32 v[72:73], v[72:73], v[80:81]
	v_add_f32_e32 v0, 1.0, v0
	v_pk_mul_f32 v[74:75], v[72:73], v[74:75]
	v_rcp_f32_e32 v72, v0
	v_mul_f32_e32 v0, 0xbfb8aa3b, v201
	v_exp_f32_e32 v0, v0
	v_pk_mul_f32 v[228:229], v[234:235], v[228:229]
	v_cvt_pk_bf16_f32 v74, v74, v75
	v_add_u32_e32 v78, v217, v122
	v_add_f32_e32 v0, 1.0, v0
	v_rcp_f32_e32 v73, v0
	v_lshlrev_b32_e32 v80, 16, v62
	v_mov_b32_e32 v195, s0
	v_mov_b32_e32 v193, s0
	v_pk_mul_f32 v[72:73], v[72:73], v[200:201]
	v_lshlrev_b32_e32 v200, 16, v58
	v_pk_mul_f32 v[76:77], v[72:73], v[198:199]
	v_cvt_pk_bf16_f32 v73, v70, v71
	v_lshlrev_b64 v[70:71], 12, v[196:197]
	v_lshl_add_u64 v[70:71], s[8:9], 0, v[70:71]
	v_lshl_add_u64 v[70:71], v[70:71], 0, s[86:87]
	v_cvt_pk_bf16_f32 v72, v228, v229
	v_cvt_pk_bf16_f32 v75, v76, v77
	v_lshl_add_u64 v[70:71], v[70:71], 0, v[136:137]
	global_store_dwordx4 v[70:71], v[72:75], off offset:1536
	ds_read_b128 v[114:117], v78
	ds_read_b32 v0, v217 offset:128
	v_and_b32_e32 v201, 0xffff0000, v58
	v_mul_f32_e32 v58, 0xbfb8aa3b, v200
	v_exp_f32_e32 v58, v58
	s_waitcnt lgkmcnt(0)
	v_and_b32_e32 v81, 0xffff0000, v114
	v_max3_f32 v74, v0, v225, v226
	v_sub_f32_e32 v0, v0, v74
	v_exp_f32_e32 v73, v0
	v_sub_f32_e32 v0, v225, v74
	v_exp_f32_e32 v72, v0
	v_sub_f32_e32 v0, v226, v74
	v_exp_f32_e32 v0, v0
	v_add_f32_e32 v58, 1.0, v58
	v_add_f32_e32 v74, v73, v72
	v_rcp_f32_e32 v202, v58
	v_add_f32_e32 v74, v0, v74
	v_rcp_f32_e32 v74, v74
	v_mul_f32_e32 v58, 0xbfb8aa3b, v201
	v_exp_f32_e32 v58, v58
	v_lshlrev_b32_e32 v196, 16, v114
	v_mul_f32_e32 v0, v0, v74
	v_pk_mul_f32 v[76:77], v[72:73], v[74:75] op_sel_hi:[1,0]
	v_lshlrev_b32_e32 v74, 16, v117
	v_and_b32_e32 v75, 0xffff0000, v65
	v_lshlrev_b32_e32 v72, 16, v65
	v_and_b32_e32 v73, 0xffff0000, v117
	v_pk_mul_f32 v[74:75], v[76:77], v[74:75] op_sel:[1,0] op_sel_hi:[0,1]
	v_add_f32_e32 v58, 1.0, v58
	v_pk_fma_f32 v[72:73], v[76:77], v[72:73], v[74:75]
	v_lshlrev_b32_e32 v74, 16, v69
	v_and_b32_e32 v75, 0xffff0000, v69
	v_rcp_f32_e32 v203, v58
	v_lshlrev_b32_e32 v58, 16, v59
	v_pk_fma_f32 v[72:73], v[0:1], v[74:75], v[72:73] op_sel_hi:[0,1,1]
	v_lshlrev_b32_e32 v74, 16, v61
	v_and_b32_e32 v75, 0xffff0000, v61
	v_mul_f32_e32 v61, 0xbfb8aa3b, v58
	v_exp_f32_e32 v61, v61
	v_and_b32_e32 v59, 0xffff0000, v59
	v_and_b32_e32 v197, 0xffff0000, v62
	v_pk_mul_f32 v[196:197], v[76:77], v[196:197] op_sel:[1,0] op_sel_hi:[0,1]
	v_add_f32_e32 v61, 1.0, v61
	v_rcp_f32_e32 v114, v61
	v_mul_f32_e32 v61, 0xbfb8aa3b, v59
	v_exp_f32_e32 v61, v61
	v_pk_fma_f32 v[80:81], v[76:77], v[80:81], v[196:197]
	v_and_b32_e32 v197, 0xffff0000, v115
	v_lshlrev_b32_e32 v62, 16, v115
	v_add_f32_e32 v61, 1.0, v61
	v_rcp_f32_e32 v115, v61
	v_lshlrev_b32_e32 v196, 16, v63
	v_and_b32_e32 v63, 0xffff0000, v63
	v_pk_mul_f32 v[62:63], v[76:77], v[62:63] op_sel:[1,0] op_sel_hi:[0,1]
	v_lshlrev_b32_e32 v198, 16, v66
	v_and_b32_e32 v199, 0xffff0000, v66
	v_lshlrev_b32_e32 v66, 16, v67
	v_and_b32_e32 v67, 0xffff0000, v67
	v_pk_fma_f32 v[62:63], v[76:77], v[196:197], v[62:63]
	v_pk_mul_f32 v[58:59], v[114:115], v[58:59]
	v_pk_fma_f32 v[62:63], v[0:1], v[66:67], v[62:63] op_sel_hi:[0,1,1]
	v_pk_mul_f32 v[58:59], v[58:59], v[62:63]
	v_lshlrev_b32_e32 v62, 16, v64
	v_and_b32_e32 v67, 0xffff0000, v64
	v_lshlrev_b32_e32 v64, 16, v68
	v_and_b32_e32 v65, 0xffff0000, v68
	v_lshlrev_b32_e32 v68, 16, v60
	v_and_b32_e32 v69, 0xffff0000, v60
	v_mul_f32_e32 v60, 0xbfb8aa3b, v68
	v_mul_f32_e32 v61, 0xbfb8aa3b, v69
	v_exp_f32_e32 v60, v60
	v_exp_f32_e32 v61, v61
	v_lshlrev_b32_e32 v66, 16, v116
	v_and_b32_e32 v63, 0xffff0000, v116
	v_pk_mul_f32 v[66:67], v[76:77], v[66:67] op_sel:[1,0] op_sel_hi:[0,1]
	v_pk_fma_f32 v[62:63], v[76:77], v[62:63], v[66:67]
	v_pk_fma_f32 v[80:81], v[0:1], v[198:199], v[80:81] op_sel_hi:[0,1,1]
	v_add_f32_e32 v60, 1.0, v60
	v_add_f32_e32 v61, 1.0, v61
	v_pk_fma_f32 v[62:63], v[0:1], v[64:65], v[62:63] op_sel_hi:[0,1,1]
	v_mul_f32_e32 v0, 0xbfb8aa3b, v74
	v_rcp_f32_e32 v60, v60
	v_rcp_f32_e32 v61, v61
	v_exp_f32_e32 v0, v0
	v_pk_mul_f32 v[200:201], v[202:203], v[200:201]
	v_add_u32_e32 v66, v218, v122
	v_pk_mul_f32 v[60:61], v[60:61], v[68:69]
	v_add_f32_e32 v0, 1.0, v0
	v_pk_mul_f32 v[62:63], v[60:61], v[62:63]
	v_rcp_f32_e32 v60, v0
	v_mul_f32_e32 v0, 0xbfb8aa3b, v75
	v_exp_f32_e32 v0, v0
	v_pk_mul_f32 v[80:81], v[200:201], v[80:81]
	v_cvt_pk_bf16_f32 v62, v62, v63
	v_lshlrev_b32_e32 v114, 16, v46
	v_add_f32_e32 v0, 1.0, v0
	v_rcp_f32_e32 v61, v0
	v_and_b32_e32 v115, 0xffff0000, v46
	v_mul_f32_e32 v46, 0xbfb8aa3b, v114
	v_exp_f32_e32 v46, v46
	v_pk_mul_f32 v[60:61], v[60:61], v[74:75]
	v_and_b32_e32 v77, 0xffff0000, v50
	v_pk_mul_f32 v[64:65], v[60:61], v[72:73]
	v_cvt_pk_bf16_f32 v61, v58, v59
	v_lshlrev_b64 v[58:59], 12, v[194:195]
	v_lshl_add_u64 v[58:59], s[8:9], 0, v[58:59]
	v_lshl_add_u64 v[58:59], v[58:59], 0, s[86:87]
	v_cvt_pk_bf16_f32 v60, v80, v81
	v_cvt_pk_bf16_f32 v63, v64, v65
	v_lshl_add_u64 v[58:59], v[58:59], 0, v[136:137]
	global_store_dwordx4 v[58:59], v[60:63], off offset:1536
	ds_read_b128 v[72:75], v66
	ds_read_b32 v0, v218 offset:128
	v_add_f32_e32 v46, 1.0, v46
	v_rcp_f32_e32 v116, v46
	v_mul_f32_e32 v46, 0xbfb8aa3b, v115
	v_exp_f32_e32 v46, v46
	s_waitcnt lgkmcnt(0)
	v_max3_f32 v62, v0, v223, v224
	v_sub_f32_e32 v0, v0, v62
	v_exp_f32_e32 v61, v0
	v_sub_f32_e32 v0, v223, v62
	v_exp_f32_e32 v60, v0
	v_sub_f32_e32 v0, v224, v62
	v_exp_f32_e32 v0, v0
	v_add_f32_e32 v46, 1.0, v46
	v_add_f32_e32 v62, v61, v60
	v_rcp_f32_e32 v117, v46
	v_add_f32_e32 v62, v0, v62
	v_rcp_f32_e32 v62, v62
	v_lshlrev_b32_e32 v46, 16, v47
	v_and_b32_e32 v47, 0xffff0000, v47
	v_and_b32_e32 v69, 0xffff0000, v72
	v_mul_f32_e32 v0, v0, v62
	v_pk_mul_f32 v[64:65], v[60:61], v[62:63] op_sel_hi:[1,0]
	v_lshlrev_b32_e32 v62, 16, v75
	v_and_b32_e32 v63, 0xffff0000, v53
	v_lshlrev_b32_e32 v60, 16, v53
	v_and_b32_e32 v61, 0xffff0000, v75
	v_pk_mul_f32 v[62:63], v[64:65], v[62:63] op_sel:[1,0] op_sel_hi:[0,1]
	v_pk_fma_f32 v[60:61], v[64:65], v[60:61], v[62:63]
	v_lshlrev_b32_e32 v62, 16, v57
	v_and_b32_e32 v63, 0xffff0000, v57
	v_pk_fma_f32 v[60:61], v[0:1], v[62:63], v[60:61] op_sel_hi:[0,1,1]
	v_lshlrev_b32_e32 v62, 16, v49
	v_and_b32_e32 v63, 0xffff0000, v49
	v_mul_f32_e32 v49, 0xbfb8aa3b, v46
	v_exp_f32_e32 v49, v49
	v_lshlrev_b32_e32 v76, 16, v72
	v_lshlrev_b32_e32 v68, 16, v50
	v_pk_mul_f32 v[76:77], v[64:65], v[76:77] op_sel:[1,0] op_sel_hi:[0,1]
	v_add_f32_e32 v49, 1.0, v49
	v_rcp_f32_e32 v72, v49
	v_mul_f32_e32 v49, 0xbfb8aa3b, v47
	v_exp_f32_e32 v49, v49
	v_pk_fma_f32 v[68:69], v[64:65], v[68:69], v[76:77]
	v_and_b32_e32 v77, 0xffff0000, v73
	v_lshlrev_b32_e32 v50, 16, v73
	v_add_f32_e32 v49, 1.0, v49
	v_rcp_f32_e32 v73, v49
	v_lshlrev_b32_e32 v76, 16, v51
	v_and_b32_e32 v51, 0xffff0000, v51
	v_pk_mul_f32 v[50:51], v[64:65], v[50:51] op_sel:[1,0] op_sel_hi:[0,1]
	v_lshlrev_b32_e32 v80, 16, v54
	v_and_b32_e32 v81, 0xffff0000, v54
	v_lshlrev_b32_e32 v54, 16, v55
	v_and_b32_e32 v55, 0xffff0000, v55
	v_pk_fma_f32 v[50:51], v[64:65], v[76:77], v[50:51]
	v_pk_mul_f32 v[46:47], v[72:73], v[46:47]
	v_pk_fma_f32 v[50:51], v[0:1], v[54:55], v[50:51] op_sel_hi:[0,1,1]
	v_pk_mul_f32 v[50:51], v[46:47], v[50:51]
	v_lshlrev_b32_e32 v46, 16, v52
	v_and_b32_e32 v55, 0xffff0000, v52
	v_lshlrev_b32_e32 v52, 16, v56
	v_and_b32_e32 v53, 0xffff0000, v56
	v_lshlrev_b32_e32 v56, 16, v48
	v_and_b32_e32 v57, 0xffff0000, v48
	v_mul_f32_e32 v48, 0xbfb8aa3b, v56
	v_mul_f32_e32 v49, 0xbfb8aa3b, v57
	v_exp_f32_e32 v48, v48
	v_exp_f32_e32 v49, v49
	v_lshlrev_b32_e32 v54, 16, v74
	v_and_b32_e32 v47, 0xffff0000, v74
	v_pk_mul_f32 v[54:55], v[64:65], v[54:55] op_sel:[1,0] op_sel_hi:[0,1]
	v_pk_fma_f32 v[46:47], v[64:65], v[46:47], v[54:55]
	v_pk_fma_f32 v[68:69], v[0:1], v[80:81], v[68:69] op_sel_hi:[0,1,1]
	v_add_f32_e32 v48, 1.0, v48
	v_add_f32_e32 v49, 1.0, v49
	v_pk_fma_f32 v[46:47], v[0:1], v[52:53], v[46:47] op_sel_hi:[0,1,1]
	v_mul_f32_e32 v0, 0xbfb8aa3b, v62
	v_rcp_f32_e32 v48, v48
	v_rcp_f32_e32 v49, v49
	v_exp_f32_e32 v0, v0
	v_pk_mul_f32 v[114:115], v[116:117], v[114:115]
	v_add_u32_e32 v67, v219, v122
	v_pk_mul_f32 v[48:49], v[48:49], v[56:57]
	v_add_f32_e32 v0, 1.0, v0
	v_pk_mul_f32 v[48:49], v[48:49], v[46:47]
	v_rcp_f32_e32 v46, v0
	v_mul_f32_e32 v0, 0xbfb8aa3b, v63
	v_exp_f32_e32 v0, v0
	v_pk_mul_f32 v[68:69], v[114:115], v[68:69]
	v_cvt_pk_bf16_f32 v48, v48, v49
	v_and_b32_e32 v57, 0xffff0000, v38
	v_add_f32_e32 v0, 1.0, v0
	v_rcp_f32_e32 v47, v0
	v_lshlrev_b32_e32 v64, 16, v42
	v_and_b32_e32 v65, 0xffff0000, v42
	v_lshlrev_b32_e32 v42, 16, v43
	v_pk_mul_f32 v[46:47], v[46:47], v[62:63]
	v_and_b32_e32 v43, 0xffff0000, v43
	v_pk_mul_f32 v[52:53], v[46:47], v[60:61]
	v_cvt_pk_bf16_f32 v47, v50, v51
	v_lshlrev_b64 v[50:51], 12, v[192:193]
	v_lshl_add_u64 v[50:51], s[8:9], 0, v[50:51]
	v_lshl_add_u64 v[50:51], v[50:51], 0, s[86:87]
	v_cvt_pk_bf16_f32 v46, v68, v69
	v_cvt_pk_bf16_f32 v49, v52, v53
	v_lshl_add_u64 v[54:55], v[50:51], 0, v[136:137]
	global_store_dwordx4 v[54:55], v[46:49], off offset:1536
	ds_read_b128 v[60:63], v67
	ds_read_b32 v0, v219 offset:128
	s_waitcnt vmcnt(0)
	v_lshlrev_b32_e32 v68, 16, v34
	v_and_b32_e32 v69, 0xffff0000, v34
	v_mul_f32_e32 v34, 0xbfb8aa3b, v68
	v_exp_f32_e32 v34, v34
	s_waitcnt lgkmcnt(0)
	v_max3_f32 v48, v0, v139, v222
	v_sub_f32_e32 v0, v0, v48
	v_exp_f32_e32 v47, v0
	v_sub_f32_e32 v0, v139, v48
	v_exp_f32_e32 v46, v0
	v_sub_f32_e32 v0, v222, v48
	v_exp_f32_e32 v0, v0
	v_add_f32_e32 v34, 1.0, v34
	v_add_f32_e32 v48, v47, v46
	v_rcp_f32_e32 v72, v34
	v_add_f32_e32 v48, v0, v48
	v_rcp_f32_e32 v48, v48
	v_mul_f32_e32 v34, 0xbfb8aa3b, v69
	v_exp_f32_e32 v34, v34
	v_and_b32_e32 v53, 0xffff0000, v60
	v_mul_f32_e32 v0, v0, v48
	v_pk_mul_f32 v[50:51], v[46:47], v[48:49] op_sel_hi:[1,0]
	v_lshlrev_b32_e32 v48, 16, v63
	v_and_b32_e32 v49, 0xffff0000, v41
	v_lshlrev_b32_e32 v46, 16, v41
	v_and_b32_e32 v47, 0xffff0000, v63
	v_pk_mul_f32 v[48:49], v[50:51], v[48:49] op_sel:[1,0] op_sel_hi:[0,1]
	v_add_f32_e32 v34, 1.0, v34
	v_pk_fma_f32 v[46:47], v[50:51], v[46:47], v[48:49]
	v_lshlrev_b32_e32 v48, 16, v45
	v_and_b32_e32 v49, 0xffff0000, v45
	v_rcp_f32_e32 v73, v34
	v_lshlrev_b32_e32 v34, 16, v35
	v_pk_fma_f32 v[46:47], v[0:1], v[48:49], v[46:47] op_sel_hi:[0,1,1]
	v_lshlrev_b32_e32 v48, 16, v37
	v_and_b32_e32 v49, 0xffff0000, v37
	v_mul_f32_e32 v37, 0xbfb8aa3b, v34
	v_exp_f32_e32 v37, v37
	v_and_b32_e32 v35, 0xffff0000, v35
	v_lshlrev_b32_e32 v56, 16, v60
	v_lshlrev_b32_e32 v52, 16, v38
	v_add_f32_e32 v37, 1.0, v37
	v_rcp_f32_e32 v60, v37
	v_mul_f32_e32 v37, 0xbfb8aa3b, v35
	v_exp_f32_e32 v37, v37
	v_pk_mul_f32 v[56:57], v[50:51], v[56:57] op_sel:[1,0] op_sel_hi:[0,1]
	v_pk_fma_f32 v[52:53], v[50:51], v[52:53], v[56:57]
	v_and_b32_e32 v57, 0xffff0000, v61
	v_add_f32_e32 v37, 1.0, v37
	v_lshlrev_b32_e32 v38, 16, v61
	v_rcp_f32_e32 v61, v37
	v_lshlrev_b32_e32 v56, 16, v39
	v_and_b32_e32 v39, 0xffff0000, v39
	v_pk_mul_f32 v[38:39], v[50:51], v[38:39] op_sel:[1,0] op_sel_hi:[0,1]
	v_pk_fma_f32 v[38:39], v[50:51], v[56:57], v[38:39]
	v_pk_mul_f32 v[34:35], v[60:61], v[34:35]
	v_pk_fma_f32 v[38:39], v[0:1], v[42:43], v[38:39] op_sel_hi:[0,1,1]
	v_pk_mul_f32 v[38:39], v[34:35], v[38:39]
	v_lshlrev_b32_e32 v34, 16, v40
	v_and_b32_e32 v43, 0xffff0000, v40
	v_lshlrev_b32_e32 v40, 16, v44
	v_and_b32_e32 v41, 0xffff0000, v44
	v_lshlrev_b32_e32 v44, 16, v36
	v_and_b32_e32 v45, 0xffff0000, v36
	v_mul_f32_e32 v36, 0xbfb8aa3b, v44
	v_mul_f32_e32 v37, 0xbfb8aa3b, v45
	v_exp_f32_e32 v36, v36
	v_exp_f32_e32 v37, v37
	v_lshlrev_b32_e32 v42, 16, v62
	v_and_b32_e32 v35, 0xffff0000, v62
	v_pk_mul_f32 v[42:43], v[50:51], v[42:43] op_sel:[1,0] op_sel_hi:[0,1]
	v_pk_fma_f32 v[34:35], v[50:51], v[34:35], v[42:43]
	v_pk_fma_f32 v[52:53], v[0:1], v[64:65], v[52:53] op_sel_hi:[0,1,1]
	v_add_f32_e32 v36, 1.0, v36
	v_add_f32_e32 v37, 1.0, v37
	v_pk_fma_f32 v[34:35], v[0:1], v[40:41], v[34:35] op_sel_hi:[0,1,1]
	v_mul_f32_e32 v0, 0xbfb8aa3b, v48
	v_rcp_f32_e32 v36, v36
	v_rcp_f32_e32 v37, v37
	v_exp_f32_e32 v0, v0
	v_mov_b32_e32 v191, s0
	v_mov_b32_e32 v141, v140
	v_pk_mul_f32 v[36:37], v[36:37], v[44:45]
	v_add_f32_e32 v0, 1.0, v0
	v_pk_mul_f32 v[36:37], v[36:37], v[34:35]
	v_rcp_f32_e32 v34, v0
	v_mul_f32_e32 v0, 0xbfb8aa3b, v49
	v_exp_f32_e32 v0, v0
	v_pk_mul_f32 v[68:69], v[72:73], v[68:69]
	v_pk_mul_f32 v[18:19], v[18:19], v[140:141]
	v_pk_mul_f32 v[20:21], v[20:21], v[140:141]
	v_add_f32_e32 v0, 1.0, v0
	v_rcp_f32_e32 v35, v0
	v_pk_mul_f32 v[2:3], v[2:3], v[140:141]
	v_pk_mul_f32 v[4:5], v[4:5], v[140:141]
	v_pk_mul_f32 v[52:53], v[68:69], v[52:53]
	v_pk_mul_f32 v[34:35], v[34:35], v[48:49]
	v_cvt_pk_bf16_f32 v18, v18, v19
	v_pk_mul_f32 v[40:41], v[34:35], v[46:47]
	v_cvt_pk_bf16_f32 v35, v38, v39
	v_lshlrev_b64 v[38:39], 12, v[190:191]
	v_lshl_add_u64 v[38:39], s[8:9], 0, v[38:39]
	v_lshl_add_u64 v[38:39], v[38:39], 0, s[86:87]
	v_cvt_pk_bf16_f32 v19, v20, v21
	v_pk_mul_f32 v[20:21], v[22:23], v[140:141]
	v_pk_mul_f32 v[22:23], v[24:25], v[140:141]
	v_cvt_pk_bf16_f32 v2, v2, v3
	v_cvt_pk_bf16_f32 v3, v4, v5
	v_pk_mul_f32 v[4:5], v[6:7], v[140:141]
	v_pk_mul_f32 v[6:7], v[8:9], v[140:141]
	v_cvt_pk_bf16_f32 v34, v52, v53
	v_cvt_pk_bf16_f32 v36, v36, v37
	v_cvt_pk_bf16_f32 v37, v40, v41
	v_lshl_add_u64 v[56:57], v[38:39], 0, v[136:137]
	v_cvt_pk_bf16_f32 v20, v20, v21
	v_cvt_pk_bf16_f32 v21, v22, v23
	v_cvt_pk_bf16_f32 v4, v4, v5
	v_cvt_pk_bf16_f32 v5, v6, v7
	global_store_dwordx4 v[56:57], v[34:37], off offset:1536
	ds_write2_b64 v220, v[18:19], v[20:21] offset1:2
	v_pk_mul_f32 v[18:19], v[26:27], v[140:141]
	v_pk_mul_f32 v[20:21], v[28:29], v[140:141]
	ds_write2_b64 v220, v[2:3], v[4:5] offset0:8 offset1:10
	v_pk_mul_f32 v[2:3], v[10:11], v[140:141]
	v_pk_mul_f32 v[4:5], v[12:13], v[140:141]
	v_cvt_pk_bf16_f32 v18, v18, v19
	v_cvt_pk_bf16_f32 v19, v20, v21
	v_pk_mul_f32 v[20:21], v[30:31], v[140:141]
	v_pk_mul_f32 v[22:23], v[32:33], v[140:141]
	v_cvt_pk_bf16_f32 v2, v2, v3
	v_cvt_pk_bf16_f32 v3, v4, v5
	v_pk_mul_f32 v[4:5], v[14:15], v[140:141]
	v_pk_mul_f32 v[6:7], v[16:17], v[140:141]
	v_cvt_pk_bf16_f32 v20, v20, v21
	v_cvt_pk_bf16_f32 v21, v22, v23
	v_cvt_pk_bf16_f32 v4, v4, v5
	v_cvt_pk_bf16_f32 v5, v6, v7
	ds_write2_b64 v220, v[18:19], v[20:21] offset0:4 offset1:6
	ds_write2_b64 v220, v[2:3], v[4:5] offset0:12 offset1:14
	v_mov_b32_e32 v139, v1
	s_waitcnt lgkmcnt(0)
	v_lshl_add_u64 v[2:3], v[142:143], 0, v[138:139]
	global_load_dwordx4 v[38:41], v[2:3], off
	global_load_dwordx4 v[46:49], v[144:145], off offset:128
	global_load_dwordx4 v[42:45], v[146:147], off offset:128
	global_load_dword v0, v[156:157], off
	global_load_dword v62, v[158:159], off
	v_lshl_add_u64 v[2:3], v[160:161], 0, v[138:139]
	global_load_dwordx4 v[26:29], v[2:3], off
	global_load_dwordx4 v[34:37], v[162:163], off offset:128
	global_load_dwordx4 v[30:33], v[164:165], off offset:128
	global_load_dword v79, v[166:167], off
	global_load_dword v137, v[168:169], off
	v_lshl_add_u64 v[2:3], v[170:171], 0, v[138:139]
	global_load_dwordx4 v[14:17], v[2:3], off
	global_load_dwordx4 v[22:25], v[172:173], off offset:128
	global_load_dwordx4 v[18:21], v[174:175], off offset:128
	global_load_dword v73, v[176:177], off
	global_load_dword v72, v[178:179], off
	v_lshl_add_u64 v[2:3], v[180:181], 0, v[138:139]
	global_load_dwordx4 v[2:5], v[2:3], off
	s_nop 0
	global_load_dwordx4 v[10:13], v[182:183], off offset:128
	global_load_dwordx4 v[6:9], v[184:185], off offset:128
	global_load_dword v69, v[186:187], off
	global_load_dword v68, v[188:189], off
	ds_read_b128 v[50:53], v221
	ds_read_b32 v60, v131 offset:128
	s_andn2_b64 vcc, exec, s[26:27]
	s_waitcnt lgkmcnt(0)
	v_and_b32_e32 v75, 0xffff0000, v50
	v_lshlrev_b32_e32 v76, 16, v50
	s_waitcnt vmcnt(0)
	v_lshlrev_b32_e32 v114, 16, v38
	v_and_b32_e32 v115, 0xffff0000, v38
	v_mul_f32_e32 v38, 0xbfb8aa3b, v114
	v_exp_f32_e32 v38, v38
	v_max3_f32 v63, v60, v0, v62
	v_sub_f32_e32 v60, v60, v63
	v_sub_f32_e32 v0, v0, v63
	v_exp_f32_e32 v61, v60
	v_exp_f32_e32 v60, v0
	v_sub_f32_e32 v0, v62, v63
	v_exp_f32_e32 v0, v0
	v_add_f32_e32 v38, 1.0, v38
	v_add_f32_e32 v62, v61, v60
	v_rcp_f32_e32 v116, v38
	v_add_f32_e32 v62, v0, v62
	v_rcp_f32_e32 v62, v62
	v_mul_f32_e32 v38, 0xbfb8aa3b, v115
	v_exp_f32_e32 v38, v38
	v_and_b32_e32 v77, 0xffff0000, v46
	v_mul_f32_e32 v0, v0, v62
	v_pk_mul_f32 v[64:65], v[60:61], v[62:63] op_sel_hi:[1,0]
	v_lshlrev_b32_e32 v62, 16, v53
	v_and_b32_e32 v63, 0xffff0000, v49
	v_lshlrev_b32_e32 v60, 16, v49
	v_and_b32_e32 v61, 0xffff0000, v53
	v_pk_mul_f32 v[62:63], v[64:65], v[62:63] op_sel:[1,0] op_sel_hi:[0,1]
	v_add_f32_e32 v38, 1.0, v38
	v_pk_fma_f32 v[60:61], v[64:65], v[60:61], v[62:63]
	v_lshlrev_b32_e32 v62, 16, v45
	v_and_b32_e32 v63, 0xffff0000, v45
	v_rcp_f32_e32 v117, v38
	v_lshlrev_b32_e32 v38, 16, v39
	v_pk_fma_f32 v[60:61], v[0:1], v[62:63], v[60:61] op_sel_hi:[0,1,1]
	v_lshlrev_b32_e32 v62, 16, v41
	v_and_b32_e32 v63, 0xffff0000, v41
	v_mul_f32_e32 v41, 0xbfb8aa3b, v38
	v_exp_f32_e32 v41, v41
	v_and_b32_e32 v39, 0xffff0000, v39
	v_lshlrev_b32_e32 v74, 16, v46
	v_pk_mul_f32 v[76:77], v[64:65], v[76:77] op_sel:[1,0] op_sel_hi:[0,1]
	v_add_f32_e32 v41, 1.0, v41
	v_rcp_f32_e32 v50, v41
	v_mul_f32_e32 v41, 0xbfb8aa3b, v39
	v_exp_f32_e32 v41, v41
	v_pk_fma_f32 v[74:75], v[64:65], v[74:75], v[76:77]
	v_and_b32_e32 v77, 0xffff0000, v51
	v_lshlrev_b32_e32 v46, 16, v51
	v_add_f32_e32 v41, 1.0, v41
	v_rcp_f32_e32 v51, v41
	v_lshlrev_b32_e32 v76, 16, v47
	v_and_b32_e32 v47, 0xffff0000, v47
	v_pk_mul_f32 v[46:47], v[64:65], v[46:47] op_sel:[1,0] op_sel_hi:[0,1]
	v_lshlrev_b32_e32 v80, 16, v42
	v_and_b32_e32 v81, 0xffff0000, v42
	v_lshlrev_b32_e32 v42, 16, v43
	v_and_b32_e32 v43, 0xffff0000, v43
	v_pk_fma_f32 v[46:47], v[64:65], v[76:77], v[46:47]
	v_pk_mul_f32 v[38:39], v[50:51], v[38:39]
	v_pk_fma_f32 v[42:43], v[0:1], v[42:43], v[46:47] op_sel_hi:[0,1,1]
	v_pk_mul_f32 v[42:43], v[38:39], v[42:43]
	v_lshlrev_b32_e32 v38, 16, v48
	v_and_b32_e32 v47, 0xffff0000, v48
	v_lshlrev_b32_e32 v48, 16, v44
	v_and_b32_e32 v49, 0xffff0000, v44
	v_lshlrev_b32_e32 v44, 16, v40
	v_and_b32_e32 v45, 0xffff0000, v40
	v_mul_f32_e32 v40, 0xbfb8aa3b, v44
	v_mul_f32_e32 v41, 0xbfb8aa3b, v45
	v_exp_f32_e32 v40, v40
	v_exp_f32_e32 v41, v41
	v_lshlrev_b32_e32 v46, 16, v52
	v_and_b32_e32 v39, 0xffff0000, v52
	v_add_f32_e32 v40, 1.0, v40
	v_add_f32_e32 v41, 1.0, v41
	v_rcp_f32_e32 v40, v40
	v_rcp_f32_e32 v41, v41
	v_pk_fma_f32 v[74:75], v[0:1], v[80:81], v[74:75] op_sel_hi:[0,1,1]
	v_pk_mul_f32 v[114:115], v[116:117], v[114:115]
	v_and_b32_e32 v51, 0xffff0000, v34
	v_pk_mul_f32 v[40:41], v[40:41], v[44:45]
	v_pk_mul_f32 v[44:45], v[64:65], v[46:47] op_sel:[1,0] op_sel_hi:[0,1]
	v_pk_fma_f32 v[38:39], v[64:65], v[38:39], v[44:45]
	v_pk_mul_f32 v[74:75], v[114:115], v[74:75]
	v_pk_fma_f32 v[38:39], v[0:1], v[48:49], v[38:39] op_sel_hi:[0,1,1]
	v_mul_f32_e32 v0, 0xbfb8aa3b, v62
	v_exp_f32_e32 v0, v0
	v_pk_mul_f32 v[40:41], v[40:41], v[38:39]
	v_lshlrev_b32_e32 v48, 16, v34
	v_cvt_pk_bf16_f32 v40, v40, v41
	v_add_f32_e32 v0, 1.0, v0
	v_rcp_f32_e32 v38, v0
	v_mul_f32_e32 v0, 0xbfb8aa3b, v63
	v_exp_f32_e32 v0, v0
	v_lshlrev_b32_e32 v52, 16, v30
	v_and_b32_e32 v53, 0xffff0000, v30
	v_lshlrev_b32_e32 v30, 16, v31
	v_add_f32_e32 v0, 1.0, v0
	v_rcp_f32_e32 v39, v0
	v_and_b32_e32 v31, 0xffff0000, v31
	v_pk_mul_f32 v[38:39], v[38:39], v[62:63]
	s_nop 0
	v_pk_mul_f32 v[44:45], v[38:39], v[60:61]
	v_cvt_pk_bf16_f32 v38, v74, v75
	v_cvt_pk_bf16_f32 v39, v42, v43
	v_cvt_pk_bf16_f32 v41, v44, v45
	global_store_dwordx4 v[70:71], v[38:41], off offset:1664
	ds_read_b128 v[44:47], v78
	ds_read_b32 v0, v217 offset:128
	v_lshlrev_b32_e32 v60, 16, v26
	v_and_b32_e32 v61, 0xffff0000, v26
	v_mul_f32_e32 v26, 0xbfb8aa3b, v60
	v_exp_f32_e32 v26, v26
	s_waitcnt lgkmcnt(0)
	v_max3_f32 v40, v0, v79, v137
	v_sub_f32_e32 v0, v0, v40
	v_exp_f32_e32 v39, v0
	v_sub_f32_e32 v0, v79, v40
	v_exp_f32_e32 v38, v0
	v_sub_f32_e32 v0, v137, v40
	v_exp_f32_e32 v0, v0
	v_add_f32_e32 v26, 1.0, v26
	v_add_f32_e32 v40, v39, v38
	v_rcp_f32_e32 v62, v26
	v_add_f32_e32 v40, v0, v40
	v_rcp_f32_e32 v40, v40
	v_mul_f32_e32 v26, 0xbfb8aa3b, v61
	v_exp_f32_e32 v26, v26
	v_and_b32_e32 v49, 0xffff0000, v44
	v_mul_f32_e32 v0, v0, v40
	v_pk_mul_f32 v[42:43], v[38:39], v[40:41] op_sel_hi:[1,0]
	v_lshlrev_b32_e32 v40, 16, v47
	v_and_b32_e32 v41, 0xffff0000, v37
	v_lshlrev_b32_e32 v38, 16, v37
	v_and_b32_e32 v39, 0xffff0000, v47
	v_pk_mul_f32 v[40:41], v[42:43], v[40:41] op_sel:[1,0] op_sel_hi:[0,1]
	v_add_f32_e32 v26, 1.0, v26
	v_pk_fma_f32 v[38:39], v[42:43], v[38:39], v[40:41]
	v_lshlrev_b32_e32 v40, 16, v33
	v_and_b32_e32 v41, 0xffff0000, v33
	v_rcp_f32_e32 v63, v26
	v_lshlrev_b32_e32 v26, 16, v27
	v_pk_fma_f32 v[38:39], v[0:1], v[40:41], v[38:39] op_sel_hi:[0,1,1]
	v_lshlrev_b32_e32 v40, 16, v29
	v_and_b32_e32 v41, 0xffff0000, v29
	v_mul_f32_e32 v29, 0xbfb8aa3b, v26
	v_exp_f32_e32 v29, v29
	v_and_b32_e32 v27, 0xffff0000, v27
	v_lshlrev_b32_e32 v50, 16, v44
	v_pk_mul_f32 v[50:51], v[42:43], v[50:51] op_sel:[1,0] op_sel_hi:[0,1]
	v_add_f32_e32 v29, 1.0, v29
	v_rcp_f32_e32 v44, v29
	v_mul_f32_e32 v29, 0xbfb8aa3b, v27
	v_exp_f32_e32 v29, v29
	v_pk_fma_f32 v[48:49], v[42:43], v[48:49], v[50:51]
	v_and_b32_e32 v51, 0xffff0000, v45
	v_lshlrev_b32_e32 v34, 16, v45
	v_add_f32_e32 v29, 1.0, v29
	v_rcp_f32_e32 v45, v29
	v_lshlrev_b32_e32 v50, 16, v35
	v_and_b32_e32 v35, 0xffff0000, v35
	v_pk_mul_f32 v[34:35], v[42:43], v[34:35] op_sel:[1,0] op_sel_hi:[0,1]
	v_pk_fma_f32 v[34:35], v[42:43], v[50:51], v[34:35]
	v_pk_mul_f32 v[26:27], v[44:45], v[26:27]
	v_pk_fma_f32 v[30:31], v[0:1], v[30:31], v[34:35] op_sel_hi:[0,1,1]
	v_pk_mul_f32 v[30:31], v[26:27], v[30:31]
	v_lshlrev_b32_e32 v26, 16, v36
	v_and_b32_e32 v35, 0xffff0000, v36
	v_lshlrev_b32_e32 v36, 16, v32
	v_and_b32_e32 v37, 0xffff0000, v32
	v_lshlrev_b32_e32 v32, 16, v28
	v_and_b32_e32 v33, 0xffff0000, v28
	v_mul_f32_e32 v28, 0xbfb8aa3b, v32
	v_mul_f32_e32 v29, 0xbfb8aa3b, v33
	v_exp_f32_e32 v28, v28
	v_exp_f32_e32 v29, v29
	v_lshlrev_b32_e32 v34, 16, v46
	v_and_b32_e32 v27, 0xffff0000, v46
	v_add_f32_e32 v28, 1.0, v28
	v_add_f32_e32 v29, 1.0, v29
	v_rcp_f32_e32 v28, v28
	v_rcp_f32_e32 v29, v29
	v_pk_fma_f32 v[48:49], v[0:1], v[52:53], v[48:49] op_sel_hi:[0,1,1]
	v_pk_mul_f32 v[60:61], v[62:63], v[60:61]
	v_pk_mul_f32 v[28:29], v[28:29], v[32:33]
	v_pk_mul_f32 v[32:33], v[42:43], v[34:35] op_sel:[1,0] op_sel_hi:[0,1]
	v_pk_fma_f32 v[26:27], v[42:43], v[26:27], v[32:33]
	v_pk_mul_f32 v[48:49], v[60:61], v[48:49]
	v_pk_fma_f32 v[26:27], v[0:1], v[36:37], v[26:27] op_sel_hi:[0,1,1]
	v_mul_f32_e32 v0, 0xbfb8aa3b, v40
	v_exp_f32_e32 v0, v0
	v_pk_mul_f32 v[28:29], v[28:29], v[26:27]
	v_lshlrev_b32_e32 v42, 16, v14
	v_cvt_pk_bf16_f32 v28, v28, v29
	v_add_f32_e32 v0, 1.0, v0
	v_rcp_f32_e32 v26, v0
	v_mul_f32_e32 v0, 0xbfb8aa3b, v41
	v_exp_f32_e32 v0, v0
	v_and_b32_e32 v43, 0xffff0000, v14
	v_mul_f32_e32 v14, 0xbfb8aa3b, v42
	v_exp_f32_e32 v14, v14
	v_add_f32_e32 v0, 1.0, v0
	v_rcp_f32_e32 v27, v0
	v_lshlrev_b32_e32 v36, 16, v22
	v_add_f32_e32 v14, 1.0, v14
	v_rcp_f32_e32 v44, v14
	v_pk_mul_f32 v[26:27], v[26:27], v[40:41]
	v_mul_f32_e32 v14, 0xbfb8aa3b, v43
	v_pk_mul_f32 v[32:33], v[26:27], v[38:39]
	v_cvt_pk_bf16_f32 v26, v48, v49
	v_cvt_pk_bf16_f32 v27, v30, v31
	v_cvt_pk_bf16_f32 v29, v32, v33
	global_store_dwordx4 v[58:59], v[26:29], off offset:1664
	ds_read_b128 v[32:35], v66
	ds_read_b32 v0, v218 offset:128
	v_exp_f32_e32 v14, v14
	v_and_b32_e32 v39, 0xffff0000, v22
	v_lshlrev_b32_e32 v40, 16, v18
	s_waitcnt lgkmcnt(0)
	v_and_b32_e32 v37, 0xffff0000, v32
	v_max3_f32 v28, v0, v73, v72
	v_sub_f32_e32 v0, v0, v28
	v_exp_f32_e32 v27, v0
	v_sub_f32_e32 v0, v73, v28
	v_exp_f32_e32 v26, v0
	v_sub_f32_e32 v0, v72, v28
	v_exp_f32_e32 v0, v0
	v_add_f32_e32 v14, 1.0, v14
	v_add_f32_e32 v28, v27, v26
	v_rcp_f32_e32 v45, v14
	v_add_f32_e32 v28, v0, v28
	v_rcp_f32_e32 v28, v28
	v_lshlrev_b32_e32 v14, 16, v15
	v_and_b32_e32 v15, 0xffff0000, v15
	v_lshlrev_b32_e32 v38, 16, v32
	v_mul_f32_e32 v0, v0, v28
	v_pk_mul_f32 v[30:31], v[26:27], v[28:29] op_sel_hi:[1,0]
	v_lshlrev_b32_e32 v28, 16, v35
	v_and_b32_e32 v29, 0xffff0000, v25
	v_lshlrev_b32_e32 v26, 16, v25
	v_and_b32_e32 v27, 0xffff0000, v35
	v_pk_mul_f32 v[28:29], v[30:31], v[28:29] op_sel:[1,0] op_sel_hi:[0,1]
	v_pk_fma_f32 v[26:27], v[30:31], v[26:27], v[28:29]
	v_lshlrev_b32_e32 v28, 16, v21
	v_and_b32_e32 v29, 0xffff0000, v21
	v_pk_fma_f32 v[26:27], v[0:1], v[28:29], v[26:27] op_sel_hi:[0,1,1]
	v_lshlrev_b32_e32 v28, 16, v17
	v_and_b32_e32 v29, 0xffff0000, v17
	v_mul_f32_e32 v17, 0xbfb8aa3b, v14
	v_exp_f32_e32 v17, v17
	v_pk_mul_f32 v[38:39], v[30:31], v[38:39] op_sel:[1,0] op_sel_hi:[0,1]
	v_pk_fma_f32 v[36:37], v[30:31], v[36:37], v[38:39]
	v_and_b32_e32 v39, 0xffff0000, v33
	v_add_f32_e32 v17, 1.0, v17
	v_rcp_f32_e32 v32, v17
	v_mul_f32_e32 v17, 0xbfb8aa3b, v15
	v_exp_f32_e32 v17, v17
	v_lshlrev_b32_e32 v22, 16, v33
	v_lshlrev_b32_e32 v38, 16, v23
	v_and_b32_e32 v23, 0xffff0000, v23
	v_add_f32_e32 v17, 1.0, v17
	v_rcp_f32_e32 v33, v17
	v_pk_mul_f32 v[22:23], v[30:31], v[22:23] op_sel:[1,0] op_sel_hi:[0,1]
	v_and_b32_e32 v41, 0xffff0000, v18
	v_lshlrev_b32_e32 v18, 16, v19
	v_and_b32_e32 v19, 0xffff0000, v19
	v_pk_fma_f32 v[22:23], v[30:31], v[38:39], v[22:23]
	v_pk_mul_f32 v[14:15], v[32:33], v[14:15]
	v_pk_fma_f32 v[18:19], v[0:1], v[18:19], v[22:23] op_sel_hi:[0,1,1]
	v_pk_mul_f32 v[18:19], v[14:15], v[18:19]
	v_lshlrev_b32_e32 v14, 16, v24
	v_and_b32_e32 v23, 0xffff0000, v24
	v_lshlrev_b32_e32 v24, 16, v20
	v_and_b32_e32 v25, 0xffff0000, v20
	v_lshlrev_b32_e32 v20, 16, v16
	v_and_b32_e32 v21, 0xffff0000, v16
	v_mul_f32_e32 v16, 0xbfb8aa3b, v20
	v_mul_f32_e32 v17, 0xbfb8aa3b, v21
	v_exp_f32_e32 v16, v16
	v_exp_f32_e32 v17, v17
	v_lshlrev_b32_e32 v22, 16, v34
	v_and_b32_e32 v15, 0xffff0000, v34
	v_add_f32_e32 v16, 1.0, v16
	v_add_f32_e32 v17, 1.0, v17
	v_rcp_f32_e32 v16, v16
	v_rcp_f32_e32 v17, v17
	v_pk_fma_f32 v[36:37], v[0:1], v[40:41], v[36:37] op_sel_hi:[0,1,1]
	v_pk_mul_f32 v[42:43], v[44:45], v[42:43]
	v_pk_mul_f32 v[16:17], v[16:17], v[20:21]
	v_pk_mul_f32 v[20:21], v[30:31], v[22:23] op_sel:[1,0] op_sel_hi:[0,1]
	v_pk_fma_f32 v[14:15], v[30:31], v[14:15], v[20:21]
	v_pk_mul_f32 v[36:37], v[42:43], v[36:37]
	v_pk_fma_f32 v[14:15], v[0:1], v[24:25], v[14:15] op_sel_hi:[0,1,1]
	v_mul_f32_e32 v0, 0xbfb8aa3b, v28
	v_exp_f32_e32 v0, v0
	v_pk_mul_f32 v[16:17], v[16:17], v[14:15]
	v_lshlrev_b32_e32 v30, 16, v2
	v_cvt_pk_bf16_f32 v16, v16, v17
	v_add_f32_e32 v0, 1.0, v0
	v_rcp_f32_e32 v14, v0
	v_mul_f32_e32 v0, 0xbfb8aa3b, v29
	v_exp_f32_e32 v0, v0
	v_and_b32_e32 v31, 0xffff0000, v2
	v_mul_f32_e32 v2, 0xbfb8aa3b, v30
	v_exp_f32_e32 v2, v2
	v_add_f32_e32 v0, 1.0, v0
	v_rcp_f32_e32 v15, v0
	v_lshlrev_b32_e32 v24, 16, v10
	v_add_f32_e32 v2, 1.0, v2
	v_rcp_f32_e32 v32, v2
	v_pk_mul_f32 v[14:15], v[14:15], v[28:29]
	v_mul_f32_e32 v2, 0xbfb8aa3b, v31
	v_pk_mul_f32 v[20:21], v[14:15], v[26:27]
	v_cvt_pk_bf16_f32 v14, v36, v37
	v_cvt_pk_bf16_f32 v15, v18, v19
	v_cvt_pk_bf16_f32 v17, v20, v21
	global_store_dwordx4 v[54:55], v[14:17], off offset:1664
	ds_read_b128 v[20:23], v67
	ds_read_b32 v0, v219 offset:128
	v_exp_f32_e32 v2, v2
	v_and_b32_e32 v27, 0xffff0000, v10
	v_lshlrev_b32_e32 v28, 16, v6
	s_waitcnt lgkmcnt(0)
	v_and_b32_e32 v25, 0xffff0000, v20
	v_max3_f32 v16, v0, v69, v68
	v_sub_f32_e32 v0, v0, v16
	v_exp_f32_e32 v15, v0
	v_sub_f32_e32 v0, v69, v16
	v_exp_f32_e32 v14, v0
	v_sub_f32_e32 v0, v68, v16
	v_exp_f32_e32 v0, v0
	v_add_f32_e32 v2, 1.0, v2
	v_add_f32_e32 v16, v15, v14
	v_rcp_f32_e32 v33, v2
	v_add_f32_e32 v16, v0, v16
	v_rcp_f32_e32 v16, v16
	v_lshlrev_b32_e32 v2, 16, v3
	v_and_b32_e32 v3, 0xffff0000, v3
	v_lshlrev_b32_e32 v26, 16, v20
	v_mul_f32_e32 v0, v0, v16
	v_pk_mul_f32 v[18:19], v[14:15], v[16:17] op_sel_hi:[1,0]
	v_lshlrev_b32_e32 v16, 16, v23
	v_and_b32_e32 v17, 0xffff0000, v13
	v_lshlrev_b32_e32 v14, 16, v13
	v_and_b32_e32 v15, 0xffff0000, v23
	v_pk_mul_f32 v[16:17], v[18:19], v[16:17] op_sel:[1,0] op_sel_hi:[0,1]
	v_pk_fma_f32 v[14:15], v[18:19], v[14:15], v[16:17]
	v_lshlrev_b32_e32 v16, 16, v9
	v_and_b32_e32 v17, 0xffff0000, v9
	v_pk_fma_f32 v[14:15], v[0:1], v[16:17], v[14:15] op_sel_hi:[0,1,1]
	v_lshlrev_b32_e32 v16, 16, v5
	v_and_b32_e32 v17, 0xffff0000, v5
	v_mul_f32_e32 v5, 0xbfb8aa3b, v2
	v_exp_f32_e32 v5, v5
	v_pk_mul_f32 v[26:27], v[18:19], v[26:27] op_sel:[1,0] op_sel_hi:[0,1]
	v_pk_fma_f32 v[24:25], v[18:19], v[24:25], v[26:27]
	v_and_b32_e32 v27, 0xffff0000, v21
	v_add_f32_e32 v5, 1.0, v5
	v_rcp_f32_e32 v20, v5
	v_mul_f32_e32 v5, 0xbfb8aa3b, v3
	v_exp_f32_e32 v5, v5
	v_lshlrev_b32_e32 v10, 16, v21
	v_lshlrev_b32_e32 v26, 16, v11
	v_and_b32_e32 v11, 0xffff0000, v11
	v_add_f32_e32 v5, 1.0, v5
	v_rcp_f32_e32 v21, v5
	v_pk_mul_f32 v[10:11], v[18:19], v[10:11] op_sel:[1,0] op_sel_hi:[0,1]
	v_and_b32_e32 v29, 0xffff0000, v6
	v_lshlrev_b32_e32 v6, 16, v7
	v_and_b32_e32 v7, 0xffff0000, v7
	v_pk_fma_f32 v[10:11], v[18:19], v[26:27], v[10:11]
	v_pk_mul_f32 v[2:3], v[20:21], v[2:3]
	v_pk_fma_f32 v[6:7], v[0:1], v[6:7], v[10:11] op_sel_hi:[0,1,1]
	v_pk_mul_f32 v[6:7], v[2:3], v[6:7]
	v_lshlrev_b32_e32 v2, 16, v12
	v_and_b32_e32 v11, 0xffff0000, v12
	v_lshlrev_b32_e32 v12, 16, v8
	v_and_b32_e32 v13, 0xffff0000, v8
	v_lshlrev_b32_e32 v8, 16, v4
	v_and_b32_e32 v9, 0xffff0000, v4
	v_mul_f32_e32 v4, 0xbfb8aa3b, v8
	v_mul_f32_e32 v5, 0xbfb8aa3b, v9
	v_exp_f32_e32 v4, v4
	v_exp_f32_e32 v5, v5
	v_lshlrev_b32_e32 v10, 16, v22
	v_and_b32_e32 v3, 0xffff0000, v22
	v_add_f32_e32 v4, 1.0, v4
	v_add_f32_e32 v5, 1.0, v5
	v_rcp_f32_e32 v4, v4
	v_rcp_f32_e32 v5, v5
	v_pk_fma_f32 v[24:25], v[0:1], v[28:29], v[24:25] op_sel_hi:[0,1,1]
	v_pk_mul_f32 v[30:31], v[32:33], v[30:31]
	v_pk_mul_f32 v[4:5], v[4:5], v[8:9]
	v_pk_mul_f32 v[8:9], v[18:19], v[10:11] op_sel:[1,0] op_sel_hi:[0,1]
	v_pk_fma_f32 v[2:3], v[18:19], v[2:3], v[8:9]
	v_pk_mul_f32 v[24:25], v[30:31], v[24:25]
	v_pk_fma_f32 v[2:3], v[0:1], v[12:13], v[2:3] op_sel_hi:[0,1,1]
	v_mul_f32_e32 v0, 0xbfb8aa3b, v16
	v_exp_f32_e32 v0, v0
	v_pk_mul_f32 v[4:5], v[4:5], v[2:3]
	v_add_f32_e32 v0, 1.0, v0
	v_rcp_f32_e32 v2, v0
	v_mul_f32_e32 v0, 0xbfb8aa3b, v17
	v_exp_f32_e32 v0, v0
	v_cvt_pk_bf16_f32 v4, v4, v5
	v_add_f32_e32 v0, 1.0, v0
	v_rcp_f32_e32 v3, v0
	s_nop 0
	v_pk_mul_f32 v[2:3], v[2:3], v[16:17]
	s_nop 0
	v_pk_mul_f32 v[8:9], v[2:3], v[14:15]
	v_cvt_pk_bf16_f32 v2, v24, v25
	v_cvt_pk_bf16_f32 v3, v6, v7
	v_cvt_pk_bf16_f32 v5, v8, v9
	global_store_dwordx4 v[56:57], v[2:5], off offset:1664
	s_cbranch_vccz .LBB0_707

.LBB0_702:
	s_add_i32 s0, s48, 1
	s_cmp_lg_u32 s0, 6
	s_waitcnt lgkmcnt(0)
	s_barrier
	s_cselect_b32 s48, s0, 0
	s_add_i32 s53, s53, 1
	s_add_i32 s27, s27, 32
	s_cmpk_eq_i32 s27, 0x180
	s_cbranch_scc0 .LBB0_682
	v_and_b32_e32 v66, 64, v207
	v_xor_b32_e32 v0, 32, v207
	v_add_u32_e32 v216, 64, v66
	v_cmp_lt_i32_e32 vcc, v0, v216
	s_add_i32 s29, s29, s42
	s_cmpk_gt_i32 s29, 0x2ff
	v_cndmask_b32_e32 v0, v207, v0, vcc
	v_lshlrev_b32_e32 v215, 2, v0
	ds_bpermute_b32 v0, v215, v114
	s_cselect_b64 s[26:27], -1, 0
	s_cmpk_lt_i32 s29, 0x300
	s_cbranch_scc0 .LBB0_705
	s_mul_hi_i32 s0, s29, 0x2aaaaaab
	s_lshr_b32 s1, s0, 31
	s_ashr_i32 s0, s0, 3
	s_add_i32 s0, s0, s1
	s_mul_i32 s1, s0, 48
	s_sub_i32 s14, s29, s1
	s_lshl_b32 s1, s14, 4
	s_lshl_b32 s14, s14, 8
	s_and_b32 s1, s1, 0xffffff80
	s_and_b32 s14, s14, 0x700
	s_add_i32 s98, s1, 0xc00
	s_ashr_i32 s1, s0, 31
	v_add_u32_e32 v66, s14, v127
	s_lshl_b64 s[0:1], s[0:1], 11
	v_ashrrev_i32_e32 v67, 31, v66
	v_lshl_add_u64 v[66:67], s[0:1], 0, v[66:67]
	v_mov_b64_e32 v[68:69], s[12:13]
	v_mad_u64_u32 v[68:69], s[0:1], v66, s43, v[68:69]
	v_mad_i32_i24 v69, v67, s43, v69
	v_lshl_add_u64 v[66:67], s[98:99], 1, v[68:69]
	v_lshl_add_u64 v[66:67], v[66:67], 0, v[120:121]
	global_load_dwordx4 v[82:85], v[66:67], off
	global_load_dwordx4 v[86:89], v[66:67], off offset:32
	global_load_dwordx4 v[90:93], v[66:67], off offset:64
	global_load_dwordx4 v[94:97], v[66:67], off offset:96
	global_load_dwordx4 v[98:101], v[66:67], off offset:128
	global_load_dwordx4 v[102:105], v[66:67], off offset:160
	global_load_dwordx4 v[106:109], v[66:67], off offset:192
	global_load_dwordx4 v[110:113], v[66:67], off offset:224

.LBB0_775:
	v_lshl_add_u32 v146, s56, 8, v142
	v_lshl_or_b32 v140, s55, 8, v144
	v_ashrrev_i32_e32 v147, 31, v146
	v_ashrrev_i32_e32 v141, 31, v140
	v_lshlrev_b64 v[156:157], 12, v[146:147]
	v_lshl_add_u64 v[156:157], s[8:9], 0, v[156:157]
	v_lshlrev_b64 v[158:159], 1, v[140:141]
	v_lshl_add_u64 v[140:141], v[156:157], 0, v[158:159]
	v_cvt_pk_bf16_f32 v126, v126, v127
	v_cvt_pk_bf16_f32 v127, v128, v129
	v_cvt_pk_bf16_f32 v128, v122, v123
	v_cvt_pk_bf16_f32 v129, v124, v125
	global_store_dwordx4 v[140:141], v[126:129], off
	v_cvt_pk_bf16_f32 v114, v114, v115
	v_cvt_pk_bf16_f32 v115, v116, v117
	v_cvt_pk_bf16_f32 v116, v106, v107
	v_or_b32_e32 v106, 16, v146
	v_ashrrev_i32_e32 v107, 31, v106
	v_lshlrev_b64 v[106:107], 12, v[106:107]
	v_lshl_add_u64 v[106:107], s[8:9], 0, v[106:107]
	v_cvt_pk_bf16_f32 v117, v108, v109
	global_store_dwordx4 v[140:141], v[114:117], off offset:256
	s_mov_b64 s[0:1], 0x80000
	v_readlane_b32 s60, v254, 37
	v_lshl_add_u64 v[114:115], v[106:107], 0, v[158:159]
	v_cvt_pk_bf16_f32 v106, v118, v119
	v_cvt_pk_bf16_f32 v107, v120, v121
	v_cvt_pk_bf16_f32 v108, v110, v111
	v_cvt_pk_bf16_f32 v109, v112, v113
	global_store_dwordx4 v[114:115], v[106:109], off
	v_cvt_pk_bf16_f32 v98, v98, v99
	v_cvt_pk_bf16_f32 v99, v100, v101
	v_cvt_pk_bf16_f32 v100, v90, v91
	v_or_b32_e32 v90, 32, v146
	v_ashrrev_i32_e32 v91, 31, v90
	v_lshlrev_b64 v[90:91], 12, v[90:91]
	v_lshl_add_u64 v[90:91], s[8:9], 0, v[90:91]
	v_cvt_pk_bf16_f32 v101, v92, v93
	global_store_dwordx4 v[114:115], v[98:101], off offset:256
	v_readlane_b32 s61, v254, 38
	s_nop 0
	v_lshl_add_u64 v[98:99], v[90:91], 0, v[158:159]
	v_cvt_pk_bf16_f32 v90, v102, v103
	v_cvt_pk_bf16_f32 v91, v104, v105
	v_cvt_pk_bf16_f32 v92, v94, v95
	v_cvt_pk_bf16_f32 v93, v96, v97
	global_store_dwordx4 v[98:99], v[90:93], off
	v_cvt_pk_bf16_f32 v82, v82, v83
	v_cvt_pk_bf16_f32 v83, v84, v85
	v_cvt_pk_bf16_f32 v84, v74, v75
	v_or_b32_e32 v74, 48, v146
	v_ashrrev_i32_e32 v75, 31, v74
	v_lshlrev_b64 v[74:75], 12, v[74:75]
	v_lshl_add_u64 v[74:75], s[8:9], 0, v[74:75]
	v_cvt_pk_bf16_f32 v85, v76, v77
	global_store_dwordx4 v[98:99], v[82:85], off offset:256
	s_nop 1
	v_lshl_add_u64 v[82:83], v[74:75], 0, v[158:159]
	v_cvt_pk_bf16_f32 v74, v86, v87
	v_cvt_pk_bf16_f32 v75, v88, v89
	v_cvt_pk_bf16_f32 v76, v78, v79
	v_cvt_pk_bf16_f32 v77, v80, v81
	global_store_dwordx4 v[82:83], v[74:77], off
	v_cvt_pk_bf16_f32 v70, v70, v71
	v_cvt_pk_bf16_f32 v71, v72, v73
	v_cvt_pk_bf16_f32 v72, v66, v67
	v_lshl_add_u64 v[66:67], v[140:141], 0, s[0:1]
	s_mov_b32 s0, 0x80000
	v_cvt_pk_bf16_f32 v73, v68, v69
	global_store_dwordx4 v[82:83], v[70:73], off offset:256
	v_cvt_pk_bf16_f32 v62, v62, v63
	v_cvt_pk_bf16_f32 v63, v64, v65
	v_cvt_pk_bf16_f32 v64, v58, v59
	v_add_co_u32_e32 v58, vcc, s0, v140
	v_cvt_pk_bf16_f32 v65, v60, v61
	s_mov_b64 s[0:1], 0x90000
	s_nop 0
	v_addc_co_u32_e32 v59, vcc, 0, v141, vcc
	global_store_dwordx4 v[58:59], v[62:65], off
	v_cvt_pk_bf16_f32 v50, v50, v51
	v_cvt_pk_bf16_f32 v51, v52, v53
	v_cvt_pk_bf16_f32 v52, v42, v43
	v_cvt_pk_bf16_f32 v53, v44, v45
	global_store_dwordx4 v[66:67], v[50:53], off offset:256
	v_cvt_pk_bf16_f32 v42, v54, v55
	v_cvt_pk_bf16_f32 v43, v56, v57
	v_cvt_pk_bf16_f32 v44, v46, v47
	v_cvt_pk_bf16_f32 v45, v48, v49
	s_nop 1
	v_lshl_add_u64 v[50:51], v[140:141], 0, s[0:1]
	s_mov_b32 s0, 0x90000
	v_add_co_u32_e32 v46, vcc, s0, v140
	s_mov_b64 s[0:1], 0xa0000
	s_nop 0
	v_addc_co_u32_e32 v47, vcc, 0, v141, vcc
	global_store_dwordx4 v[46:47], v[42:45], off
	v_cvt_pk_bf16_f32 v34, v34, v35
	v_cvt_pk_bf16_f32 v35, v36, v37
	v_cvt_pk_bf16_f32 v36, v26, v27
	v_cvt_pk_bf16_f32 v37, v28, v29
	global_store_dwordx4 v[50:51], v[34:37], off offset:256
	v_cvt_pk_bf16_f32 v26, v38, v39
	v_cvt_pk_bf16_f32 v27, v40, v41
	v_cvt_pk_bf16_f32 v28, v30, v31
	v_cvt_pk_bf16_f32 v29, v32, v33
	s_nop 1
	v_lshl_add_u64 v[34:35], v[140:141], 0, s[0:1]
	s_mov_b32 s0, 0xa0000
	v_add_co_u32_e32 v30, vcc, s0, v140
	s_mov_b64 s[0:1], 0xb0000
	s_nop 0
	v_addc_co_u32_e32 v31, vcc, 0, v141, vcc
	global_store_dwordx4 v[30:31], v[26:29], off
	v_cvt_pk_bf16_f32 v18, v18, v19
	v_cvt_pk_bf16_f32 v19, v20, v21
	v_cvt_pk_bf16_f32 v20, v10, v11
	v_cvt_pk_bf16_f32 v21, v12, v13
	global_store_dwordx4 v[34:35], v[18:21], off offset:256
	v_cvt_pk_bf16_f32 v10, v22, v23
	v_cvt_pk_bf16_f32 v11, v24, v25
	v_cvt_pk_bf16_f32 v12, v14, v15
	v_cvt_pk_bf16_f32 v13, v16, v17
	s_nop 1
	v_lshl_add_u64 v[18:19], v[140:141], 0, s[0:1]
	s_mov_b32 s0, 0xb0000
	v_add_co_u32_e32 v14, vcc, s0, v140
	s_mov_b64 s[0:1], -1
	s_nop 0
	v_addc_co_u32_e32 v15, vcc, 0, v141, vcc
	s_andn2_b64 vcc, exec, s[6:7]
	global_store_dwordx4 v[14:15], v[10:13], off
	v_cvt_pk_bf16_f32 v6, v6, v7
	v_cvt_pk_bf16_f32 v7, v8, v9
	v_cvt_pk_bf16_f32 v8, v2, v3
	v_cvt_pk_bf16_f32 v9, v4, v5
	global_store_dwordx4 v[18:19], v[6:9], off offset:256
	s_cbranch_vccnz .LBB0_764
	s_andn2_b64 vcc, exec, s[4:5]
	s_cbranch_vccnz .LBB0_763
	s_barrier
	s_branch .LBB0_763

.LBB0_834:
	s_add_i32 s8, s68, s0
	v_add_co_u32_e32 v12, vcc, 0x8000000, v100
	s_ashr_i32 s9, s8, 31
	v_lshl_add_u64 v[10:11], s[16:17], 0, v[80:81]
	v_addc_co_u32_e32 v13, vcc, 0, v101, vcc
	s_lshl_b64 s[10:11], s[8:9], 12
	global_load_dwordx2 v[8:9], v[12:13], off nt
	global_load_dwordx4 v[2:5], v[10:11], off nt
	global_load_dwordx2 v[46:47], v[12:13], off offset:512 nt
	global_load_dwordx4 v[30:33], v[10:11], off offset:1024 nt
	global_load_dwordx2 v[48:49], v[12:13], off offset:1024 nt
	global_load_dwordx4 v[34:37], v[10:11], off offset:2048 nt
	global_load_dwordx2 v[58:59], v[12:13], off offset:1536 nt
	global_load_dwordx4 v[26:29], v[10:11], off offset:3072 nt
	global_load_dwordx2 v[60:61], v[12:13], off offset:2048 nt
	v_add_co_u32_e32 v10, vcc, s71, v10
	v_lshl_add_u64 v[6:7], v[84:85], 0, s[10:11]
	s_nop 0
	v_addc_co_u32_e32 v11, vcc, 0, v11, vcc
	s_lshl_b64 s[14:15], s[8:9], 13
	global_load_dwordx4 v[22:25], v[10:11], off nt
	global_load_dwordx2 v[110:111], v[12:13], off offset:2560 nt
	global_load_dwordx4 v[14:17], v[10:11], off offset:1024 nt
	global_load_dwordx2 v[108:109], v[12:13], off offset:3072 nt
	global_load_dwordx4 v[18:21], v[10:11], off offset:2048 nt
	global_load_dwordx2 v[106:107], v[12:13], off offset:3584 nt
	global_load_dwordx4 v[62:65], v[10:11], off offset:3072 nt
	v_lshl_add_u64 v[10:11], v[82:83], 0, s[14:15]
	global_load_dwordx2 v[50:51], v[6:7], off nt
	global_load_dwordx4 v[124:127], v[10:11], off nt
	global_load_dwordx2 v[104:105], v[6:7], off offset:512 nt
	global_load_dwordx4 v[128:131], v[10:11], off offset:1024 nt
	global_load_dwordx2 v[52:53], v[6:7], off offset:1024 nt
	global_load_dwordx4 v[42:45], v[10:11], off offset:2048 nt
	global_load_dwordx2 v[102:103], v[6:7], off offset:1536 nt
	global_load_dwordx4 v[54:57], v[10:11], off offset:3072 nt
	global_load_dwordx2 v[118:119], v[6:7], off offset:2048 nt
	v_add_co_u32_e32 v10, vcc, s71, v10
	s_add_i32 s0, s0, s58
	s_nop 0
	v_addc_co_u32_e32 v11, vcc, 0, v11, vcc
	global_load_dwordx4 v[38:41], v[10:11], off nt
	global_load_dwordx2 v[116:117], v[6:7], off offset:2560 nt
	global_load_dwordx4 v[74:77], v[10:11], off offset:1024 nt
	global_load_dwordx2 v[114:115], v[6:7], off offset:3072 nt
	global_load_dwordx4 v[70:73], v[10:11], off offset:2048 nt
	global_load_dwordx2 v[112:113], v[6:7], off offset:3584 nt
	global_load_dwordx4 v[66:69], v[10:11], off offset:3072 nt
	s_waitcnt vmcnt(0) lgkmcnt(0)
	v_lshlrev_b32_e32 v6, 16, v8
	v_and_b32_e32 v7, 0xffff0000, v8
	v_pk_add_f32 v[10:11], v[2:3], v[6:7]
	v_lshlrev_b32_e32 v2, 16, v9
	v_and_b32_e32 v3, 0xffff0000, v9
	v_pk_add_f32 v[12:13], v[4:5], v[2:3]
	v_lshlrev_b32_e32 v2, 16, v50
	v_and_b32_e32 v3, 0xffff0000, v50
	v_pk_add_f32 v[6:7], v[124:125], v[2:3]
	v_lshlrev_b32_e32 v2, 16, v51
	v_and_b32_e32 v3, 0xffff0000, v51
	v_pk_add_f32 v[8:9], v[126:127], v[2:3]
	v_lshlrev_b32_e32 v2, 16, v104
	v_and_b32_e32 v3, 0xffff0000, v104
	v_lshlrev_b32_e32 v50, 16, v46
	v_and_b32_e32 v51, 0xffff0000, v46
	v_pk_add_f32 v[2:3], v[128:129], v[2:3]
	v_lshlrev_b32_e32 v4, 16, v105
	v_and_b32_e32 v5, 0xffff0000, v105
	v_pk_add_f32 v[30:31], v[30:31], v[50:51]
	v_and_b32_e32 v51, 0xffff0000, v47
	v_lshlrev_b32_e32 v50, 16, v47
	v_pk_add_f32 v[4:5], v[130:131], v[4:5]
	v_pk_add_f32 v[32:33], v[32:33], v[50:51]
	v_mov_b32_e32 v50, v7
	v_mov_b32_e32 v51, v3
	v_mov_b32_e32 v46, v6
	v_mov_b32_e32 v47, v2
	v_pk_mul_f32 v[50:51], v[50:51], v[50:51]
	v_mov_b32_e32 v130, v9
	v_mov_b32_e32 v131, v5
	v_pk_fma_f32 v[46:47], v[46:47], v[46:47], v[50:51]
	v_mov_b32_e32 v50, v8
	v_mov_b32_e32 v51, v4
	v_pk_mul_f32 v[130:131], v[130:131], v[130:131]
	v_pk_mul_f32 v[124:125], v[10:11], v[10:11]
	v_pk_fma_f32 v[50:51], v[50:51], v[50:51], v[130:131]
	v_pk_mul_f32 v[126:127], v[12:13], v[12:13]
	v_pk_add_f32 v[46:47], v[46:47], v[50:51]
	v_mul_f32_e32 v0, v31, v31
	v_pk_add_f32 v[130:131], v[46:47], v[46:47] op_sel:[0,1] op_sel_hi:[1,0]
	v_lshlrev_b32_e32 v46, 16, v48
	v_and_b32_e32 v47, 0xffff0000, v48
	v_pk_add_f32 v[46:47], v[34:35], v[46:47]
	v_lshlrev_b32_e32 v34, 16, v49
	v_and_b32_e32 v35, 0xffff0000, v49
	v_pk_add_f32 v[48:49], v[36:37], v[34:35]
	v_lshlrev_b32_e32 v34, 16, v52
	v_and_b32_e32 v35, 0xffff0000, v52
	v_pk_mov_b32 v[36:37], v[124:125], v[46:47] op_sel:[1,0]
	v_pk_add_f32 v[50:51], v[42:43], v[34:35]
	v_pk_fma_f32 v[42:43], v[10:11], v[10:11], v[36:37]
	v_pk_mul_f32 v[36:37], v[46:47], v[36:37] op_sel_hi:[0,1]
	v_pk_fma_f32 v[104:105], v[30:31], v[30:31], v[0:1] op_sel_hi:[1,1,0]
	v_mul_f32_e32 v0, v33, v33
	v_lshlrev_b32_e32 v34, 16, v53
	v_and_b32_e32 v35, 0xffff0000, v53
	v_mov_b32_e32 v43, v37
	v_mov_b32_e32 v36, v127
	v_mov_b32_e32 v37, v47
	v_pk_fma_f32 v[128:129], v[32:33], v[32:33], v[0:1] op_sel_hi:[1,1,0]
	v_pk_add_f32 v[52:53], v[44:45], v[34:35]
	v_pk_mul_f32 v[34:35], v[48:49], v[48:49]
	v_pk_fma_f32 v[36:37], v[12:13], v[12:13], v[36:37]
	v_pk_mul_f32 v[44:45], v[46:47], v[46:47]
	v_mov_b32_e32 v105, v35
	v_mov_b32_e32 v37, v45
	v_mov_b32_e32 v129, v34
	v_pk_add_f32 v[36:37], v[42:43], v[36:37]
	v_pk_add_f32 v[34:35], v[104:105], v[128:129]
	v_mov_b32_e32 v42, v27
	v_pk_add_f32 v[34:35], v[36:37], v[34:35]
	v_mov_b32_e32 v36, v51
	v_mov_b32_e32 v37, v53
	v_pk_add_f32 v[124:125], v[34:35], v[34:35] op_sel:[0,1] op_sel_hi:[1,0]
	v_mov_b32_e32 v34, v50
	v_mov_b32_e32 v35, v52
	v_pk_mul_f32 v[36:37], v[36:37], v[36:37]
	v_mov_b32_e32 v43, v28
	v_pk_fma_f32 v[34:35], v[34:35], v[34:35], v[36:37]
	v_lshlrev_b32_e32 v36, 16, v102
	v_and_b32_e32 v37, 0xffff0000, v102
	v_pk_add_f32 v[54:55], v[54:55], v[36:37]
	v_lshlrev_b32_e32 v36, 16, v103
	v_and_b32_e32 v37, 0xffff0000, v103
	v_pk_add_f32 v[56:57], v[56:57], v[36:37]
	v_and_b32_e32 v36, 0xffff0000, v58
	v_lshlrev_b32_e32 v37, 16, v59
	v_pk_add_f32 v[102:103], v[42:43], v[36:37]
	v_lshlrev_b32_e32 v36, 16, v58
	v_and_b32_e32 v37, 0xffff0000, v59
	v_mov_b32_e32 v27, v29
	v_pk_add_f32 v[104:105], v[26:27], v[36:37]
	v_lshlrev_b32_e32 v36, 16, v118
	v_and_b32_e32 v37, 0xffff0000, v118
	v_pk_add_f32 v[42:43], v[38:39], v[36:37]
	v_lshlrev_b32_e32 v36, 16, v119
	v_and_b32_e32 v37, 0xffff0000, v119
	v_pk_mul_f32 v[26:27], v[102:103], v[102:103]
	v_mul_f32_e32 v0, v55, v55
	v_pk_add_f32 v[44:45], v[40:41], v[36:37]
	v_lshlrev_b32_e32 v36, 16, v60
	v_and_b32_e32 v37, 0xffff0000, v60
	v_pk_fma_f32 v[126:127], v[104:105], v[104:105], v[26:27]
	v_pk_fma_f32 v[26:27], v[54:55], v[54:55], v[0:1] op_sel_hi:[1,1,0]
	v_mul_f32_e32 v0, v57, v57
	v_pk_add_f32 v[58:59], v[22:23], v[36:37]
	v_and_b32_e32 v37, 0xffff0000, v61
	v_lshlrev_b32_e32 v36, 16, v61
	v_pk_add_f32 v[34:35], v[34:35], v[34:35] op_sel:[0,1] op_sel_hi:[1,0]
	v_pk_fma_f32 v[28:29], v[56:57], v[56:57], v[0:1] op_sel_hi:[1,1,0]
	v_pk_add_f32 v[60:61], v[24:25], v[36:37]
	v_pk_mul_f32 v[24:25], v[42:43], v[42:43]
	v_pk_mul_f32 v[36:37], v[44:45], v[44:45]
	v_mov_b32_e32 v131, v24
	v_mov_b32_e32 v35, v25
	v_mov_b32_e32 v27, v36
	v_mov_b32_e32 v29, v37
	v_pk_add_f32 v[24:25], v[130:131], v[34:35]
	v_pk_add_f32 v[26:27], v[26:27], v[28:29]
	v_mul_f32_e32 v0, v59, v59
	v_pk_add_f32 v[24:25], v[24:25], v[26:27]
	v_pk_fma_f32 v[22:23], v[58:59], v[58:59], v[0:1] op_sel_hi:[1,1,0]
	v_pk_add_f32 v[128:129], v[24:25], v[24:25] op_sel:[0,1] op_sel_hi:[1,0]
	v_lshlrev_b32_e32 v24, 16, v110
	v_and_b32_e32 v25, 0xffff0000, v110
	v_pk_add_f32 v[38:39], v[14:15], v[24:25]
	v_lshlrev_b32_e32 v14, 16, v111
	v_and_b32_e32 v15, 0xffff0000, v111
	v_pk_add_f32 v[40:41], v[16:17], v[14:15]
	v_lshlrev_b32_e32 v14, 16, v116
	v_and_b32_e32 v15, 0xffff0000, v116
	v_lshlrev_b32_e32 v24, 16, v108
	v_and_b32_e32 v25, 0xffff0000, v108
	v_pk_add_f32 v[34:35], v[74:75], v[14:15]
	v_lshlrev_b32_e32 v14, 16, v117
	v_and_b32_e32 v15, 0xffff0000, v117
	v_pk_add_f32 v[26:27], v[18:19], v[24:25]
	v_and_b32_e32 v19, 0xffff0000, v109
	v_lshlrev_b32_e32 v18, 16, v109
	v_mul_f32_e32 v0, v61, v61
	v_pk_add_f32 v[36:37], v[76:77], v[14:15]
	v_pk_add_f32 v[28:29], v[20:21], v[18:19]
	v_lshlrev_b32_e32 v18, 16, v107
	v_and_b32_e32 v19, 0xffff0000, v107
	v_pk_fma_f32 v[118:119], v[60:61], v[60:61], v[0:1] op_sel_hi:[1,1,0]
	v_mov_b32_e32 v16, v35
	v_mov_b32_e32 v17, v37
	v_pk_add_f32 v[24:25], v[64:65], v[18:19]
	v_lshlrev_b32_e32 v18, 16, v112
	v_and_b32_e32 v19, 0xffff0000, v112
	v_pk_mul_f32 v[74:75], v[38:39], v[38:39]
	v_mov_b32_e32 v14, v34
	v_mov_b32_e32 v15, v36
	v_pk_mul_f32 v[16:17], v[16:17], v[16:17]
	v_lshlrev_b32_e32 v119, 16, v106
	v_pk_add_f32 v[18:19], v[66:67], v[18:19]
	v_pk_add_f32 v[66:67], v[126:127], v[126:127] op_sel:[0,1] op_sel_hi:[1,0]
	v_pk_mul_f32 v[76:77], v[40:41], v[40:41]
	v_pk_fma_f32 v[14:15], v[14:15], v[14:15], v[16:17]
	v_and_b32_e32 v117, 0xffff0000, v106
	v_lshlrev_b32_e32 v20, 16, v113
	v_and_b32_e32 v21, 0xffff0000, v113
	v_mov_b32_e32 v125, v62
	v_mov_b32_e32 v67, v119
	v_mov_b32_e32 v23, v62
	v_mov_b32_e32 v62, v74
	v_mov_b32_e32 v116, v75
	v_pk_add_f32 v[110:111], v[14:15], v[14:15] op_sel:[0,1] op_sel_hi:[1,0]
	v_lshlrev_b32_e32 v14, 16, v114
	v_and_b32_e32 v15, 0xffff0000, v114
	v_mul_f32_e32 v0, v27, v27
	v_pk_add_f32 v[20:21], v[68:69], v[20:21]
	v_pk_add_f32 v[66:67], v[124:125], v[66:67]
	v_pk_add_f32 v[68:69], v[22:23], v[118:119]
	v_pk_add_f32 v[22:23], v[62:63], v[116:117]
	v_mov_b32_e32 v62, v77
	v_mov_b32_e32 v77, v117
	v_pk_add_f32 v[14:15], v[70:71], v[14:15]
	v_lshlrev_b32_e32 v16, 16, v115
	v_and_b32_e32 v17, 0xffff0000, v115
	v_pk_fma_f32 v[70:71], v[26:27], v[26:27], v[0:1] op_sel_hi:[1,1,0]
	v_mul_f32_e32 v0, v29, v29
	v_pk_add_f32 v[62:63], v[62:63], v[76:77]
	v_pk_add_f32 v[74:75], v[66:67], v[68:69]
	v_pk_mul_f32 v[68:69], v[66:67], v[68:69]
	v_pk_add_f32 v[16:17], v[72:73], v[16:17]
	v_pk_fma_f32 v[72:73], v[28:29], v[28:29], v[0:1] op_sel_hi:[1,1,0]
	v_pk_mul_f32 v[64:65], v[24:25], v[24:25]
	v_mov_b32_e32 v75, v69
	v_pk_add_f32 v[68:69], v[22:23], v[62:63]
	v_pk_mul_f32 v[62:63], v[22:23], v[62:63]
	v_mov_b32_e32 v71, v65
	v_mov_b32_e32 v69, v63
	v_mov_b32_e32 v73, v64
	v_mul_f32_e32 v0, v15, v15
	v_pk_add_f32 v[62:63], v[74:75], v[68:69]
	v_pk_add_f32 v[64:65], v[70:71], v[72:73]
	v_pk_fma_f32 v[108:109], v[14:15], v[14:15], v[0:1] op_sel_hi:[1,1,0]
	v_mul_f32_e32 v0, v17, v17
	v_pk_add_f32 v[62:63], v[62:63], v[64:65]
	v_pk_fma_f32 v[114:115], v[16:17], v[16:17], v[0:1] op_sel_hi:[1,1,0]
	v_add_f32_e32 v0, v62, v63
	v_pk_mul_f32 v[62:63], v[18:19], v[18:19]
	v_pk_mul_f32 v[64:65], v[20:21], v[20:21]
	v_mov_b32_e32 v129, v62
	v_mov_b32_e32 v111, v63
	v_mov_b32_e32 v109, v64
	v_mov_b32_e32 v115, v65
	v_pk_add_f32 v[62:63], v[128:129], v[110:111]
	v_pk_add_f32 v[64:65], v[108:109], v[114:115]
	v_lshl_add_u64 v[72:73], s[24:25], 0, v[80:81]
	v_pk_add_f32 v[62:63], v[62:63], v[64:65]
	v_lshl_add_u64 v[70:71], v[88:89], 0, s[14:15]
	v_add_f32_e32 v22, v62, v63
	ds_bpermute_b32 v62, v79, v0
	v_lshl_add_u64 v[68:69], v[90:91], 0, s[10:11]
	s_add_u32 s24, s24, s78
	s_addc_u32 s25, s25, s79
	s_add_u32 s16, s16, s78
	s_waitcnt lgkmcnt(0)
	v_add_f32_e32 v0, v0, v62
	ds_bpermute_b32 v62, v120, v0
	s_addc_u32 s17, s17, s79
	s_cmpk_gt_i32 s0, 0x7fff
	s_waitcnt lgkmcnt(0)
	v_add_f32_e32 v0, v0, v62
	ds_bpermute_b32 v62, v121, v0
	s_waitcnt lgkmcnt(0)
	v_add_f32_e32 v0, v0, v62
	ds_bpermute_b32 v62, v122, v0
	s_waitcnt lgkmcnt(0)
	v_add_f32_e32 v0, v0, v62
	ds_bpermute_b32 v62, v123, v0
	s_waitcnt lgkmcnt(0)
	v_add_f32_e32 v0, v0, v62
	ds_bpermute_b32 v62, v215, v0
	s_waitcnt lgkmcnt(0)
	v_add_f32_e32 v0, v0, v62
	v_fmamk_f32 v0, v0, 0x3a000000, v208
	v_cmp_gt_f32_e32 vcc, s26, v0
	v_mul_f32_e32 v62, 0x4f800000, v0
	s_nop 0
	v_cndmask_b32_e32 v0, v0, v62, vcc
	v_sqrt_f32_e32 v62, v0
	s_nop 0
	v_add_u32_e32 v63, -1, v62
	v_fma_f32 v64, -v63, v62, v0
	v_cmp_ge_f32_e64 s[8:9], 0, v64
	v_add_u32_e32 v64, 1, v62
	s_nop 0
	v_cndmask_b32_e64 v63, v62, v63, s[8:9]
	v_fma_f32 v62, -v64, v62, v0
	v_cmp_lt_f32_e64 s[8:9], 0, v62
	s_nop 1
	v_cndmask_b32_e64 v62, v63, v64, s[8:9]
	v_mul_f32_e32 v63, 0x37800000, v62
	v_cndmask_b32_e32 v62, v62, v63, vcc
	v_cmp_class_f32_e32 vcc, v0, v209
	s_nop 1
	v_cndmask_b32_e32 v0, v62, v0, vcc
	v_div_scale_f32 v62, s[8:9], v0, v0, 1.0
	v_rcp_f32_e32 v63, v62
	s_nop 0
	v_fma_f32 v64, -v62, v63, 1.0
	v_fmac_f32_e32 v63, v64, v63
	v_div_scale_f32 v64, vcc, 1.0, v0, 1.0
	v_mul_f32_e32 v65, v64, v63
	v_fma_f32 v66, -v62, v65, v64
	v_fmac_f32_e32 v65, v66, v63
	v_fma_f32 v62, -v62, v65, v64
	v_div_fmas_f32 v62, v62, v63, v65
	v_div_fixup_f32 v0, v62, v0, 1.0
	ds_bpermute_b32 v62, v79, v22
	s_waitcnt lgkmcnt(0)
	v_add_f32_e32 v22, v22, v62
	ds_bpermute_b32 v62, v120, v22
	s_waitcnt lgkmcnt(0)
	v_add_f32_e32 v22, v22, v62
	ds_bpermute_b32 v62, v121, v22
	s_waitcnt lgkmcnt(0)
	v_add_f32_e32 v22, v22, v62
	ds_bpermute_b32 v62, v122, v22
	s_waitcnt lgkmcnt(0)
	v_add_f32_e32 v22, v22, v62
	ds_bpermute_b32 v62, v123, v22
	s_waitcnt lgkmcnt(0)
	v_add_f32_e32 v22, v22, v62
	ds_bpermute_b32 v62, v215, v22
	s_waitcnt lgkmcnt(0)
	v_add_f32_e32 v22, v22, v62
	v_fmamk_f32 v22, v22, 0x3a000000, v208
	v_cmp_gt_f32_e32 vcc, s26, v22
	v_mul_f32_e32 v62, 0x4f800000, v22
	s_nop 0
	v_cndmask_b32_e32 v22, v22, v62, vcc
	v_sqrt_f32_e32 v62, v22
	s_nop 0
	v_add_u32_e32 v63, -1, v62
	v_fma_f32 v64, -v63, v62, v22
	v_cmp_ge_f32_e64 s[8:9], 0, v64
	v_add_u32_e32 v64, 1, v62
	s_nop 0
	v_cndmask_b32_e64 v63, v62, v63, s[8:9]
	v_fma_f32 v62, -v64, v62, v22
	v_cmp_lt_f32_e64 s[8:9], 0, v62
	s_nop 1
	v_cndmask_b32_e64 v62, v63, v64, s[8:9]
	v_mul_f32_e32 v63, 0x37800000, v62
	v_cndmask_b32_e32 v62, v62, v63, vcc
	v_cmp_class_f32_e32 vcc, v22, v209
	s_nop 1
	v_cndmask_b32_e32 v22, v62, v22, vcc
	v_div_scale_f32 v62, s[8:9], v22, v22, 1.0
	v_rcp_f32_e32 v63, v62
	s_nop 0
	v_fma_f32 v64, -v62, v63, 1.0
	v_fmac_f32_e32 v63, v64, v63
	v_div_scale_f32 v64, vcc, 1.0, v22, 1.0
	v_mul_f32_e32 v65, v64, v63
	v_fma_f32 v66, -v62, v65, v64
	v_fmac_f32_e32 v65, v66, v63
	v_fma_f32 v62, -v62, v65, v64
	v_div_fmas_f32 v62, v62, v63, v65
	v_div_fixup_f32 v66, v62, v22, 1.0
	global_load_dwordx4 v[62:65], v[86:87], off
	s_nop 0
	global_store_dwordx4 v[72:73], v[10:13], off sc1 nt
	global_store_dwordx4 v[70:71], v[6:9], off sc1 nt
	v_mov_b32_e32 v22, v67
	v_pk_mul_f32 v[10:11], v[10:11], v[0:1] op_sel_hi:[1,0]
	v_pk_mul_f32 v[12:13], v[12:13], v[0:1] op_sel_hi:[1,0]
	v_pk_mul_f32 v[6:7], v[6:7], v[66:67] op_sel_hi:[1,0]
	v_pk_mul_f32 v[8:9], v[8:9], v[66:67] op_sel_hi:[1,0]
	s_waitcnt vmcnt(2)
	v_pk_mul_f32 v[10:11], v[10:11], v[62:63]
	v_pk_mul_f32 v[12:13], v[12:13], v[64:65]
	v_pk_mul_f32 v[6:7], v[62:63], v[6:7]
	v_pk_mul_f32 v[8:9], v[64:65], v[8:9]
	v_cvt_pk_bf16_f32 v10, v10, v11
	v_cvt_pk_bf16_f32 v11, v12, v13
	v_cvt_pk_bf16_f32 v6, v6, v7
	v_cvt_pk_bf16_f32 v7, v8, v9
	global_store_dwordx2 v[100:101], v[10:11], off
	global_store_dwordx2 v[68:69], v[6:7], off
	global_load_dwordx4 v[6:9], v[86:87], off offset:1024
	s_nop 0
	global_store_dwordx4 v[72:73], v[30:33], off offset:1024 sc1 nt
	global_store_dwordx4 v[70:71], v[2:5], off offset:1024 sc1 nt
	v_pk_mul_f32 v[10:11], v[30:31], v[0:1] op_sel_hi:[1,0]
	v_pk_mul_f32 v[12:13], v[32:33], v[0:1] op_sel_hi:[1,0]
	v_pk_mul_f32 v[2:3], v[2:3], v[66:67] op_sel_hi:[1,0]
	v_pk_mul_f32 v[4:5], v[4:5], v[66:67] op_sel_hi:[1,0]
	s_waitcnt vmcnt(0)
	v_pk_mul_f32 v[10:11], v[10:11], v[6:7]
	v_pk_mul_f32 v[12:13], v[12:13], v[8:9]
	v_pk_mul_f32 v[2:3], v[6:7], v[2:3]
	v_pk_mul_f32 v[4:5], v[8:9], v[4:5]
	v_cvt_pk_bf16_f32 v10, v10, v11
	v_cvt_pk_bf16_f32 v11, v12, v13
	v_cvt_pk_bf16_f32 v2, v2, v3
	v_cvt_pk_bf16_f32 v3, v4, v5
	global_store_dwordx2 v[100:101], v[10:11], off offset:512
	global_store_dwordx2 v[68:69], v[2:3], off offset:512
	global_load_dwordx4 v[2:5], v[86:87], off offset:2048
	v_pk_mul_f32 v[6:7], v[46:47], v[0:1] op_sel_hi:[1,0]
	v_pk_mul_f32 v[8:9], v[48:49], v[0:1] op_sel_hi:[1,0]
	global_store_dwordx4 v[72:73], v[46:49], off offset:2048 sc1 nt
	global_store_dwordx4 v[70:71], v[50:53], off offset:2048 sc1 nt
	v_pk_mul_f32 v[10:11], v[58:59], v[0:1] op_sel_hi:[1,0]
	v_pk_mul_f32 v[12:13], v[60:61], v[0:1] op_sel_hi:[1,0]
	s_waitcnt vmcnt(0)
	v_pk_mul_f32 v[6:7], v[6:7], v[2:3]
	v_pk_mul_f32 v[8:9], v[8:9], v[4:5]
	v_cvt_pk_bf16_f32 v6, v6, v7
	v_cvt_pk_bf16_f32 v7, v8, v9
	global_store_dwordx2 v[100:101], v[6:7], off offset:1024
	v_pk_mul_f32 v[6:7], v[50:51], v[66:67] op_sel_hi:[1,0]
	v_mov_b32_e32 v8, v103
	v_pk_mul_f32 v[2:3], v[6:7], v[2:3]
	v_pk_mul_f32 v[6:7], v[52:53], v[66:67] op_sel_hi:[1,0]
	v_cvt_pk_bf16_f32 v2, v2, v3
	v_pk_mul_f32 v[4:5], v[6:7], v[4:5]
	v_mov_b32_e32 v6, v104
	v_cvt_pk_bf16_f32 v3, v4, v5
	global_store_dwordx2 v[68:69], v[2:3], off offset:1024
	global_load_dwordx4 v[2:5], v[86:87], off offset:3072
	v_mov_b32_e32 v7, v102
	v_mov_b32_e32 v9, v105
	v_mov_b32_e32 v104, v103
	global_store_dwordx4 v[72:73], v[6:9], off offset:3072 sc1 nt
	global_store_dwordx4 v[70:71], v[54:57], off offset:3072 sc1 nt
	s_nop 0
	v_pk_mul_f32 v[6:7], v[6:7], v[0:1] op_sel_hi:[1,0]
	v_pk_mul_f32 v[8:9], v[104:105], v[0:1] op_sel_hi:[1,0]
	s_waitcnt vmcnt(0)
	v_pk_mul_f32 v[6:7], v[6:7], v[2:3]
	v_pk_mul_f32 v[8:9], v[8:9], v[4:5]
	v_cvt_pk_bf16_f32 v6, v6, v7
	v_cvt_pk_bf16_f32 v7, v8, v9
	global_store_dwordx2 v[100:101], v[6:7], off offset:1536
	v_pk_mul_f32 v[6:7], v[54:55], v[66:67] op_sel_hi:[1,0]
	s_nop 0
	v_pk_mul_f32 v[2:3], v[6:7], v[2:3]
	v_pk_mul_f32 v[6:7], v[56:57], v[66:67] op_sel_hi:[1,0]
	v_cvt_pk_bf16_f32 v2, v2, v3
	v_pk_mul_f32 v[4:5], v[6:7], v[4:5]
	s_nop 0
	v_cvt_pk_bf16_f32 v3, v4, v5
	global_store_dwordx2 v[68:69], v[2:3], off offset:1536
	global_load_dwordx4 v[6:9], v[92:93], off
	v_add_co_u32_e32 v2, vcc, s71, v72
	s_waitcnt vmcnt(0)
	v_pk_mul_f32 v[10:11], v[10:11], v[6:7]
	v_addc_co_u32_e32 v3, vcc, 0, v73, vcc
	v_add_co_u32_e32 v4, vcc, s71, v70
	v_pk_mul_f32 v[12:13], v[12:13], v[8:9]
	s_nop 0
	v_addc_co_u32_e32 v5, vcc, 0, v71, vcc
	v_cvt_pk_bf16_f32 v10, v10, v11
	v_cvt_pk_bf16_f32 v11, v12, v13
	global_store_dwordx4 v[2:3], v[58:61], off sc1 nt
	global_store_dwordx4 v[4:5], v[42:45], off sc1 nt
	global_store_dwordx2 v[100:101], v[10:11], off offset:2048
	v_pk_mul_f32 v[10:11], v[42:43], v[66:67] op_sel_hi:[1,0]
	v_pk_mul_f32 v[12:13], v[40:41], v[0:1] op_sel_hi:[1,0]
	v_pk_mul_f32 v[6:7], v[10:11], v[6:7]
	v_pk_mul_f32 v[10:11], v[44:45], v[66:67] op_sel_hi:[1,0]
	v_cvt_pk_bf16_f32 v6, v6, v7
	v_pk_mul_f32 v[8:9], v[10:11], v[8:9]
	v_pk_mul_f32 v[10:11], v[38:39], v[0:1] op_sel_hi:[1,0]
	v_cvt_pk_bf16_f32 v7, v8, v9
	global_store_dwordx2 v[68:69], v[6:7], off offset:2048
	global_load_dwordx4 v[6:9], v[94:95], off
	s_nop 0
	global_store_dwordx4 v[2:3], v[38:41], off offset:1024 sc1 nt
	global_store_dwordx4 v[4:5], v[34:37], off offset:1024 sc1 nt
	s_waitcnt vmcnt(0)
	v_pk_mul_f32 v[10:11], v[10:11], v[6:7]
	v_pk_mul_f32 v[12:13], v[12:13], v[8:9]
	v_cvt_pk_bf16_f32 v10, v10, v11
	v_cvt_pk_bf16_f32 v11, v12, v13
	global_store_dwordx2 v[100:101], v[10:11], off offset:2560
	v_pk_mul_f32 v[10:11], v[34:35], v[66:67] op_sel_hi:[1,0]
	v_pk_mul_f32 v[12:13], v[28:29], v[0:1] op_sel_hi:[1,0]
	v_pk_mul_f32 v[6:7], v[10:11], v[6:7]
	v_pk_mul_f32 v[10:11], v[36:37], v[66:67] op_sel_hi:[1,0]
	v_cvt_pk_bf16_f32 v6, v6, v7
	v_pk_mul_f32 v[8:9], v[10:11], v[8:9]
	v_pk_mul_f32 v[10:11], v[26:27], v[0:1] op_sel_hi:[1,0]
	v_cvt_pk_bf16_f32 v7, v8, v9
	global_store_dwordx2 v[68:69], v[6:7], off offset:2560
	global_load_dwordx4 v[6:9], v[96:97], off
	s_nop 0
	global_store_dwordx4 v[2:3], v[26:29], off offset:2048 sc1 nt
	global_store_dwordx4 v[4:5], v[14:17], off offset:2048 sc1 nt
	s_waitcnt vmcnt(0)
	v_pk_mul_f32 v[10:11], v[10:11], v[6:7]
	v_pk_mul_f32 v[12:13], v[12:13], v[8:9]
	v_cvt_pk_bf16_f32 v10, v10, v11
	v_cvt_pk_bf16_f32 v11, v12, v13
	global_store_dwordx2 v[100:101], v[10:11], off offset:3072
	v_pk_mul_f32 v[10:11], v[14:15], v[66:67] op_sel_hi:[1,0]
	s_nop 0
	v_pk_mul_f32 v[6:7], v[10:11], v[6:7]
	v_pk_mul_f32 v[10:11], v[16:17], v[66:67] op_sel_hi:[1,0]
	v_cvt_pk_bf16_f32 v6, v6, v7
	v_pk_mul_f32 v[8:9], v[10:11], v[8:9]
	s_nop 0
	v_cvt_pk_bf16_f32 v7, v8, v9
	global_store_dwordx2 v[68:69], v[6:7], off offset:3072
	global_load_dwordx4 v[6:9], v[98:99], off
	s_nop 0
	global_store_dwordx4 v[2:3], v[22:25], off offset:3072 sc1 nt
	global_store_dwordx4 v[4:5], v[18:21], off offset:3072 sc1 nt
	v_pk_mul_f32 v[2:3], v[22:23], v[0:1] op_sel_hi:[1,0]
	v_pk_mul_f32 v[4:5], v[24:25], v[0:1] op_sel_hi:[1,0]
	s_waitcnt vmcnt(0)
	v_pk_mul_f32 v[2:3], v[2:3], v[6:7]
	v_pk_mul_f32 v[4:5], v[4:5], v[8:9]
	v_cvt_pk_bf16_f32 v2, v2, v3
	v_cvt_pk_bf16_f32 v3, v4, v5
	global_store_dwordx2 v[100:101], v[2:3], off offset:3584
	v_pk_mul_f32 v[2:3], v[18:19], v[66:67] op_sel_hi:[1,0]
	v_pk_mul_f32 v[4:5], v[20:21], v[66:67] op_sel_hi:[1,0]
	v_pk_mul_f32 v[2:3], v[2:3], v[6:7]
	v_pk_mul_f32 v[4:5], v[4:5], v[8:9]
	v_cvt_pk_bf16_f32 v2, v2, v3
	v_cvt_pk_bf16_f32 v3, v4, v5
	v_lshl_add_u64 v[100:101], v[100:101], 0, s[60:61]
	global_store_dwordx2 v[68:69], v[2:3], off offset:3584
	s_cbranch_scc0 .LBB0_834

.LBB0_839:
	s_add_i32 s4, s68, s0
	s_ashr_i32 s5, s4, 31
	s_lshl_b64 s[6:7], s[4:5], 12
	v_lshl_add_u64 v[64:65], v[8:9], 0, s[6:7]
	s_lshl_b64 s[4:5], s[4:5], 13
	global_load_dwordx2 v[66:67], v[20:21], off nt
	global_load_dwordx4 v[2:5], v[22:23], off offset:-4096 nt
	global_load_dwordx2 v[68:69], v[20:21], off offset:512 nt
	global_load_dwordx4 v[28:31], v[22:23], off offset:-3072 nt
	global_load_dwordx2 v[70:71], v[20:21], off offset:1024 nt
	global_load_dwordx4 v[32:35], v[22:23], off offset:-2048 nt
	global_load_dwordx2 v[124:125], v[20:21], off offset:1536 nt
	global_load_dwordx4 v[36:39], v[22:23], off offset:-1024 nt
	global_load_dwordx2 v[126:127], v[20:21], off offset:2048 nt
	global_load_dwordx4 v[40:43], v[22:23], off nt
	global_load_dwordx2 v[128:129], v[20:21], off offset:2560 nt
	global_load_dwordx4 v[44:47], v[22:23], off offset:1024 nt
	global_load_dwordx2 v[130:131], v[20:21], off offset:3072 nt
	global_load_dwordx4 v[100:103], v[22:23], off offset:2048 nt
	global_load_dwordx2 v[132:133], v[20:21], off offset:3584 nt
	global_load_dwordx4 v[104:107], v[22:23], off offset:3072 nt
	v_lshl_add_u64 v[26:27], v[6:7], 0, s[4:5]
	global_load_dwordx2 v[72:73], v[64:65], off nt
	global_load_dwordx4 v[48:51], v[26:27], off nt
	global_load_dwordx2 v[76:77], v[64:65], off offset:512 nt
	global_load_dwordx4 v[52:55], v[26:27], off offset:1024 nt
	global_load_dwordx2 v[134:135], v[64:65], off offset:1024 nt
	global_load_dwordx4 v[56:59], v[26:27], off offset:2048 nt
	global_load_dwordx2 v[136:137], v[64:65], off offset:1536 nt
	global_load_dwordx4 v[60:63], v[26:27], off offset:3072 nt
	global_load_dwordx2 v[138:139], v[64:65], off offset:2048 nt
	v_add_co_u32_e32 v24, vcc, s71, v26
	s_add_i32 s0, s0, s58
	s_nop 0
	v_addc_co_u32_e32 v25, vcc, 0, v27, vcc
	global_load_dwordx4 v[108:111], v[24:25], off nt
	global_load_dwordx2 v[140:141], v[64:65], off offset:2560 nt
	global_load_dwordx4 v[112:115], v[24:25], off offset:1024 nt
	global_load_dwordx2 v[142:143], v[64:65], off offset:3072 nt
	global_load_dwordx4 v[116:119], v[24:25], off offset:2048 nt
	global_load_dwordx2 v[144:145], v[64:65], off offset:3584 nt
	global_load_dwordx4 v[120:123], v[24:25], off offset:3072 nt
	v_lshl_add_u64 v[20:21], v[20:21], 0, s[60:61]
	s_cmpk_gt_i32 s0, 0x7fff
	s_waitcnt vmcnt(0) lgkmcnt(0)
	v_lshlrev_b32_e32 v64, 16, v66
	v_and_b32_e32 v65, 0xffff0000, v66
	v_pk_add_f32 v[90:91], v[2:3], v[64:65]
	v_lshlrev_b32_e32 v2, 16, v67
	v_and_b32_e32 v3, 0xffff0000, v67
	v_pk_add_f32 v[92:93], v[4:5], v[2:3]
	v_lshlrev_b32_e32 v2, 16, v72
	v_and_b32_e32 v3, 0xffff0000, v72
	v_pk_add_f32 v[82:83], v[48:49], v[2:3]
	v_lshlrev_b32_e32 v48, 16, v76
	v_and_b32_e32 v49, 0xffff0000, v76
	v_pk_add_f32 v[74:75], v[52:53], v[48:49]
	v_lshlrev_b32_e32 v48, 16, v77
	v_and_b32_e32 v49, 0xffff0000, v77
	v_lshlrev_b32_e32 v2, 16, v73
	v_and_b32_e32 v3, 0xffff0000, v73
	v_pk_add_f32 v[76:77], v[54:55], v[48:49]
	v_lshlrev_b32_e32 v48, 16, v68
	v_and_b32_e32 v49, 0xffff0000, v68
	v_pk_add_f32 v[84:85], v[50:51], v[2:3]
	v_pk_add_f32 v[86:87], v[28:29], v[48:49]
	v_and_b32_e32 v49, 0xffff0000, v69
	v_lshlrev_b32_e32 v48, 16, v69
	v_mov_b32_e32 v50, v83
	v_mov_b32_e32 v51, v75
	v_pk_add_f32 v[88:89], v[30:31], v[48:49]
	v_mov_b32_e32 v48, v82
	v_mov_b32_e32 v49, v74
	v_pk_mul_f32 v[50:51], v[50:51], v[50:51]
	v_mov_b32_e32 v52, v85
	v_mov_b32_e32 v53, v77
	v_pk_fma_f32 v[48:49], v[48:49], v[48:49], v[50:51]
	v_mov_b32_e32 v50, v84
	v_mov_b32_e32 v51, v76
	v_pk_mul_f32 v[52:53], v[52:53], v[52:53]
	v_pk_mul_f32 v[2:3], v[90:91], v[90:91]
	v_pk_fma_f32 v[50:51], v[50:51], v[50:51], v[52:53]
	v_pk_mul_f32 v[4:5], v[92:93], v[92:93]
	v_pk_add_f32 v[48:49], v[48:49], v[50:51]
	v_lshlrev_b32_e32 v50, 16, v70
	v_and_b32_e32 v51, 0xffff0000, v70
	v_pk_add_f32 v[78:79], v[32:33], v[50:51]
	v_lshlrev_b32_e32 v32, 16, v71
	v_and_b32_e32 v33, 0xffff0000, v71
	v_pk_mov_b32 v[2:3], v[2:3], v[78:79] op_sel:[1,0]
	v_mul_f32_e32 v0, v87, v87
	v_pk_add_f32 v[80:81], v[34:35], v[32:33]
	v_lshlrev_b32_e32 v32, 16, v134
	v_and_b32_e32 v33, 0xffff0000, v134
	v_pk_fma_f32 v[34:35], v[90:91], v[90:91], v[2:3]
	v_pk_mul_f32 v[2:3], v[78:79], v[2:3] op_sel_hi:[0,1]
	v_pk_fma_f32 v[28:29], v[86:87], v[86:87], v[0:1] op_sel_hi:[1,1,0]
	v_mul_f32_e32 v0, v89, v89
	v_pk_add_f32 v[66:67], v[56:57], v[32:33]
	v_lshlrev_b32_e32 v32, 16, v135
	v_and_b32_e32 v33, 0xffff0000, v135
	v_mov_b32_e32 v35, v3
	v_mov_b32_e32 v2, v5
	v_mov_b32_e32 v3, v79
	v_pk_fma_f32 v[30:31], v[88:89], v[88:89], v[0:1] op_sel_hi:[1,1,0]
	v_pk_add_f32 v[68:69], v[58:59], v[32:33]
	v_pk_mul_f32 v[32:33], v[80:81], v[80:81]
	v_pk_fma_f32 v[2:3], v[92:93], v[92:93], v[2:3]
	v_pk_mul_f32 v[4:5], v[78:79], v[78:79]
	v_mov_b32_e32 v29, v33
	v_mov_b32_e32 v3, v5
	v_mov_b32_e32 v31, v32
	v_pk_add_f32 v[2:3], v[34:35], v[2:3]
	v_pk_add_f32 v[4:5], v[28:29], v[30:31]
	v_mov_b32_e32 v28, v67
	v_mov_b32_e32 v29, v69
	v_pk_add_f32 v[2:3], v[2:3], v[4:5]
	v_mov_b32_e32 v4, v66
	v_mov_b32_e32 v5, v68
	v_pk_mul_f32 v[28:29], v[28:29], v[28:29]
	v_mov_b32_e32 v30, v37
	v_pk_fma_f32 v[4:5], v[4:5], v[4:5], v[28:29]
	v_lshlrev_b32_e32 v28, 16, v136
	v_and_b32_e32 v29, 0xffff0000, v136
	v_pk_add_f32 v[58:59], v[60:61], v[28:29]
	v_lshlrev_b32_e32 v28, 16, v137
	v_and_b32_e32 v29, 0xffff0000, v137
	v_pk_add_f32 v[60:61], v[62:63], v[28:29]
	v_and_b32_e32 v28, 0xffff0000, v124
	v_lshlrev_b32_e32 v29, 16, v125
	v_mov_b32_e32 v31, v38
	v_lshlrev_b32_e32 v32, 16, v138
	v_and_b32_e32 v33, 0xffff0000, v138
	v_pk_add_f32 v[72:73], v[30:31], v[28:29]
	v_lshlrev_b32_e32 v28, 16, v124
	v_and_b32_e32 v29, 0xffff0000, v125
	v_mov_b32_e32 v37, v39
	v_pk_add_f32 v[50:51], v[108:109], v[32:33]
	v_lshlrev_b32_e32 v32, 16, v139
	v_and_b32_e32 v33, 0xffff0000, v139
	v_pk_add_f32 v[70:71], v[36:37], v[28:29]
	v_pk_mul_f32 v[28:29], v[72:73], v[72:73]
	v_mul_f32_e32 v0, v59, v59
	v_pk_add_f32 v[52:53], v[110:111], v[32:33]
	v_lshlrev_b32_e32 v32, 16, v126
	v_and_b32_e32 v33, 0xffff0000, v126
	v_pk_fma_f32 v[38:39], v[70:71], v[70:71], v[28:29]
	v_pk_fma_f32 v[28:29], v[58:59], v[58:59], v[0:1] op_sel_hi:[1,1,0]
	v_mul_f32_e32 v0, v61, v61
	v_pk_add_f32 v[62:63], v[40:41], v[32:33]
	v_and_b32_e32 v33, 0xffff0000, v127
	v_lshlrev_b32_e32 v32, 16, v127
	v_pk_add_f32 v[48:49], v[48:49], v[48:49] op_sel:[0,1] op_sel_hi:[1,0]
	v_pk_add_f32 v[4:5], v[4:5], v[4:5] op_sel:[0,1] op_sel_hi:[1,0]
	v_pk_fma_f32 v[30:31], v[60:61], v[60:61], v[0:1] op_sel_hi:[1,1,0]
	v_pk_add_f32 v[64:65], v[42:43], v[32:33]
	v_pk_mul_f32 v[32:33], v[50:51], v[50:51]
	v_pk_mul_f32 v[34:35], v[52:53], v[52:53]
	v_mov_b32_e32 v49, v32
	v_mov_b32_e32 v5, v33
	v_mov_b32_e32 v29, v34
	v_mov_b32_e32 v31, v35
	v_pk_add_f32 v[4:5], v[48:49], v[4:5]
	v_pk_add_f32 v[28:29], v[28:29], v[30:31]
	v_mul_f32_e32 v0, v63, v63
	v_pk_add_f32 v[4:5], v[4:5], v[28:29]
	v_lshlrev_b32_e32 v28, 16, v128
	v_and_b32_e32 v29, 0xffff0000, v128
	v_pk_add_f32 v[54:55], v[44:45], v[28:29]
	v_lshlrev_b32_e32 v28, 16, v129
	v_and_b32_e32 v29, 0xffff0000, v129
	v_pk_add_f32 v[56:57], v[46:47], v[28:29]
	v_lshlrev_b32_e32 v28, 16, v140
	v_and_b32_e32 v29, 0xffff0000, v140
	v_pk_add_f32 v[44:45], v[112:113], v[28:29]
	v_lshlrev_b32_e32 v28, 16, v141
	v_and_b32_e32 v29, 0xffff0000, v141
	v_pk_add_f32 v[46:47], v[114:115], v[28:29]
	v_mov_b32_e32 v30, v45
	v_mov_b32_e32 v31, v47
	v_mov_b32_e32 v28, v44
	v_mov_b32_e32 v29, v46
	v_pk_mul_f32 v[30:31], v[30:31], v[30:31]
	v_pk_fma_f32 v[40:41], v[62:63], v[62:63], v[0:1] op_sel_hi:[1,1,0]
	v_pk_fma_f32 v[28:29], v[28:29], v[28:29], v[30:31]
	v_mul_f32_e32 v0, v65, v65
	v_pk_add_f32 v[114:115], v[28:29], v[28:29] op_sel:[0,1] op_sel_hi:[1,0]
	v_lshlrev_b32_e32 v28, 16, v142
	v_and_b32_e32 v29, 0xffff0000, v142
	v_pk_fma_f32 v[108:109], v[64:65], v[64:65], v[0:1] op_sel_hi:[1,1,0]
	v_pk_add_f32 v[30:31], v[116:117], v[28:29]
	v_lshlrev_b32_e32 v28, 16, v143
	v_and_b32_e32 v29, 0xffff0000, v143
	v_pk_add_f32 v[2:3], v[2:3], v[2:3] op_sel:[0,1] op_sel_hi:[1,0]
	v_pk_mul_f32 v[110:111], v[54:55], v[54:55]
	v_pk_add_f32 v[36:37], v[118:119], v[28:29]
	v_lshlrev_b32_e32 v28, 16, v130
	v_and_b32_e32 v29, 0xffff0000, v130
	v_lshlrev_b32_e32 v109, 16, v132
	v_pk_add_f32 v[38:39], v[38:39], v[38:39] op_sel:[0,1] op_sel_hi:[1,0]
	v_pk_mul_f32 v[112:113], v[56:57], v[56:57]
	v_pk_add_f32 v[42:43], v[100:101], v[28:29]
	v_and_b32_e32 v29, 0xffff0000, v131
	v_lshlrev_b32_e32 v28, 16, v131
	v_and_b32_e32 v125, 0xffff0000, v132
	v_mov_b32_e32 v3, v104
	v_mov_b32_e32 v39, v109
	v_mov_b32_e32 v41, v104
	v_mov_b32_e32 v104, v110
	v_mov_b32_e32 v124, v111
	v_mul_f32_e32 v0, v43, v43
	v_pk_add_f32 v[48:49], v[102:103], v[28:29]
	v_lshlrev_b32_e32 v28, 16, v133
	v_and_b32_e32 v29, 0xffff0000, v133
	v_pk_add_f32 v[38:39], v[2:3], v[38:39]
	v_pk_add_f32 v[2:3], v[40:41], v[108:109]
	v_pk_add_f32 v[40:41], v[104:105], v[124:125]
	v_mov_b32_e32 v104, v113
	v_mov_b32_e32 v113, v125
	v_pk_fma_f32 v[100:101], v[42:43], v[42:43], v[0:1] op_sel_hi:[1,1,0]
	v_mul_f32_e32 v0, v49, v49
	v_pk_add_f32 v[32:33], v[106:107], v[28:29]
	v_pk_add_f32 v[104:105], v[104:105], v[112:113]
	v_pk_add_f32 v[108:109], v[38:39], v[2:3]
	v_pk_mul_f32 v[2:3], v[38:39], v[2:3]
	v_pk_fma_f32 v[102:103], v[48:49], v[48:49], v[0:1] op_sel_hi:[1,1,0]
	v_pk_mul_f32 v[106:107], v[32:33], v[32:33]
	v_mov_b32_e32 v109, v3
	v_pk_add_f32 v[2:3], v[40:41], v[104:105]
	v_pk_mul_f32 v[104:105], v[40:41], v[104:105]
	v_mov_b32_e32 v101, v107
	v_mov_b32_e32 v3, v105
	v_mov_b32_e32 v103, v106
	v_mul_f32_e32 v0, v31, v31
	v_lshlrev_b32_e32 v28, 16, v144
	v_and_b32_e32 v29, 0xffff0000, v144
	v_lshlrev_b32_e32 v34, 16, v145
	v_and_b32_e32 v35, 0xffff0000, v145
	v_pk_add_f32 v[2:3], v[108:109], v[2:3]
	v_pk_add_f32 v[100:101], v[100:101], v[102:103]
	v_pk_fma_f32 v[116:117], v[30:31], v[30:31], v[0:1] op_sel_hi:[1,1,0]
	v_mul_f32_e32 v0, v37, v37
	v_pk_add_f32 v[28:29], v[120:121], v[28:29]
	v_pk_add_f32 v[34:35], v[122:123], v[34:35]
	v_pk_add_f32 v[2:3], v[2:3], v[100:101]
	v_pk_add_f32 v[4:5], v[4:5], v[4:5] op_sel:[0,1] op_sel_hi:[1,0]
	v_pk_fma_f32 v[118:119], v[36:37], v[36:37], v[0:1] op_sel_hi:[1,1,0]
	v_add_f32_e32 v0, v2, v3
	v_pk_mul_f32 v[2:3], v[28:29], v[28:29]
	v_pk_mul_f32 v[100:101], v[34:35], v[34:35]
	v_mov_b32_e32 v5, v2
	v_mov_b32_e32 v115, v3
	v_mov_b32_e32 v117, v100
	v_mov_b32_e32 v119, v101
	v_pk_add_f32 v[2:3], v[4:5], v[114:115]
	v_pk_add_f32 v[4:5], v[116:117], v[118:119]
	s_nop 0
	v_pk_add_f32 v[2:3], v[2:3], v[4:5]
	s_nop 0
	v_add_f32_e32 v2, v2, v3
	ds_bpermute_b32 v3, v94, v0
	s_waitcnt lgkmcnt(0)
	v_add_f32_e32 v0, v0, v3
	ds_bpermute_b32 v3, v95, v0
	s_waitcnt lgkmcnt(0)
	v_add_f32_e32 v0, v0, v3
	ds_bpermute_b32 v3, v96, v0
	s_waitcnt lgkmcnt(0)
	v_add_f32_e32 v0, v0, v3
	ds_bpermute_b32 v3, v97, v0
	s_waitcnt lgkmcnt(0)
	v_add_f32_e32 v0, v0, v3
	ds_bpermute_b32 v3, v98, v0
	s_waitcnt lgkmcnt(0)
	v_add_f32_e32 v0, v0, v3
	ds_bpermute_b32 v3, v215, v0
	s_waitcnt lgkmcnt(0)
	v_add_f32_e32 v0, v0, v3
	v_fmamk_f32 v0, v0, 0x3a000000, v208
	v_cmp_gt_f32_e32 vcc, s1, v0
	v_mul_f32_e32 v3, 0x4f800000, v0
	s_nop 0
	v_cndmask_b32_e32 v0, v0, v3, vcc
	v_sqrt_f32_e32 v3, v0
	s_nop 0
	v_add_u32_e32 v4, -1, v3
	v_fma_f32 v5, -v4, v3, v0
	v_cmp_ge_f32_e64 s[6:7], 0, v5
	v_add_u32_e32 v5, 1, v3
	s_nop 0
	v_cndmask_b32_e64 v4, v3, v4, s[6:7]
	v_fma_f32 v3, -v5, v3, v0
	v_cmp_lt_f32_e64 s[6:7], 0, v3
	s_nop 1
	v_cndmask_b32_e64 v3, v4, v5, s[6:7]
	v_mul_f32_e32 v4, 0x37800000, v3
	v_cndmask_b32_e32 v3, v3, v4, vcc
	v_cmp_class_f32_e32 vcc, v0, v209
	s_nop 1
	v_cndmask_b32_e32 v0, v3, v0, vcc
	v_div_scale_f32 v3, s[4:5], v0, v0, 1.0
	v_rcp_f32_e32 v4, v3
	s_nop 0
	v_fma_f32 v5, -v3, v4, 1.0
	v_fmac_f32_e32 v4, v5, v4
	v_div_scale_f32 v5, vcc, 1.0, v0, 1.0
	v_mul_f32_e32 v38, v5, v4
	v_fma_f32 v40, -v3, v38, v5
	v_fmac_f32_e32 v38, v40, v4
	v_fma_f32 v3, -v3, v38, v5
	v_div_fmas_f32 v3, v3, v4, v38
	v_div_fixup_f32 v0, v3, v0, 1.0
	ds_bpermute_b32 v3, v94, v2
	v_pk_mul_f32 v[90:91], v[90:91], v[0:1] op_sel_hi:[1,0]
	v_pk_mul_f32 v[92:93], v[92:93], v[0:1] op_sel_hi:[1,0]
	v_pk_mul_f32 v[42:43], v[42:43], v[0:1] op_sel_hi:[1,0]
	s_waitcnt lgkmcnt(0)
	v_add_f32_e32 v2, v2, v3
	ds_bpermute_b32 v3, v95, v2
	s_waitcnt lgkmcnt(0)
	v_add_f32_e32 v2, v2, v3
	ds_bpermute_b32 v3, v96, v2
	s_waitcnt lgkmcnt(0)
	v_add_f32_e32 v2, v2, v3
	ds_bpermute_b32 v3, v97, v2
	s_waitcnt lgkmcnt(0)
	v_add_f32_e32 v2, v2, v3
	ds_bpermute_b32 v3, v98, v2
	s_waitcnt lgkmcnt(0)
	v_add_f32_e32 v2, v2, v3
	ds_bpermute_b32 v3, v215, v2
	s_waitcnt lgkmcnt(0)
	v_add_f32_e32 v2, v2, v3
	v_fmamk_f32 v2, v2, 0x3a000000, v208
	v_cmp_gt_f32_e32 vcc, s1, v2
	v_mul_f32_e32 v3, 0x4f800000, v2
	s_nop 0
	v_cndmask_b32_e32 v2, v2, v3, vcc
	v_sqrt_f32_e32 v3, v2
	s_nop 0
	v_add_u32_e32 v4, -1, v3
	v_fma_f32 v5, -v4, v3, v2
	v_cmp_ge_f32_e64 s[6:7], 0, v5
	v_add_u32_e32 v5, 1, v3
	s_nop 0
	v_cndmask_b32_e64 v4, v3, v4, s[6:7]
	v_fma_f32 v3, -v5, v3, v2
	v_cmp_lt_f32_e64 s[6:7], 0, v3
	s_nop 1
	v_cndmask_b32_e64 v3, v4, v5, s[6:7]
	v_mul_f32_e32 v4, 0x37800000, v3
	v_cndmask_b32_e32 v3, v3, v4, vcc
	v_cmp_class_f32_e32 vcc, v2, v209
	s_nop 1
	v_cndmask_b32_e32 v2, v3, v2, vcc
	v_div_scale_f32 v3, s[4:5], v2, v2, 1.0
	v_rcp_f32_e32 v4, v3
	s_nop 0
	v_fma_f32 v5, -v3, v4, 1.0
	v_fmac_f32_e32 v4, v5, v4
	v_div_scale_f32 v5, vcc, 1.0, v2, 1.0
	v_mul_f32_e32 v38, v5, v4
	v_fma_f32 v40, -v3, v38, v5
	v_fmac_f32_e32 v38, v40, v4
	v_fma_f32 v3, -v3, v38, v5
	v_div_fmas_f32 v3, v3, v4, v38
	v_div_fixup_f32 v38, v3, v2, 1.0
	global_load_dwordx4 v[2:5], v[10:11], off
	v_pk_mul_f32 v[82:83], v[82:83], v[38:39] op_sel_hi:[1,0]
	v_pk_mul_f32 v[84:85], v[84:85], v[38:39] op_sel_hi:[1,0]
	v_pk_mul_f32 v[76:77], v[76:77], v[38:39] op_sel_hi:[1,0]
	v_pk_mul_f32 v[74:75], v[74:75], v[38:39] op_sel_hi:[1,0]
	v_pk_mul_f32 v[68:69], v[68:69], v[38:39] op_sel_hi:[1,0]
	v_pk_mul_f32 v[66:67], v[66:67], v[38:39] op_sel_hi:[1,0]
	v_pk_mul_f32 v[60:61], v[60:61], v[38:39] op_sel_hi:[1,0]
	v_pk_mul_f32 v[58:59], v[58:59], v[38:39] op_sel_hi:[1,0]
	v_pk_mul_f32 v[50:51], v[50:51], v[38:39] op_sel_hi:[1,0]
	v_pk_mul_f32 v[44:45], v[44:45], v[38:39] op_sel_hi:[1,0]
	v_pk_mul_f32 v[30:31], v[30:31], v[38:39] op_sel_hi:[1,0]
	v_mov_b32_e32 v40, v39
	v_pk_mul_f32 v[28:29], v[28:29], v[38:39] op_sel_hi:[1,0]
	s_waitcnt vmcnt(0)
	v_pk_mul_f32 v[92:93], v[4:5], v[92:93]
	v_pk_mul_f32 v[90:91], v[2:3], v[90:91]
	v_pk_mul_f32 v[4:5], v[4:5], v[84:85]
	v_pk_mul_f32 v[2:3], v[2:3], v[82:83]
	global_store_dwordx4 v[22:23], v[90:93], off offset:-4096 sc1 nt
	global_store_dwordx4 v[26:27], v[2:5], off sc1 nt
	global_load_dwordx4 v[2:5], v[10:11], off offset:1024
	v_pk_mul_f32 v[84:85], v[88:89], v[0:1] op_sel_hi:[1,0]
	v_pk_mul_f32 v[82:83], v[86:87], v[0:1] op_sel_hi:[1,0]
	s_waitcnt vmcnt(0)
	v_pk_mul_f32 v[84:85], v[84:85], v[4:5]
	v_pk_mul_f32 v[82:83], v[82:83], v[2:3]
	v_pk_mul_f32 v[2:3], v[2:3], v[74:75]
	v_pk_mul_f32 v[4:5], v[4:5], v[76:77]
	global_store_dwordx4 v[22:23], v[82:85], off offset:-3072 sc1 nt
	global_store_dwordx4 v[26:27], v[2:5], off offset:1024 sc1 nt
	global_load_dwordx4 v[2:5], v[10:11], off offset:2048
	v_pk_mul_f32 v[76:77], v[80:81], v[0:1] op_sel_hi:[1,0]
	v_pk_mul_f32 v[74:75], v[78:79], v[0:1] op_sel_hi:[1,0]
	s_waitcnt vmcnt(0)
	v_pk_mul_f32 v[76:77], v[76:77], v[4:5]
	v_pk_mul_f32 v[74:75], v[74:75], v[2:3]
	v_pk_mul_f32 v[2:3], v[2:3], v[66:67]
	v_pk_mul_f32 v[4:5], v[4:5], v[68:69]
	global_store_dwordx4 v[22:23], v[74:77], off offset:-2048 sc1 nt
	global_store_dwordx4 v[26:27], v[2:5], off offset:2048 sc1 nt
	global_load_dwordx4 v[2:5], v[10:11], off offset:3072
	v_mov_b32_e32 v66, v73
	v_mov_b32_e32 v67, v71
	v_mov_b32_e32 v71, v72
	v_pk_mul_f32 v[68:69], v[66:67], v[0:1] op_sel_hi:[1,0]
	v_pk_mul_f32 v[66:67], v[70:71], v[0:1] op_sel_hi:[1,0]
	s_waitcnt vmcnt(0)
	v_pk_mul_f32 v[68:69], v[68:69], v[4:5]
	v_pk_mul_f32 v[66:67], v[66:67], v[2:3]
	v_pk_mul_f32 v[2:3], v[58:59], v[2:3]
	v_pk_mul_f32 v[4:5], v[60:61], v[4:5]
	global_store_dwordx4 v[22:23], v[66:69], off offset:-1024 sc1 nt
	global_store_dwordx4 v[26:27], v[2:5], off offset:3072 sc1 nt
	global_load_dwordx4 v[2:5], v[12:13], off
	v_pk_mul_f32 v[26:27], v[64:65], v[0:1] op_sel_hi:[1,0]
	v_pk_mul_f32 v[58:59], v[62:63], v[0:1] op_sel_hi:[1,0]
	s_waitcnt vmcnt(0)
	v_pk_mul_f32 v[60:61], v[26:27], v[4:5]
	v_pk_mul_f32 v[26:27], v[52:53], v[38:39] op_sel_hi:[1,0]
	v_pk_mul_f32 v[58:59], v[58:59], v[2:3]
	v_pk_mul_f32 v[2:3], v[50:51], v[2:3]
	v_pk_mul_f32 v[4:5], v[26:27], v[4:5]
	global_store_dwordx4 v[22:23], v[58:61], off sc1 nt
	global_store_dwordx4 v[24:25], v[2:5], off sc1 nt
	global_load_dwordx4 v[2:5], v[14:15], off
	v_pk_mul_f32 v[26:27], v[56:57], v[0:1] op_sel_hi:[1,0]
	v_pk_mul_f32 v[50:51], v[54:55], v[0:1] op_sel_hi:[1,0]
	s_waitcnt vmcnt(0)
	v_pk_mul_f32 v[52:53], v[26:27], v[4:5]
	v_pk_mul_f32 v[26:27], v[46:47], v[38:39] op_sel_hi:[1,0]
	v_pk_mul_f32 v[50:51], v[50:51], v[2:3]
	v_pk_mul_f32 v[2:3], v[44:45], v[2:3]
	v_pk_mul_f32 v[4:5], v[26:27], v[4:5]
	global_store_dwordx4 v[22:23], v[50:53], off offset:1024 sc1 nt
	global_store_dwordx4 v[24:25], v[2:5], off offset:1024 sc1 nt
	global_load_dwordx4 v[2:5], v[16:17], off
	v_pk_mul_f32 v[26:27], v[48:49], v[0:1] op_sel_hi:[1,0]
	s_waitcnt vmcnt(0)
	v_pk_mul_f32 v[42:43], v[42:43], v[2:3]
	v_pk_mul_f32 v[44:45], v[26:27], v[4:5]
	v_pk_mul_f32 v[26:27], v[36:37], v[38:39] op_sel_hi:[1,0]
	v_pk_mul_f32 v[2:3], v[30:31], v[2:3]
	v_pk_mul_f32 v[4:5], v[26:27], v[4:5]
	global_store_dwordx4 v[22:23], v[42:45], off offset:2048 sc1 nt
	global_store_dwordx4 v[24:25], v[2:5], off offset:2048 sc1 nt
	global_load_dwordx4 v[2:5], v[18:19], off
	v_pk_mul_f32 v[26:27], v[32:33], v[0:1] op_sel_hi:[1,0]
	v_pk_mul_f32 v[30:31], v[40:41], v[0:1] op_sel_hi:[1,0]
	s_waitcnt vmcnt(0)
	v_pk_mul_f32 v[32:33], v[26:27], v[4:5]
	v_pk_mul_f32 v[30:31], v[30:31], v[2:3]
	v_pk_mul_f32 v[26:27], v[34:35], v[38:39] op_sel_hi:[1,0]
	global_store_dwordx4 v[22:23], v[30:33], off offset:3072 sc1 nt
	v_pk_mul_f32 v[2:3], v[28:29], v[2:3]
	v_pk_mul_f32 v[4:5], v[26:27], v[4:5]
	v_lshl_add_u64 v[22:23], v[22:23], 0, s[78:79]
	global_store_dwordx4 v[24:25], v[2:5], off offset:3072 sc1 nt
	s_cbranch_scc0 .LBB0_839
